# same s_nop removal at the 51 GEMM LDS-DMA sites (m0 write, address add, DMA)
# baseline (speedup 1.0000x reference)
; #define PG8_STAGE(bufoff, gbase, voff) do { _Pragma("unroll") for (int _i = 0; _i < 2; ++_i) \
;         __builtin_amdgcn_global_load_lds((const unsigned*)((const char*)(gbase) + (voff)[_i]), (PG8_LAS unsigned*)(lds + (bufoff) + ldsw + _i * 8192), 16, 0, 0); } while (0)
; #define PG8_LDA(dst, b, h) do { _Pragma("unroll") for (int m = 0; m < 4; ++m) _Pragma("unroll") for (int k = 0; k < 2; ++k) dst[m][k] = *(const PG8_LAS bf16x8*)(lds + PG8_SA(b, h) + aoff + m * 2048 + k * 1024); } while (0)
; #define PG8_LDB(dst, b, h) do { _Pragma("unroll") for (int n = 0; n < 2; ++n) _Pragma("unroll") for (int k = 0; k < 2; ++k) dst[n][k] = *(const PG8_LAS bf16x8*)(lds + PG8_SB(b, h) + boff + n * 2048 + k * 1024); } while (0)
; #define PG8_WAIT_V(n) asm volatile("s_waitcnt vmcnt(" #n ")" ::: "memory")
; #define PG8_WAIT_L(n) asm volatile("s_waitcnt lgkmcnt(" #n ")" ::: "memory")
; #define PG8_BAR __builtin_amdgcn_s_barrier()
; #define PG8_SCHED __builtin_amdgcn_sched_barrier(0)
; template <class Epi, class Sched, bool ALIGN_EPI = false, bool SP2 = false>
; __device__ __forceinline__ void gemm_phase(PG8_LAS unsigned char* lds, const Gemm g, const Sched& S, const Epi& E) {
;     ...
;         const bool has_next = S.next(ui + 1, nxt);
;         const char* nA = has_next ? (const char*)g.A + (size_t)nxt.pm * tstep : cA; const char* nB = has_next ? (const char*)g.Bt + (size_t)nxt.pn * tstep : cB;
;         for (int t = 0; t < nt; t += 2) {
;             const bool last = (t == nt - 2);
;             const char* a1 = cA + (size_t)(t + 1) * kstep;
;             const char* a2 = last ? nA : cA + (size_t)(t + 2) * kstep; const char* b2 = last ? nB : cB + (size_t)(t + 2) * kstep;
;             const char* a3 = a2 + kstep; const char* b3 = b2 + kstep;
;             if (last && has_next) S.a_ready(nxt);
;             if constexpr (SP2) {
;             PG8_LDB(B0, 0, 0); PG8_LDB(B1, 0, 1); PG8_SCHED; PG8_LDA(At, 0, 0); PG8_STAGE(PG8_SA(1, 0), a1, voffA); PG8_STAGE(PG8_SA(1, 1), a1 + hstep, voffA);
;             PG8_WAIT_V(8); PG8_WAIT_L(0); PG8_BAR; PG8_MMA(0, 0, At, B0); PG8_MMA(0, 1, At, B1); PG8_BAR; PG8_SCHED;
;             PG8_LDA(At, 0, 1); PG8_STAGE(PG8_SB(0, 0), b2, voffB); PG8_STAGE(PG8_SB(0, 1), b2 + hstep, voffB);
;             PG8_WAIT_V(6); PG8_WAIT_L(0); PG8_BAR; PG8_MMA(1, 0, At, B0); PG8_MMA(1, 1, At, B1); PG8_BAR; PG8_SCHED;
.LBB0_211:
	s_ashr_i32 s89, s88, 31
	s_lshl_b64 s[4:5], s[88:89], 20
	s_add_u32 s4, s22, s4
	s_addc_u32 s5, s75, s5
	s_and_b64 s[6:7], s[38:39], exec
	s_cselect_b32 s89, s5, s9
	s_cselect_b32 vcc_lo, s4, s8
	s_ashr_i32 s73, s72, 31
	s_lshl_b64 s[6:7], s[72:73], 20
	s_add_u32 s6, s68, s6
	s_addc_u32 s7, s69, s7
	s_and_b64 s[16:17], s[38:39], exec
	s_cselect_b32 s70, s7, s11
	s_cselect_b32 s71, s6, s10
	s_add_u32 s73, s10, 0x100
	s_addc_u32 vcc_hi, s11, 0
	s_mov_b32 s52, -2
	s_mov_b64 s[10:11], 0
	v_lshl_add_u64 v[138:139], s[8:9], 0, v[134:135]
	v_lshl_add_u64 v[140:141], s[8:9], 0, v[136:137]
	v_lshl_add_u32 v240, s35, 8, v146
	v_ashrrev_i32_e32 v241, 31, v240
	v_lshl_add_u64 v[240:241], v[240:241], 2, s[42:43]
	global_load_dword v242, v[240:241], off
	global_load_dword v243, v[240:241], off offset:64
	global_load_dword v244, v[240:241], off offset:128
	global_load_dword v245, v[240:241], off offset:192
	global_load_dword v246, v[240:241], off offset:512
	global_load_dword v247, v[240:241], off offset:576
	global_load_dword v248, v[240:241], off offset:640
	global_load_dword v249, v[240:241], off offset:704
	s_add_u32 s16, s8, s10
	s_addc_u32 s17, s9, s11
	s_add_u32 s44, s16, 0x100
	s_addc_u32 s45, s17, 0
	s_add_u32 s16, s73, s10
	s_addc_u32 s17, vcc_hi, s11
	s_add_i32 s53, 0, 0x10000
	s_cmpk_eq_i32 s10, 0xf00
	s_cselect_b32 s17, s70, s17
	s_cselect_b32 s16, s71, s16
	s_cselect_b32 s45, s89, s45
	s_cselect_b32 s44, vcc_lo, s44
	s_add_i32 s92, 0, 0x14000
	v_add_u32_e32 v158, s53, v147
	ds_read_b128 v[142:145], v158
	ds_read_b128 v[150:153], v158 offset:1024
	ds_read_b128 v[154:157], v158 offset:2048
	ds_read_b128 v[158:161], v158 offset:3072
	v_lshl_add_u64 v[202:203], v[138:139], 0, s[10:11]
	v_lshl_add_u64 v[206:207], v[202:203], 0, s[26:27]
	s_add_i32 m0, s97, 0x8000
	global_load_lds_dwordx4 v[206:207], off
	v_lshl_add_u64 v[206:207], v[140:141], 0, s[10:11]
	v_lshl_add_u64 v[208:209], v[206:207], 0, s[26:27]
	s_add_i32 m0, s97, 0xa000
	v_lshl_add_u64 v[202:203], v[202:203], 0, s[28:29]
	global_load_lds_dwordx4 v[208:209], off
	s_add_i32 m0, s97, 0xc000
	s_nop 0
	global_load_lds_dwordx4 v[202:203], off
	s_add_i32 m0, s97, 0xe000
	v_lshl_add_u64 v[202:203], v[206:207], 0, s[28:29]
	global_load_lds_dwordx4 v[202:203], off
	s_waitcnt vmcnt(8)
	s_waitcnt lgkmcnt(0)
	s_barrier
	v_mfma_f32_16x16x32_bf16 v[124:127], v[142:145], v[178:181], 0
	v_mfma_f32_16x16x32_bf16 v[120:123], v[154:157], v[178:181], 0
	v_mfma_f32_16x16x32_bf16 v[108:111], v[142:145], v[186:189], 0
	v_mfma_f32_16x16x32_bf16 v[104:107], v[154:157], v[186:189], 0
	v_mfma_f32_16x16x32_bf16 v[92:95], v[142:145], v[194:197], 0
	v_mfma_f32_16x16x32_bf16 v[88:91], v[154:157], v[194:197], 0
	v_mfma_f32_16x16x32_bf16 v[76:79], v[142:145], v[218:221], 0
	v_mfma_f32_16x16x32_bf16 v[72:75], v[154:157], v[218:221], 0
	v_mfma_f32_16x16x32_bf16 v[124:127], v[150:153], v[182:185], v[124:127]
	v_mfma_f32_16x16x32_bf16 v[120:123], v[158:161], v[182:185], v[120:123]
	v_mfma_f32_16x16x32_bf16 v[108:111], v[150:153], v[190:193], v[108:111]
	v_mfma_f32_16x16x32_bf16 v[104:107], v[158:161], v[190:193], v[104:107]
	v_mfma_f32_16x16x32_bf16 v[92:95], v[150:153], v[198:201], v[92:95]
	v_mfma_f32_16x16x32_bf16 v[88:91], v[158:161], v[198:201], v[88:91]
	v_mfma_f32_16x16x32_bf16 v[76:79], v[150:153], v[232:235], v[76:79]
	v_mfma_f32_16x16x32_bf16 v[72:75], v[158:161], v[232:235], v[72:75]
	v_mfma_f32_16x16x32_bf16 v[116:119], v[162:165], v[178:181], 0
	v_mfma_f32_16x16x32_bf16 v[112:115], v[170:173], v[178:181], 0
	v_mfma_f32_16x16x32_bf16 v[100:103], v[162:165], v[186:189], 0
	v_mfma_f32_16x16x32_bf16 v[96:99], v[170:173], v[186:189], 0
	v_mfma_f32_16x16x32_bf16 v[84:87], v[162:165], v[194:197], 0
	v_mfma_f32_16x16x32_bf16 v[80:83], v[170:173], v[194:197], 0
	v_mfma_f32_16x16x32_bf16 v[68:71], v[162:165], v[218:221], 0
	v_mfma_f32_16x16x32_bf16 v[64:67], v[170:173], v[218:221], 0
	v_mfma_f32_16x16x32_bf16 v[116:119], v[166:169], v[182:185], v[116:119]
	v_mfma_f32_16x16x32_bf16 v[112:115], v[174:177], v[182:185], v[112:115]
	v_mfma_f32_16x16x32_bf16 v[100:103], v[166:169], v[190:193], v[100:103]
	v_mfma_f32_16x16x32_bf16 v[96:99], v[174:177], v[190:193], v[96:99]
	v_mfma_f32_16x16x32_bf16 v[84:87], v[166:169], v[198:201], v[84:87]
	v_mfma_f32_16x16x32_bf16 v[80:83], v[174:177], v[198:201], v[80:83]
	v_mfma_f32_16x16x32_bf16 v[68:71], v[166:169], v[232:235], v[68:71]
	v_mfma_f32_16x16x32_bf16 v[64:67], v[174:177], v[232:235], v[64:67]
	s_barrier
	s_add_i32 s53, s53, s23
	v_lshl_add_u64 v[202:203], s[16:17], 0, v[204:205]
	s_mov_b32 m0, s53
	ds_read_b128 v[178:181], v149 offset:16384
	ds_read_b128 v[182:185], v149 offset:17408
	ds_read_b128 v[186:189], v149 offset:18432
	ds_read_b128 v[190:193], v149 offset:19456
	ds_read_b128 v[194:197], v149 offset:20480
	ds_read_b128 v[198:201], v149 offset:21504
	ds_read_b128 v[218:221], v149 offset:22528
	ds_read_b128 v[232:235], v149 offset:23552
	global_load_lds_dwordx4 v[202:203], off
	s_add_i32 m0, s53, 0x2000
	s_add_u32 s78, s16, 0x80000
	v_lshl_add_u64 v[206:207], s[16:17], 0, v[128:129]
	s_addc_u32 s79, s17, 0
	s_add_i32 s53, s92, s23
	global_load_lds_dwordx4 v[206:207], off
	s_mov_b32 m0, s53
	v_lshl_add_u64 v[208:209], s[78:79], 0, v[204:205]
	global_load_lds_dwordx4 v[208:209], off
	s_add_i32 m0, s53, 0x2000
	v_lshl_add_u64 v[208:209], s[78:79], 0, v[128:129]
	global_load_lds_dwordx4 v[208:209], off
	s_waitcnt vmcnt(6)
	s_waitcnt lgkmcnt(0)
	s_barrier
; #define PG8_STAGE(bufoff, gbase, voff) do { _Pragma("unroll") for (int _i = 0; _i < 2; ++_i) \
;         __builtin_amdgcn_global_load_lds((const unsigned*)((const char*)(gbase) + (voff)[_i]), (PG8_LAS unsigned*)(lds + (bufoff) + ldsw + _i * 8192), 16, 0, 0); } while (0)
; #define PG8_LDA(dst, b, h) do { _Pragma("unroll") for (int m = 0; m < 4; ++m) _Pragma("unroll") for (int k = 0; k < 2; ++k) dst[m][k] = *(const PG8_LAS bf16x8*)(lds + PG8_SA(b, h) + aoff + m * 2048 + k * 1024); } while (0)
; #define PG8_LDB(dst, b, h) do { _Pragma("unroll") for (int n = 0; n < 2; ++n) _Pragma("unroll") for (int k = 0; k < 2; ++k) dst[n][k] = *(const PG8_LAS bf16x8*)(lds + PG8_SB(b, h) + boff + n * 2048 + k * 1024); } while (0)
; #define PG8_MMA(ai, bj, At, Bt) do { __builtin_amdgcn_s_setprio(1); _Pragma("unroll") for (int m = 0; m < 4; ++m) _Pragma("unroll") for (int n = 0; n < 2; ++n) _Pragma("unroll") for (int k = 0; k < 2; ++k) \
;         acc[ai][bj][m][n] = __builtin_amdgcn_mfma_f32_16x16x32_bf16(Bt[n][k], At[m][k], acc[ai][bj][m][n], 0, 0, 0); __builtin_amdgcn_s_setprio(0); } while (0)
; #define PG8_WAIT_V(n) asm volatile("s_waitcnt vmcnt(" #n ")" ::: "memory")
; #define PG8_WAIT_L(n) asm volatile("s_waitcnt lgkmcnt(" #n ")" ::: "memory")
; #define PG8_BAR __builtin_amdgcn_s_barrier()
; #define PG8_SCHED __builtin_amdgcn_sched_barrier(0)
; template <class Epi, class Sched, bool ALIGN_EPI = false, bool SP2 = false>
; __device__ __forceinline__ void gemm_phase(PG8_LAS unsigned char* lds, const Gemm g, const Sched& S, const Epi& E) {
;     ...
;             PG8_LDB(B0, 0, 0); PG8_LDB(B1, 0, 1); PG8_SCHED; PG8_LDA(At, 0, 0); PG8_STAGE(PG8_SA(1, 0), a1, voffA); PG8_STAGE(PG8_SA(1, 1), a1 + hstep, voffA);
;             PG8_WAIT_V(8); PG8_WAIT_L(0); PG8_BAR; PG8_MMA(0, 0, At, B0); PG8_MMA(0, 1, At, B1); PG8_BAR; PG8_SCHED;
;             PG8_LDA(At, 0, 1); PG8_STAGE(PG8_SB(0, 0), b2, voffB); PG8_STAGE(PG8_SB(0, 1), b2 + hstep, voffB);
;             PG8_WAIT_V(6); PG8_WAIT_L(0); PG8_BAR; PG8_MMA(1, 0, At, B0); PG8_MMA(1, 1, At, B1); PG8_BAR; PG8_SCHED;
	v_mfma_f32_16x16x32_bf16 v[60:63], v[142:145], v[178:181], 0
	v_mfma_f32_16x16x32_bf16 v[56:59], v[154:157], v[178:181], 0
	v_mfma_f32_16x16x32_bf16 v[44:47], v[142:145], v[186:189], 0
	v_mfma_f32_16x16x32_bf16 v[40:43], v[154:157], v[186:189], 0
	v_mfma_f32_16x16x32_bf16 v[28:31], v[142:145], v[194:197], 0
	v_mfma_f32_16x16x32_bf16 v[24:27], v[154:157], v[194:197], 0
	v_mfma_f32_16x16x32_bf16 v[12:15], v[142:145], v[218:221], 0
	v_mfma_f32_16x16x32_bf16 v[8:11], v[154:157], v[218:221], 0
	v_mfma_f32_16x16x32_bf16 v[60:63], v[150:153], v[182:185], v[60:63]
	v_mfma_f32_16x16x32_bf16 v[56:59], v[158:161], v[182:185], v[56:59]
	v_mfma_f32_16x16x32_bf16 v[44:47], v[150:153], v[190:193], v[44:47]
	v_mfma_f32_16x16x32_bf16 v[40:43], v[158:161], v[190:193], v[40:43]
	v_mfma_f32_16x16x32_bf16 v[28:31], v[150:153], v[198:201], v[28:31]
	v_mfma_f32_16x16x32_bf16 v[24:27], v[158:161], v[198:201], v[24:27]
	v_mfma_f32_16x16x32_bf16 v[12:15], v[150:153], v[232:235], v[12:15]
	v_mfma_f32_16x16x32_bf16 v[8:11], v[158:161], v[232:235], v[8:11]
	v_mfma_f32_16x16x32_bf16 v[52:55], v[162:165], v[178:181], 0
	v_mfma_f32_16x16x32_bf16 v[48:51], v[170:173], v[178:181], 0
	v_mfma_f32_16x16x32_bf16 v[36:39], v[162:165], v[186:189], 0
	v_mfma_f32_16x16x32_bf16 v[32:35], v[170:173], v[186:189], 0
	v_mfma_f32_16x16x32_bf16 v[20:23], v[162:165], v[194:197], 0
	v_mfma_f32_16x16x32_bf16 v[16:19], v[170:173], v[194:197], 0
	v_mfma_f32_16x16x32_bf16 v[4:7], v[162:165], v[218:221], 0
	v_mfma_f32_16x16x32_bf16 v[0:3], v[170:173], v[218:221], 0
	v_mfma_f32_16x16x32_bf16 v[52:55], v[166:169], v[182:185], v[52:55]
	v_mfma_f32_16x16x32_bf16 v[48:51], v[174:177], v[182:185], v[48:51]
	v_mfma_f32_16x16x32_bf16 v[36:39], v[166:169], v[190:193], v[36:39]
	v_mfma_f32_16x16x32_bf16 v[32:35], v[174:177], v[190:193], v[32:35]
	v_mfma_f32_16x16x32_bf16 v[20:23], v[166:169], v[198:201], v[20:23]
	v_mfma_f32_16x16x32_bf16 v[16:19], v[174:177], v[198:201], v[16:19]
	v_mfma_f32_16x16x32_bf16 v[4:7], v[166:169], v[232:235], v[4:7]
	v_mfma_f32_16x16x32_bf16 v[0:3], v[174:177], v[232:235], v[0:3]
	s_barrier
	s_branch .Lpl_qk
.LBB0_212:
	s_add_u32 s16, s8, s10
	s_addc_u32 s17, s9, s11
	s_add_u32 s44, s16, 0x100
	s_addc_u32 s45, s17, 0
	s_add_u32 s16, s73, s10
	s_addc_u32 s17, vcc_hi, s11
	s_add_i32 s53, 0, 0x10000
	s_cmpk_eq_i32 s10, 0xf00
	s_cselect_b32 s17, s70, s17
	s_cselect_b32 s16, s71, s16
	s_cselect_b32 s45, s89, s45
	s_cselect_b32 s44, vcc_lo, s44
	s_add_i32 s92, 0, 0x14000
	v_add_u32_e32 v158, s53, v147
	v_add_u32_e32 v174, s92, v147
	ds_read_b128 v[142:145], v158
	ds_read_b128 v[150:153], v158 offset:1024
	ds_read_b128 v[154:157], v158 offset:2048
	ds_read_b128 v[158:161], v158 offset:3072
	ds_read_b128 v[162:165], v174
	ds_read_b128 v[166:169], v174 offset:1024
	ds_read_b128 v[170:173], v174 offset:2048
	ds_read_b128 v[174:177], v174 offset:3072
	v_lshl_add_u64 v[202:203], v[138:139], 0, s[10:11]
	v_lshl_add_u64 v[206:207], v[202:203], 0, s[26:27]
	s_add_i32 m0, s97, 0x8000
	ds_read_b128 v[178:181], v149
	ds_read_b128 v[182:185], v149 offset:1024
	ds_read_b128 v[186:189], v149 offset:2048
	ds_read_b128 v[190:193], v149 offset:3072
	ds_read_b128 v[194:197], v149 offset:4096
	ds_read_b128 v[198:201], v149 offset:5120
	ds_read_b128 v[218:221], v149 offset:6144
	ds_read_b128 v[232:235], v149 offset:7168
	global_load_lds_dwordx4 v[206:207], off
	v_lshl_add_u64 v[206:207], v[140:141], 0, s[10:11]
	v_lshl_add_u64 v[208:209], v[206:207], 0, s[26:27]
	s_add_i32 m0, s97, 0xa000
	v_lshl_add_u64 v[202:203], v[202:203], 0, s[28:29]
	global_load_lds_dwordx4 v[208:209], off
	s_add_i32 m0, s97, 0xc000
	s_nop 0
	global_load_lds_dwordx4 v[202:203], off
	s_add_i32 m0, s97, 0xe000
	v_lshl_add_u64 v[202:203], v[206:207], 0, s[28:29]
	global_load_lds_dwordx4 v[202:203], off
	s_waitcnt vmcnt(8)
	s_waitcnt lgkmcnt(0)
	s_barrier
	v_mfma_f32_16x16x32_bf16 v[124:127], v[142:145], v[178:181], v[124:127]
	v_mfma_f32_16x16x32_bf16 v[120:123], v[154:157], v[178:181], v[120:123]
	v_mfma_f32_16x16x32_bf16 v[108:111], v[142:145], v[186:189], v[108:111]
	v_mfma_f32_16x16x32_bf16 v[104:107], v[154:157], v[186:189], v[104:107]
	v_mfma_f32_16x16x32_bf16 v[92:95], v[142:145], v[194:197], v[92:95]
	v_mfma_f32_16x16x32_bf16 v[88:91], v[154:157], v[194:197], v[88:91]
	v_mfma_f32_16x16x32_bf16 v[76:79], v[142:145], v[218:221], v[76:79]
	v_mfma_f32_16x16x32_bf16 v[72:75], v[154:157], v[218:221], v[72:75]
	v_mfma_f32_16x16x32_bf16 v[124:127], v[150:153], v[182:185], v[124:127]
	v_mfma_f32_16x16x32_bf16 v[120:123], v[158:161], v[182:185], v[120:123]
	v_mfma_f32_16x16x32_bf16 v[108:111], v[150:153], v[190:193], v[108:111]
	v_mfma_f32_16x16x32_bf16 v[104:107], v[158:161], v[190:193], v[104:107]
	v_mfma_f32_16x16x32_bf16 v[92:95], v[150:153], v[198:201], v[92:95]
	v_mfma_f32_16x16x32_bf16 v[88:91], v[158:161], v[198:201], v[88:91]
	v_mfma_f32_16x16x32_bf16 v[76:79], v[150:153], v[232:235], v[76:79]
	v_mfma_f32_16x16x32_bf16 v[72:75], v[158:161], v[232:235], v[72:75]
	v_mfma_f32_16x16x32_bf16 v[116:119], v[162:165], v[178:181], v[116:119]
	v_mfma_f32_16x16x32_bf16 v[112:115], v[170:173], v[178:181], v[112:115]
	v_mfma_f32_16x16x32_bf16 v[100:103], v[162:165], v[186:189], v[100:103]
	v_mfma_f32_16x16x32_bf16 v[96:99], v[170:173], v[186:189], v[96:99]
	v_mfma_f32_16x16x32_bf16 v[84:87], v[162:165], v[194:197], v[84:87]
	v_mfma_f32_16x16x32_bf16 v[80:83], v[170:173], v[194:197], v[80:83]
	v_mfma_f32_16x16x32_bf16 v[68:71], v[162:165], v[218:221], v[68:71]
	v_mfma_f32_16x16x32_bf16 v[64:67], v[170:173], v[218:221], v[64:67]
	v_mfma_f32_16x16x32_bf16 v[116:119], v[166:169], v[182:185], v[116:119]
	v_mfma_f32_16x16x32_bf16 v[112:115], v[174:177], v[182:185], v[112:115]
	v_mfma_f32_16x16x32_bf16 v[100:103], v[166:169], v[190:193], v[100:103]
	v_mfma_f32_16x16x32_bf16 v[96:99], v[174:177], v[190:193], v[96:99]
	v_mfma_f32_16x16x32_bf16 v[84:87], v[166:169], v[198:201], v[84:87]
	v_mfma_f32_16x16x32_bf16 v[80:83], v[174:177], v[198:201], v[80:83]
	v_mfma_f32_16x16x32_bf16 v[68:71], v[166:169], v[232:235], v[68:71]
	v_mfma_f32_16x16x32_bf16 v[64:67], v[174:177], v[232:235], v[64:67]
	s_barrier
; #define PG8_STAGE(bufoff, gbase, voff) do { _Pragma("unroll") for (int _i = 0; _i < 2; ++_i) \
;         __builtin_amdgcn_global_load_lds((const unsigned*)((const char*)(gbase) + (voff)[_i]), (PG8_LAS unsigned*)(lds + (bufoff) + ldsw + _i * 8192), 16, 0, 0); } while (0)
; #define PG8_LDA(dst, b, h) do { _Pragma("unroll") for (int m = 0; m < 4; ++m) _Pragma("unroll") for (int k = 0; k < 2; ++k) dst[m][k] = *(const PG8_LAS bf16x8*)(lds + PG8_SA(b, h) + aoff + m * 2048 + k * 1024); } while (0)
; #define PG8_MMA(ai, bj, At, Bt) do { __builtin_amdgcn_s_setprio(1); _Pragma("unroll") for (int m = 0; m < 4; ++m) _Pragma("unroll") for (int n = 0; n < 2; ++n) _Pragma("unroll") for (int k = 0; k < 2; ++k) \
;         acc[ai][bj][m][n] = __builtin_amdgcn_mfma_f32_16x16x32_bf16(Bt[n][k], At[m][k], acc[ai][bj][m][n], 0, 0, 0); __builtin_amdgcn_s_setprio(0); } while (0)
; #define PG8_WAIT_V(n) asm volatile("s_waitcnt vmcnt(" #n ")" ::: "memory")
; #define PG8_WAIT_L(n) asm volatile("s_waitcnt lgkmcnt(" #n ")" ::: "memory")
; #define PG8_BAR __builtin_amdgcn_s_barrier()
; #define PG8_SCHED __builtin_amdgcn_sched_barrier(0)
; template <class Epi, class Sched, bool ALIGN_EPI = false, bool SP2 = false>
; __device__ __forceinline__ void gemm_phase(PG8_LAS unsigned char* lds, const Gemm g, const Sched& S, const Epi& E) {
;     ...
;             PG8_LDA(At, 0, 1); PG8_STAGE(PG8_SB(0, 0), b2, voffB); PG8_STAGE(PG8_SB(0, 1), b2 + hstep, voffB);
;             PG8_WAIT_V(6); PG8_WAIT_L(0); PG8_BAR; PG8_MMA(1, 0, At, B0); PG8_MMA(1, 1, At, B1); PG8_BAR; PG8_SCHED;
	s_add_i32 s53, s53, s23
	v_lshl_add_u64 v[202:203], s[16:17], 0, v[204:205]
	s_mov_b32 m0, s53
	ds_read_b128 v[178:181], v149 offset:16384
	ds_read_b128 v[182:185], v149 offset:17408
	ds_read_b128 v[186:189], v149 offset:18432
	ds_read_b128 v[190:193], v149 offset:19456
	ds_read_b128 v[194:197], v149 offset:20480
	ds_read_b128 v[198:201], v149 offset:21504
	ds_read_b128 v[218:221], v149 offset:22528
	ds_read_b128 v[232:235], v149 offset:23552
	global_load_lds_dwordx4 v[202:203], off
	s_add_i32 m0, s53, 0x2000
	s_add_u32 s78, s16, 0x80000
	v_lshl_add_u64 v[206:207], s[16:17], 0, v[128:129]
	s_addc_u32 s79, s17, 0
	s_add_i32 s53, s92, s23
	global_load_lds_dwordx4 v[206:207], off
	s_mov_b32 m0, s53
	v_lshl_add_u64 v[208:209], s[78:79], 0, v[204:205]
	global_load_lds_dwordx4 v[208:209], off
	s_add_i32 m0, s53, 0x2000
	v_lshl_add_u64 v[208:209], s[78:79], 0, v[128:129]
	global_load_lds_dwordx4 v[208:209], off
	s_waitcnt vmcnt(6)
	s_waitcnt lgkmcnt(0)
	s_barrier
	v_mfma_f32_16x16x32_bf16 v[60:63], v[142:145], v[178:181], v[60:63]
	v_mfma_f32_16x16x32_bf16 v[56:59], v[154:157], v[178:181], v[56:59]
	v_mfma_f32_16x16x32_bf16 v[44:47], v[142:145], v[186:189], v[44:47]
	v_mfma_f32_16x16x32_bf16 v[40:43], v[154:157], v[186:189], v[40:43]
	v_mfma_f32_16x16x32_bf16 v[28:31], v[142:145], v[194:197], v[28:31]
	v_mfma_f32_16x16x32_bf16 v[24:27], v[154:157], v[194:197], v[24:27]
	v_mfma_f32_16x16x32_bf16 v[12:15], v[142:145], v[218:221], v[12:15]
	v_mfma_f32_16x16x32_bf16 v[8:11], v[154:157], v[218:221], v[8:11]
	v_mfma_f32_16x16x32_bf16 v[60:63], v[150:153], v[182:185], v[60:63]
	v_mfma_f32_16x16x32_bf16 v[56:59], v[158:161], v[182:185], v[56:59]
	v_mfma_f32_16x16x32_bf16 v[44:47], v[150:153], v[190:193], v[44:47]
	v_mfma_f32_16x16x32_bf16 v[40:43], v[158:161], v[190:193], v[40:43]
	v_mfma_f32_16x16x32_bf16 v[28:31], v[150:153], v[198:201], v[28:31]
	v_mfma_f32_16x16x32_bf16 v[24:27], v[158:161], v[198:201], v[24:27]
	v_mfma_f32_16x16x32_bf16 v[12:15], v[150:153], v[232:235], v[12:15]
	v_mfma_f32_16x16x32_bf16 v[8:11], v[158:161], v[232:235], v[8:11]
	v_mfma_f32_16x16x32_bf16 v[52:55], v[162:165], v[178:181], v[52:55]
	v_mfma_f32_16x16x32_bf16 v[48:51], v[170:173], v[178:181], v[48:51]
	v_mfma_f32_16x16x32_bf16 v[36:39], v[162:165], v[186:189], v[36:39]
	v_mfma_f32_16x16x32_bf16 v[32:35], v[170:173], v[186:189], v[32:35]
	v_mfma_f32_16x16x32_bf16 v[20:23], v[162:165], v[194:197], v[20:23]
	v_mfma_f32_16x16x32_bf16 v[16:19], v[170:173], v[194:197], v[16:19]
	v_mfma_f32_16x16x32_bf16 v[4:7], v[162:165], v[218:221], v[4:7]
	v_mfma_f32_16x16x32_bf16 v[0:3], v[170:173], v[218:221], v[0:3]
	v_mfma_f32_16x16x32_bf16 v[52:55], v[166:169], v[182:185], v[52:55]
	v_mfma_f32_16x16x32_bf16 v[48:51], v[174:177], v[182:185], v[48:51]
	v_mfma_f32_16x16x32_bf16 v[36:39], v[166:169], v[190:193], v[36:39]
	v_mfma_f32_16x16x32_bf16 v[32:35], v[174:177], v[190:193], v[32:35]
	v_mfma_f32_16x16x32_bf16 v[20:23], v[166:169], v[198:201], v[20:23]
	v_mfma_f32_16x16x32_bf16 v[16:19], v[174:177], v[198:201], v[16:19]
	v_mfma_f32_16x16x32_bf16 v[4:7], v[166:169], v[232:235], v[4:7]
	v_mfma_f32_16x16x32_bf16 v[0:3], v[174:177], v[232:235], v[0:3]
	s_barrier
; #define PG8_STAGE(bufoff, gbase, voff) do { _Pragma("unroll") for (int _i = 0; _i < 2; ++_i) \
;         __builtin_amdgcn_global_load_lds((const unsigned*)((const char*)(gbase) + (voff)[_i]), (PG8_LAS unsigned*)(lds + (bufoff) + ldsw + _i * 8192), 16, 0, 0); } while (0)
; #define PG8_LDA(dst, b, h) do { _Pragma("unroll") for (int m = 0; m < 4; ++m) _Pragma("unroll") for (int k = 0; k < 2; ++k) dst[m][k] = *(const PG8_LAS bf16x8*)(lds + PG8_SA(b, h) + aoff + m * 2048 + k * 1024); } while (0)
; #define PG8_LDB(dst, b, h) do { _Pragma("unroll") for (int n = 0; n < 2; ++n) _Pragma("unroll") for (int k = 0; k < 2; ++k) dst[n][k] = *(const PG8_LAS bf16x8*)(lds + PG8_SB(b, h) + boff + n * 2048 + k * 1024); } while (0)
; #define PG8_MMA(ai, bj, At, Bt) do { __builtin_amdgcn_s_setprio(1); _Pragma("unroll") for (int m = 0; m < 4; ++m) _Pragma("unroll") for (int n = 0; n < 2; ++n) _Pragma("unroll") for (int k = 0; k < 2; ++k) \
;         acc[ai][bj][m][n] = __builtin_amdgcn_mfma_f32_16x16x32_bf16(Bt[n][k], At[m][k], acc[ai][bj][m][n], 0, 0, 0); __builtin_amdgcn_s_setprio(0); } while (0)
; #define PG8_WAIT_V(n) asm volatile("s_waitcnt vmcnt(" #n ")" ::: "memory")
; #define PG8_WAIT_L(n) asm volatile("s_waitcnt lgkmcnt(" #n ")" ::: "memory")
; #define PG8_BAR __builtin_amdgcn_s_barrier()
; #define PG8_SCHED __builtin_amdgcn_sched_barrier(0)
; template <class Epi, class Sched, bool ALIGN_EPI = false, bool SP2 = false>
; __device__ __forceinline__ void gemm_phase(PG8_LAS unsigned char* lds, const Gemm g, const Sched& S, const Epi& E) {
;     ...
;             PG8_LDB(B0, 1, 0); PG8_LDB(B1, 1, 1); PG8_SCHED; PG8_LDA(At, 1, 0); PG8_STAGE(PG8_SA(0, 0), a2, voffA); PG8_STAGE(PG8_SA(0, 1), a2 + hstep, voffA);
;             PG8_WAIT_V(8); PG8_WAIT_L(0); PG8_BAR; PG8_MMA(0, 0, At, B0); PG8_MMA(0, 1, At, B1); PG8_BAR; PG8_SCHED;
;             PG8_LDA(At, 1, 1); PG8_STAGE(PG8_SB(1, 0), b3, voffB); PG8_STAGE(PG8_SB(1, 1), b3 + hstep, voffB); (void)a3;
;             PG8_WAIT_V(6); PG8_WAIT_L(0); PG8_BAR; PG8_MMA(1, 0, At, B0); PG8_MMA(1, 1, At, B1); PG8_BAR; PG8_SCHED;
.Lpl_qk:
	s_add_i32 s53, 0, 0x18000
	s_add_i32 s78, 0, 0x1c000
	v_add_u32_e32 v158, s53, v147
	v_add_u32_e32 v174, s78, v147
	ds_read_b128 v[142:145], v158
	ds_read_b128 v[150:153], v158 offset:1024
	ds_read_b128 v[154:157], v158 offset:2048
	ds_read_b128 v[158:161], v158 offset:3072
	ds_read_b128 v[162:165], v174
	ds_read_b128 v[166:169], v174 offset:1024
	ds_read_b128 v[170:173], v174 offset:2048
	ds_read_b128 v[174:177], v174 offset:3072
	s_mov_b32 m0, s97
	v_lshl_add_u64 v[208:209], s[44:45], 0, v[132:133]
	ds_read_b128 v[178:181], v149 offset:32768
	ds_read_b128 v[182:185], v149 offset:33792
	ds_read_b128 v[186:189], v149 offset:34816
	ds_read_b128 v[190:193], v149 offset:35840
	ds_read_b128 v[194:197], v149 offset:36864
	ds_read_b128 v[198:201], v149 offset:37888
	ds_read_b128 v[218:221], v149 offset:38912
	ds_read_b128 v[232:235], v149 offset:39936
	global_load_lds_dwordx4 v[208:209], off
	v_lshl_add_u64 v[208:209], s[44:45], 0, v[130:131]
	s_add_u32 s44, s44, 0x80000
	s_mov_b32 m0, s20
	s_addc_u32 s45, s45, 0
	global_load_lds_dwordx4 v[208:209], off
	s_mov_b32 m0, s21
	v_lshl_add_u64 v[208:209], s[44:45], 0, v[132:133]
	global_load_lds_dwordx4 v[208:209], off
	s_mov_b32 m0, s57
	v_lshl_add_u64 v[208:209], s[44:45], 0, v[130:131]
	global_load_lds_dwordx4 v[208:209], off
	s_waitcnt vmcnt(8)
	s_waitcnt lgkmcnt(0)
	s_barrier
	v_mfma_f32_16x16x32_bf16 v[124:127], v[142:145], v[178:181], v[124:127]
	v_mfma_f32_16x16x32_bf16 v[120:123], v[154:157], v[178:181], v[120:123]
	v_mfma_f32_16x16x32_bf16 v[108:111], v[142:145], v[186:189], v[108:111]
	v_mfma_f32_16x16x32_bf16 v[104:107], v[154:157], v[186:189], v[104:107]
	v_mfma_f32_16x16x32_bf16 v[92:95], v[142:145], v[194:197], v[92:95]
	v_mfma_f32_16x16x32_bf16 v[88:91], v[154:157], v[194:197], v[88:91]
	v_mfma_f32_16x16x32_bf16 v[76:79], v[142:145], v[218:221], v[76:79]
	v_mfma_f32_16x16x32_bf16 v[72:75], v[154:157], v[218:221], v[72:75]
	v_mfma_f32_16x16x32_bf16 v[124:127], v[150:153], v[182:185], v[124:127]
	v_mfma_f32_16x16x32_bf16 v[120:123], v[158:161], v[182:185], v[120:123]
	v_mfma_f32_16x16x32_bf16 v[108:111], v[150:153], v[190:193], v[108:111]
	v_mfma_f32_16x16x32_bf16 v[104:107], v[158:161], v[190:193], v[104:107]
	v_mfma_f32_16x16x32_bf16 v[92:95], v[150:153], v[198:201], v[92:95]
	v_mfma_f32_16x16x32_bf16 v[88:91], v[158:161], v[198:201], v[88:91]
	v_mfma_f32_16x16x32_bf16 v[76:79], v[150:153], v[232:235], v[76:79]
	v_mfma_f32_16x16x32_bf16 v[72:75], v[158:161], v[232:235], v[72:75]
	v_mfma_f32_16x16x32_bf16 v[116:119], v[162:165], v[178:181], v[116:119]
	v_mfma_f32_16x16x32_bf16 v[112:115], v[170:173], v[178:181], v[112:115]
	v_mfma_f32_16x16x32_bf16 v[100:103], v[162:165], v[186:189], v[100:103]
	v_mfma_f32_16x16x32_bf16 v[96:99], v[170:173], v[186:189], v[96:99]
	v_mfma_f32_16x16x32_bf16 v[84:87], v[162:165], v[194:197], v[84:87]
	v_mfma_f32_16x16x32_bf16 v[80:83], v[170:173], v[194:197], v[80:83]
	v_mfma_f32_16x16x32_bf16 v[68:71], v[162:165], v[218:221], v[68:71]
	v_mfma_f32_16x16x32_bf16 v[64:67], v[170:173], v[218:221], v[64:67]
	v_mfma_f32_16x16x32_bf16 v[116:119], v[166:169], v[182:185], v[116:119]
	v_mfma_f32_16x16x32_bf16 v[112:115], v[174:177], v[182:185], v[112:115]
	v_mfma_f32_16x16x32_bf16 v[100:103], v[166:169], v[190:193], v[100:103]
	v_mfma_f32_16x16x32_bf16 v[96:99], v[174:177], v[190:193], v[96:99]
	v_mfma_f32_16x16x32_bf16 v[84:87], v[166:169], v[198:201], v[84:87]
	v_mfma_f32_16x16x32_bf16 v[80:83], v[174:177], v[198:201], v[80:83]
	v_mfma_f32_16x16x32_bf16 v[68:71], v[166:169], v[232:235], v[68:71]
	v_mfma_f32_16x16x32_bf16 v[64:67], v[174:177], v[232:235], v[64:67]
	s_barrier
	s_add_i32 s44, s53, s23
	v_lshl_add_u64 v[202:203], v[202:203], 0, s[26:27]
	s_mov_b32 m0, s44
	ds_read_b128 v[178:181], v149 offset:49152
	ds_read_b128 v[182:185], v149 offset:50176
	ds_read_b128 v[186:189], v149 offset:51200
	ds_read_b128 v[190:193], v149 offset:52224
	ds_read_b128 v[194:197], v149 offset:53248
	ds_read_b128 v[198:201], v149 offset:54272
	ds_read_b128 v[218:221], v149 offset:55296
	ds_read_b128 v[232:235], v149 offset:56320
	global_load_lds_dwordx4 v[202:203], off
	s_add_i32 m0, s44, 0x2000
	s_add_u32 s16, s16, 0x80080
	v_lshl_add_u64 v[202:203], v[206:207], 0, s[26:27]
	s_addc_u32 s17, s17, 0
	s_add_i32 s44, s78, s23
	global_load_lds_dwordx4 v[202:203], off
	s_mov_b32 m0, s44
	v_lshl_add_u64 v[202:203], s[16:17], 0, v[204:205]
	global_load_lds_dwordx4 v[202:203], off
	s_add_i32 m0, s44, 0x2000
	v_lshl_add_u64 v[202:203], s[16:17], 0, v[128:129]
	global_load_lds_dwordx4 v[202:203], off
	s_waitcnt vmcnt(6)
	s_waitcnt lgkmcnt(0)
	s_barrier
	v_mfma_f32_16x16x32_bf16 v[60:63], v[142:145], v[178:181], v[60:63]
	v_mfma_f32_16x16x32_bf16 v[56:59], v[154:157], v[178:181], v[56:59]
	v_mfma_f32_16x16x32_bf16 v[44:47], v[142:145], v[186:189], v[44:47]
	v_mfma_f32_16x16x32_bf16 v[40:43], v[154:157], v[186:189], v[40:43]
	v_mfma_f32_16x16x32_bf16 v[28:31], v[142:145], v[194:197], v[28:31]
	v_mfma_f32_16x16x32_bf16 v[24:27], v[154:157], v[194:197], v[24:27]
	v_mfma_f32_16x16x32_bf16 v[12:15], v[142:145], v[218:221], v[12:15]
	v_mfma_f32_16x16x32_bf16 v[8:11], v[154:157], v[218:221], v[8:11]
	v_mfma_f32_16x16x32_bf16 v[60:63], v[150:153], v[182:185], v[60:63]
	v_mfma_f32_16x16x32_bf16 v[56:59], v[158:161], v[182:185], v[56:59]
	v_mfma_f32_16x16x32_bf16 v[44:47], v[150:153], v[190:193], v[44:47]
	v_mfma_f32_16x16x32_bf16 v[40:43], v[158:161], v[190:193], v[40:43]
	v_mfma_f32_16x16x32_bf16 v[28:31], v[150:153], v[198:201], v[28:31]
	v_mfma_f32_16x16x32_bf16 v[24:27], v[158:161], v[198:201], v[24:27]
	v_mfma_f32_16x16x32_bf16 v[12:15], v[150:153], v[232:235], v[12:15]
	v_mfma_f32_16x16x32_bf16 v[8:11], v[158:161], v[232:235], v[8:11]
	v_mfma_f32_16x16x32_bf16 v[52:55], v[162:165], v[178:181], v[52:55]
	v_mfma_f32_16x16x32_bf16 v[48:51], v[170:173], v[178:181], v[48:51]
	v_mfma_f32_16x16x32_bf16 v[36:39], v[162:165], v[186:189], v[36:39]
	v_mfma_f32_16x16x32_bf16 v[32:35], v[170:173], v[186:189], v[32:35]
	v_mfma_f32_16x16x32_bf16 v[20:23], v[162:165], v[194:197], v[20:23]
	v_mfma_f32_16x16x32_bf16 v[16:19], v[170:173], v[194:197], v[16:19]
	v_mfma_f32_16x16x32_bf16 v[4:7], v[162:165], v[218:221], v[4:7]
	v_mfma_f32_16x16x32_bf16 v[0:3], v[170:173], v[218:221], v[0:3]
	v_mfma_f32_16x16x32_bf16 v[52:55], v[166:169], v[182:185], v[52:55]
	v_mfma_f32_16x16x32_bf16 v[48:51], v[174:177], v[182:185], v[48:51]
	v_mfma_f32_16x16x32_bf16 v[36:39], v[166:169], v[190:193], v[36:39]
	v_mfma_f32_16x16x32_bf16 v[32:35], v[174:177], v[190:193], v[32:35]
	v_mfma_f32_16x16x32_bf16 v[20:23], v[166:169], v[198:201], v[20:23]
	v_mfma_f32_16x16x32_bf16 v[16:19], v[174:177], v[198:201], v[16:19]
	v_mfma_f32_16x16x32_bf16 v[4:7], v[166:169], v[232:235], v[4:7]
	v_mfma_f32_16x16x32_bf16 v[0:3], v[174:177], v[232:235], v[0:3]
	s_barrier
	s_add_i32 s52, s52, 2
	s_add_u32 s10, s10, 0x100
	s_addc_u32 s11, s11, 0
	s_cmp_gt_u32 s52, 29
	s_cbranch_scc0 .LBB0_212
	s_and_b64 vcc, exec, s[76:77]
	s_cbranch_vccz .LBB0_215
	s_barrier

; #define PG8_STAGE(bufoff, gbase, voff) do { _Pragma("unroll") for (int _i = 0; _i < 2; ++_i) \
;         __builtin_amdgcn_global_load_lds((const unsigned*)((const char*)(gbase) + (voff)[_i]), (PG8_LAS unsigned*)(lds + (bufoff) + ldsw + _i * 8192), 16, 0, 0); } while (0)
; #define PG8_LDA(dst, b, h) do { _Pragma("unroll") for (int m = 0; m < 4; ++m) _Pragma("unroll") for (int k = 0; k < 2; ++k) dst[m][k] = *(const PG8_LAS bf16x8*)(lds + PG8_SA(b, h) + aoff + m * 2048 + k * 1024); } while (0)
; #define PG8_LDB(dst, b, h) do { _Pragma("unroll") for (int n = 0; n < 2; ++n) _Pragma("unroll") for (int k = 0; k < 2; ++k) dst[n][k] = *(const PG8_LAS bf16x8*)(lds + PG8_SB(b, h) + boff + n * 2048 + k * 1024); } while (0)
; #define PG8_WAIT_V(n) asm volatile("s_waitcnt vmcnt(" #n ")" ::: "memory")
; #define PG8_WAIT_L(n) asm volatile("s_waitcnt lgkmcnt(" #n ")" ::: "memory")
; #define PG8_BAR __builtin_amdgcn_s_barrier()
; #define PG8_SCHED __builtin_amdgcn_sched_barrier(0)
; template <class Epi, class Sched, bool ALIGN_EPI = false, bool SP2 = false>
; __device__ __forceinline__ void gemm_phase(PG8_LAS unsigned char* lds, const Gemm g, const Sched& S, const Epi& E) {
;     ...
;         const char* nA = has_next ? (const char*)g.A + (size_t)nxt.pm * tstep : cA; const char* nB = has_next ? (const char*)g.Bt + (size_t)nxt.pn * tstep : cB;
;         for (int t = 0; t < nt; t += 2) {
;             const bool last = (t == nt - 2);
;             const char* a1 = cA + (size_t)(t + 1) * kstep;
;             const char* a2 = last ? nA : cA + (size_t)(t + 2) * kstep; const char* b2 = last ? nB : cB + (size_t)(t + 2) * kstep;
;             const char* a3 = a2 + kstep; const char* b3 = b2 + kstep;
;             if (last && has_next) S.a_ready(nxt);
;             if constexpr (SP2) {
;             PG8_LDB(B0, 0, 0); PG8_LDB(B1, 0, 1); PG8_SCHED; PG8_LDA(At, 0, 0); PG8_STAGE(PG8_SA(1, 0), a1, voffA); PG8_STAGE(PG8_SA(1, 1), a1 + hstep, voffA);
;             PG8_WAIT_V(8); PG8_WAIT_L(0); PG8_BAR; PG8_MMA(0, 0, At, B0); PG8_MMA(0, 1, At, B1); PG8_BAR; PG8_SCHED;
;             PG8_LDA(At, 0, 1); PG8_STAGE(PG8_SB(0, 0), b2, voffB); PG8_STAGE(PG8_SB(0, 1), b2 + hstep, voffB);
;             PG8_WAIT_V(6); PG8_WAIT_L(0); PG8_BAR; PG8_MMA(1, 0, At, B0); PG8_MMA(1, 1, At, B1); PG8_BAR; PG8_SCHED;
.LBB0_231:
	s_ashr_i32 s47, s46, 31
	s_lshl_b64 s[52:53], s[46:47], 20
	s_add_u32 s72, s20, s52
	s_addc_u32 s73, s21, s53
	s_and_b64 s[52:53], s[38:39], exec
	s_cselect_b32 s47, s73, s17
	s_cselect_b32 s68, s72, s16
	s_ashr_i32 s11, s10, 31
	s_lshl_b64 s[52:53], s[10:11], 20
	s_add_u32 s76, s22, s52
	s_addc_u32 s77, s75, s53
	s_and_b64 s[52:53], s[38:39], exec
	s_cselect_b32 s11, s77, s45
	s_cselect_b32 s69, s76, s44
	s_add_u32 s70, s44, 0x100
	s_addc_u32 s71, s45, 0
	v_lshl_add_u64 v[96:97], s[16:17], 0, v[150:151]
	v_lshl_add_u64 v[98:99], s[16:17], 0, v[152:153]
	s_mov_b32 s52, -2
	s_mov_b64 s[88:89], 0
	s_add_u32 s44, s16, s88
	s_addc_u32 s45, s17, s89
	s_add_u32 s53, s44, 0x100
	s_addc_u32 s78, s45, 0
	s_add_u32 s44, s70, s88
	s_addc_u32 s45, s71, s89
	s_add_i32 s79, 0, 0x10000
	s_cmpk_eq_i32 s88, 0xf00
	s_cselect_b32 s45, s11, s45
	s_cselect_b32 s44, s69, s44
	s_cselect_b32 s95, s47, s78
	s_cselect_b32 s94, s68, s53
	s_add_i32 s53, 0, 0x14000
	v_add_u32_e32 v154, s79, v161
	v_add_u32_e32 v158, s53, v161
	ds_read_b128 v[100:103], v154
	ds_read_b128 v[104:107], v154 offset:1024
	ds_read_b128 v[108:111], v154 offset:2048
	ds_read_b128 v[154:157], v154 offset:3072
	ds_read_b128 v[164:167], v158
	ds_read_b128 v[168:171], v158 offset:1024
	ds_read_b128 v[172:175], v158 offset:2048
	ds_read_b128 v[176:179], v158 offset:3072
	v_lshl_add_u64 v[158:159], v[96:97], 0, s[88:89]
	v_lshl_add_u64 v[206:207], v[158:159], 0, s[26:27]
	s_add_i32 m0, s57, 0x8000
	global_load_lds_dwordx4 v[206:207], off
	v_lshl_add_u64 v[206:207], v[98:99], 0, s[88:89]
	v_lshl_add_u64 v[208:209], v[206:207], 0, s[26:27]
	s_add_i32 m0, s57, 0xa000
	v_lshl_add_u64 v[158:159], v[158:159], 0, s[28:29]
	global_load_lds_dwordx4 v[208:209], off
	s_add_i32 m0, s57, 0xc000
	s_nop 0
	global_load_lds_dwordx4 v[158:159], off
	s_add_i32 m0, s57, 0xe000
	v_lshl_add_u64 v[158:159], v[206:207], 0, s[28:29]
	global_load_lds_dwordx4 v[158:159], off
	s_waitcnt vmcnt(8)
	s_waitcnt lgkmcnt(0)
	s_barrier
	v_mfma_f32_16x16x32_bf16 v[140:143], v[100:103], v[180:183], 0
	v_mfma_f32_16x16x32_bf16 v[136:139], v[108:111], v[180:183], 0
	v_mfma_f32_16x16x32_bf16 v[124:127], v[100:103], v[188:191], 0
	v_mfma_f32_16x16x32_bf16 v[120:123], v[108:111], v[188:191], 0
	v_mfma_f32_16x16x32_bf16 v[92:95], v[100:103], v[196:199], 0
	v_mfma_f32_16x16x32_bf16 v[88:91], v[108:111], v[196:199], 0
	v_mfma_f32_16x16x32_bf16 v[76:79], v[100:103], v[218:221], 0
	v_mfma_f32_16x16x32_bf16 v[72:75], v[108:111], v[218:221], 0
	v_mfma_f32_16x16x32_bf16 v[140:143], v[104:107], v[184:187], v[140:143]
	v_mfma_f32_16x16x32_bf16 v[136:139], v[154:157], v[184:187], v[136:139]
	v_mfma_f32_16x16x32_bf16 v[124:127], v[104:107], v[192:195], v[124:127]
	v_mfma_f32_16x16x32_bf16 v[120:123], v[154:157], v[192:195], v[120:123]
	v_mfma_f32_16x16x32_bf16 v[92:95], v[104:107], v[200:203], v[92:95]
	v_mfma_f32_16x16x32_bf16 v[88:91], v[154:157], v[200:203], v[88:91]
	v_mfma_f32_16x16x32_bf16 v[76:79], v[104:107], v[232:235], v[76:79]
	v_mfma_f32_16x16x32_bf16 v[72:75], v[154:157], v[232:235], v[72:75]
	v_mfma_f32_16x16x32_bf16 v[132:135], v[164:167], v[180:183], 0
	v_mfma_f32_16x16x32_bf16 v[128:131], v[172:175], v[180:183], 0
	v_mfma_f32_16x16x32_bf16 v[116:119], v[164:167], v[188:191], 0
	v_mfma_f32_16x16x32_bf16 v[112:115], v[172:175], v[188:191], 0
	v_mfma_f32_16x16x32_bf16 v[84:87], v[164:167], v[196:199], 0
	v_mfma_f32_16x16x32_bf16 v[80:83], v[172:175], v[196:199], 0
	v_mfma_f32_16x16x32_bf16 v[68:71], v[164:167], v[218:221], 0
	v_mfma_f32_16x16x32_bf16 v[64:67], v[172:175], v[218:221], 0
	v_mfma_f32_16x16x32_bf16 v[132:135], v[168:171], v[184:187], v[132:135]
	v_mfma_f32_16x16x32_bf16 v[128:131], v[176:179], v[184:187], v[128:131]
	v_mfma_f32_16x16x32_bf16 v[116:119], v[168:171], v[192:195], v[116:119]
	v_mfma_f32_16x16x32_bf16 v[112:115], v[176:179], v[192:195], v[112:115]
	v_mfma_f32_16x16x32_bf16 v[84:87], v[168:171], v[200:203], v[84:87]
	v_mfma_f32_16x16x32_bf16 v[80:83], v[176:179], v[200:203], v[80:83]
	v_mfma_f32_16x16x32_bf16 v[68:71], v[168:171], v[232:235], v[68:71]
	v_mfma_f32_16x16x32_bf16 v[64:67], v[176:179], v[232:235], v[64:67]
	s_barrier
	s_add_i32 s78, s79, s23
	v_lshl_add_u64 v[158:159], s[44:45], 0, v[204:205]
	s_mov_b32 m0, s78
	ds_read_b128 v[180:183], v163 offset:16384
	ds_read_b128 v[184:187], v163 offset:17408
	ds_read_b128 v[188:191], v163 offset:18432
	ds_read_b128 v[192:195], v163 offset:19456
	ds_read_b128 v[196:199], v163 offset:20480
	ds_read_b128 v[200:203], v163 offset:21504
	ds_read_b128 v[218:221], v163 offset:22528
	ds_read_b128 v[232:235], v163 offset:23552
	global_load_lds_dwordx4 v[158:159], off
	s_add_i32 m0, s78, 0x2000
	s_add_u32 s78, s44, 0x80000
	v_lshl_add_u64 v[206:207], s[44:45], 0, v[144:145]
	s_addc_u32 s79, s45, 0
	s_add_i32 s53, s53, s23
	global_load_lds_dwordx4 v[206:207], off
	s_mov_b32 m0, s53
	v_lshl_add_u64 v[208:209], s[78:79], 0, v[204:205]
	global_load_lds_dwordx4 v[208:209], off
	s_add_i32 m0, s53, 0x2000
	v_lshl_add_u64 v[208:209], s[78:79], 0, v[144:145]
	global_load_lds_dwordx4 v[208:209], off
	s_waitcnt vmcnt(6)
	s_waitcnt lgkmcnt(0)
	s_barrier
; #define PG8_STAGE(bufoff, gbase, voff) do { _Pragma("unroll") for (int _i = 0; _i < 2; ++_i) \
;         __builtin_amdgcn_global_load_lds((const unsigned*)((const char*)(gbase) + (voff)[_i]), (PG8_LAS unsigned*)(lds + (bufoff) + ldsw + _i * 8192), 16, 0, 0); } while (0)
; #define PG8_LDA(dst, b, h) do { _Pragma("unroll") for (int m = 0; m < 4; ++m) _Pragma("unroll") for (int k = 0; k < 2; ++k) dst[m][k] = *(const PG8_LAS bf16x8*)(lds + PG8_SA(b, h) + aoff + m * 2048 + k * 1024); } while (0)
; #define PG8_LDB(dst, b, h) do { _Pragma("unroll") for (int n = 0; n < 2; ++n) _Pragma("unroll") for (int k = 0; k < 2; ++k) dst[n][k] = *(const PG8_LAS bf16x8*)(lds + PG8_SB(b, h) + boff + n * 2048 + k * 1024); } while (0)
; #define PG8_MMA(ai, bj, At, Bt) do { __builtin_amdgcn_s_setprio(1); _Pragma("unroll") for (int m = 0; m < 4; ++m) _Pragma("unroll") for (int n = 0; n < 2; ++n) _Pragma("unroll") for (int k = 0; k < 2; ++k) \
;         acc[ai][bj][m][n] = __builtin_amdgcn_mfma_f32_16x16x32_bf16(Bt[n][k], At[m][k], acc[ai][bj][m][n], 0, 0, 0); __builtin_amdgcn_s_setprio(0); } while (0)
; #define PG8_WAIT_V(n) asm volatile("s_waitcnt vmcnt(" #n ")" ::: "memory")
; #define PG8_WAIT_L(n) asm volatile("s_waitcnt lgkmcnt(" #n ")" ::: "memory")
; #define PG8_BAR __builtin_amdgcn_s_barrier()
; #define PG8_SCHED __builtin_amdgcn_sched_barrier(0)
; template <class Epi, class Sched, bool ALIGN_EPI = false, bool SP2 = false>
; __device__ __forceinline__ void gemm_phase(PG8_LAS unsigned char* lds, const Gemm g, const Sched& S, const Epi& E) {
;     ...
;             const char* a2 = last ? nA : cA + (size_t)(t + 2) * kstep; const char* b2 = last ? nB : cB + (size_t)(t + 2) * kstep;
;             const char* a3 = a2 + kstep; const char* b3 = b2 + kstep;
;             if (last && has_next) S.a_ready(nxt);
;             if constexpr (SP2) {
;             PG8_LDB(B0, 0, 0); PG8_LDB(B1, 0, 1); PG8_SCHED; PG8_LDA(At, 0, 0); PG8_STAGE(PG8_SA(1, 0), a1, voffA); PG8_STAGE(PG8_SA(1, 1), a1 + hstep, voffA);
;             PG8_WAIT_V(8); PG8_WAIT_L(0); PG8_BAR; PG8_MMA(0, 0, At, B0); PG8_MMA(0, 1, At, B1); PG8_BAR; PG8_SCHED;
;             PG8_LDA(At, 0, 1); PG8_STAGE(PG8_SB(0, 0), b2, voffB); PG8_STAGE(PG8_SB(0, 1), b2 + hstep, voffB);
;             PG8_WAIT_V(6); PG8_WAIT_L(0); PG8_BAR; PG8_MMA(1, 0, At, B0); PG8_MMA(1, 1, At, B1); PG8_BAR; PG8_SCHED;
	v_mfma_f32_16x16x32_bf16 v[60:63], v[100:103], v[180:183], 0
	v_mfma_f32_16x16x32_bf16 v[56:59], v[108:111], v[180:183], 0
	v_mfma_f32_16x16x32_bf16 v[48:51], v[100:103], v[188:191], 0
	v_mfma_f32_16x16x32_bf16 v[40:43], v[108:111], v[188:191], 0
	v_mfma_f32_16x16x32_bf16 v[32:35], v[100:103], v[196:199], 0
	v_mfma_f32_16x16x32_bf16 v[24:27], v[108:111], v[196:199], 0
	v_mfma_f32_16x16x32_bf16 v[16:19], v[100:103], v[218:221], 0
	v_mfma_f32_16x16x32_bf16 v[8:11], v[108:111], v[218:221], 0
	v_mfma_f32_16x16x32_bf16 v[60:63], v[104:107], v[184:187], v[60:63]
	v_mfma_f32_16x16x32_bf16 v[56:59], v[154:157], v[184:187], v[56:59]
	v_mfma_f32_16x16x32_bf16 v[48:51], v[104:107], v[192:195], v[48:51]
	v_mfma_f32_16x16x32_bf16 v[40:43], v[154:157], v[192:195], v[40:43]
	v_mfma_f32_16x16x32_bf16 v[32:35], v[104:107], v[200:203], v[32:35]
	v_mfma_f32_16x16x32_bf16 v[24:27], v[154:157], v[200:203], v[24:27]
	v_mfma_f32_16x16x32_bf16 v[16:19], v[104:107], v[232:235], v[16:19]
	v_mfma_f32_16x16x32_bf16 v[8:11], v[154:157], v[232:235], v[8:11]
	v_mfma_f32_16x16x32_bf16 v[52:55], v[164:167], v[180:183], 0
	v_mfma_f32_16x16x32_bf16 v[44:47], v[172:175], v[180:183], 0
	v_mfma_f32_16x16x32_bf16 v[36:39], v[164:167], v[188:191], 0
	v_mfma_f32_16x16x32_bf16 v[28:31], v[172:175], v[188:191], 0
	v_mfma_f32_16x16x32_bf16 v[20:23], v[164:167], v[196:199], 0
	v_mfma_f32_16x16x32_bf16 v[12:15], v[172:175], v[196:199], 0
	v_mfma_f32_16x16x32_bf16 v[4:7], v[164:167], v[218:221], 0
	v_mfma_f32_16x16x32_bf16 v[0:3], v[172:175], v[218:221], 0
	v_mfma_f32_16x16x32_bf16 v[52:55], v[168:171], v[184:187], v[52:55]
	v_mfma_f32_16x16x32_bf16 v[44:47], v[176:179], v[184:187], v[44:47]
	v_mfma_f32_16x16x32_bf16 v[36:39], v[168:171], v[192:195], v[36:39]
	v_mfma_f32_16x16x32_bf16 v[28:31], v[176:179], v[192:195], v[28:31]
	v_mfma_f32_16x16x32_bf16 v[20:23], v[168:171], v[200:203], v[20:23]
	v_mfma_f32_16x16x32_bf16 v[12:15], v[176:179], v[200:203], v[12:15]
	v_mfma_f32_16x16x32_bf16 v[4:7], v[168:171], v[232:235], v[4:7]
	v_mfma_f32_16x16x32_bf16 v[0:3], v[176:179], v[232:235], v[0:3]
	s_barrier
	s_branch .Lpl_vt
.LBB0_232:
	s_add_u32 s44, s16, s88
	s_addc_u32 s45, s17, s89
	s_add_u32 s53, s44, 0x100
	s_addc_u32 s78, s45, 0
	s_add_u32 s44, s70, s88
	s_addc_u32 s45, s71, s89
	s_add_i32 s79, 0, 0x10000
	s_cmpk_eq_i32 s88, 0xf00
	s_cselect_b32 s45, s11, s45
	s_cselect_b32 s44, s69, s44
	s_cselect_b32 s95, s47, s78
	s_cselect_b32 s94, s68, s53
	s_add_i32 s53, 0, 0x14000
	v_add_u32_e32 v154, s79, v161
	v_add_u32_e32 v158, s53, v161
	ds_read_b128 v[100:103], v154
	ds_read_b128 v[104:107], v154 offset:1024
	ds_read_b128 v[108:111], v154 offset:2048
	ds_read_b128 v[154:157], v154 offset:3072
	ds_read_b128 v[164:167], v158
	ds_read_b128 v[168:171], v158 offset:1024
	ds_read_b128 v[172:175], v158 offset:2048
	ds_read_b128 v[176:179], v158 offset:3072
	v_lshl_add_u64 v[158:159], v[96:97], 0, s[88:89]
	v_lshl_add_u64 v[206:207], v[158:159], 0, s[26:27]
	s_add_i32 m0, s57, 0x8000
	ds_read_b128 v[180:183], v163
	ds_read_b128 v[184:187], v163 offset:1024
	ds_read_b128 v[188:191], v163 offset:2048
	ds_read_b128 v[192:195], v163 offset:3072
	ds_read_b128 v[196:199], v163 offset:4096
	ds_read_b128 v[200:203], v163 offset:5120
	ds_read_b128 v[218:221], v163 offset:6144
	ds_read_b128 v[232:235], v163 offset:7168
	global_load_lds_dwordx4 v[206:207], off
	v_lshl_add_u64 v[206:207], v[98:99], 0, s[88:89]
	v_lshl_add_u64 v[208:209], v[206:207], 0, s[26:27]
	s_add_i32 m0, s57, 0xa000
	v_lshl_add_u64 v[158:159], v[158:159], 0, s[28:29]
	global_load_lds_dwordx4 v[208:209], off
	s_add_i32 m0, s57, 0xc000
	s_nop 0
	global_load_lds_dwordx4 v[158:159], off
	s_add_i32 m0, s57, 0xe000
	v_lshl_add_u64 v[158:159], v[206:207], 0, s[28:29]
	global_load_lds_dwordx4 v[158:159], off
	s_waitcnt vmcnt(8)
	s_waitcnt lgkmcnt(0)
	s_barrier
	v_mfma_f32_16x16x32_bf16 v[140:143], v[100:103], v[180:183], v[140:143]
	v_mfma_f32_16x16x32_bf16 v[136:139], v[108:111], v[180:183], v[136:139]
	v_mfma_f32_16x16x32_bf16 v[124:127], v[100:103], v[188:191], v[124:127]
	v_mfma_f32_16x16x32_bf16 v[120:123], v[108:111], v[188:191], v[120:123]
	v_mfma_f32_16x16x32_bf16 v[92:95], v[100:103], v[196:199], v[92:95]
	v_mfma_f32_16x16x32_bf16 v[88:91], v[108:111], v[196:199], v[88:91]
	v_mfma_f32_16x16x32_bf16 v[76:79], v[100:103], v[218:221], v[76:79]
	v_mfma_f32_16x16x32_bf16 v[72:75], v[108:111], v[218:221], v[72:75]
	v_mfma_f32_16x16x32_bf16 v[140:143], v[104:107], v[184:187], v[140:143]
	v_mfma_f32_16x16x32_bf16 v[136:139], v[154:157], v[184:187], v[136:139]
	v_mfma_f32_16x16x32_bf16 v[124:127], v[104:107], v[192:195], v[124:127]
	v_mfma_f32_16x16x32_bf16 v[120:123], v[154:157], v[192:195], v[120:123]
	v_mfma_f32_16x16x32_bf16 v[92:95], v[104:107], v[200:203], v[92:95]
	v_mfma_f32_16x16x32_bf16 v[88:91], v[154:157], v[200:203], v[88:91]
	v_mfma_f32_16x16x32_bf16 v[76:79], v[104:107], v[232:235], v[76:79]
	v_mfma_f32_16x16x32_bf16 v[72:75], v[154:157], v[232:235], v[72:75]
	v_mfma_f32_16x16x32_bf16 v[132:135], v[164:167], v[180:183], v[132:135]
	v_mfma_f32_16x16x32_bf16 v[128:131], v[172:175], v[180:183], v[128:131]
	v_mfma_f32_16x16x32_bf16 v[116:119], v[164:167], v[188:191], v[116:119]
	v_mfma_f32_16x16x32_bf16 v[112:115], v[172:175], v[188:191], v[112:115]
	v_mfma_f32_16x16x32_bf16 v[84:87], v[164:167], v[196:199], v[84:87]
	v_mfma_f32_16x16x32_bf16 v[80:83], v[172:175], v[196:199], v[80:83]
	v_mfma_f32_16x16x32_bf16 v[68:71], v[164:167], v[218:221], v[68:71]
	v_mfma_f32_16x16x32_bf16 v[64:67], v[172:175], v[218:221], v[64:67]
	v_mfma_f32_16x16x32_bf16 v[132:135], v[168:171], v[184:187], v[132:135]
	v_mfma_f32_16x16x32_bf16 v[128:131], v[176:179], v[184:187], v[128:131]
	v_mfma_f32_16x16x32_bf16 v[116:119], v[168:171], v[192:195], v[116:119]
	v_mfma_f32_16x16x32_bf16 v[112:115], v[176:179], v[192:195], v[112:115]
	v_mfma_f32_16x16x32_bf16 v[84:87], v[168:171], v[200:203], v[84:87]
	v_mfma_f32_16x16x32_bf16 v[80:83], v[176:179], v[200:203], v[80:83]
	v_mfma_f32_16x16x32_bf16 v[68:71], v[168:171], v[232:235], v[68:71]
	v_mfma_f32_16x16x32_bf16 v[64:67], v[176:179], v[232:235], v[64:67]
	s_barrier
; #define PG8_STAGE(bufoff, gbase, voff) do { _Pragma("unroll") for (int _i = 0; _i < 2; ++_i) \
;         __builtin_amdgcn_global_load_lds((const unsigned*)((const char*)(gbase) + (voff)[_i]), (PG8_LAS unsigned*)(lds + (bufoff) + ldsw + _i * 8192), 16, 0, 0); } while (0)
; #define PG8_LDA(dst, b, h) do { _Pragma("unroll") for (int m = 0; m < 4; ++m) _Pragma("unroll") for (int k = 0; k < 2; ++k) dst[m][k] = *(const PG8_LAS bf16x8*)(lds + PG8_SA(b, h) + aoff + m * 2048 + k * 1024); } while (0)
; #define PG8_MMA(ai, bj, At, Bt) do { __builtin_amdgcn_s_setprio(1); _Pragma("unroll") for (int m = 0; m < 4; ++m) _Pragma("unroll") for (int n = 0; n < 2; ++n) _Pragma("unroll") for (int k = 0; k < 2; ++k) \
;         acc[ai][bj][m][n] = __builtin_amdgcn_mfma_f32_16x16x32_bf16(Bt[n][k], At[m][k], acc[ai][bj][m][n], 0, 0, 0); __builtin_amdgcn_s_setprio(0); } while (0)
; #define PG8_WAIT_V(n) asm volatile("s_waitcnt vmcnt(" #n ")" ::: "memory")
; #define PG8_WAIT_L(n) asm volatile("s_waitcnt lgkmcnt(" #n ")" ::: "memory")
; #define PG8_BAR __builtin_amdgcn_s_barrier()
; #define PG8_SCHED __builtin_amdgcn_sched_barrier(0)
; template <class Epi, class Sched, bool ALIGN_EPI = false, bool SP2 = false>
; __device__ __forceinline__ void gemm_phase(PG8_LAS unsigned char* lds, const Gemm g, const Sched& S, const Epi& E) {
;     ...
;             PG8_LDA(At, 0, 1); PG8_STAGE(PG8_SB(0, 0), b2, voffB); PG8_STAGE(PG8_SB(0, 1), b2 + hstep, voffB);
;             PG8_WAIT_V(6); PG8_WAIT_L(0); PG8_BAR; PG8_MMA(1, 0, At, B0); PG8_MMA(1, 1, At, B1); PG8_BAR; PG8_SCHED;
	s_add_i32 s78, s79, s23
	v_lshl_add_u64 v[158:159], s[44:45], 0, v[204:205]
	s_mov_b32 m0, s78
	ds_read_b128 v[180:183], v163 offset:16384
	ds_read_b128 v[184:187], v163 offset:17408
	ds_read_b128 v[188:191], v163 offset:18432
	ds_read_b128 v[192:195], v163 offset:19456
	ds_read_b128 v[196:199], v163 offset:20480
	ds_read_b128 v[200:203], v163 offset:21504
	ds_read_b128 v[218:221], v163 offset:22528
	ds_read_b128 v[232:235], v163 offset:23552
	global_load_lds_dwordx4 v[158:159], off
	s_add_i32 m0, s78, 0x2000
	s_add_u32 s78, s44, 0x80000
	v_lshl_add_u64 v[206:207], s[44:45], 0, v[144:145]
	s_addc_u32 s79, s45, 0
	s_add_i32 s53, s53, s23
	global_load_lds_dwordx4 v[206:207], off
	s_mov_b32 m0, s53
	v_lshl_add_u64 v[208:209], s[78:79], 0, v[204:205]
	global_load_lds_dwordx4 v[208:209], off
	s_add_i32 m0, s53, 0x2000
	v_lshl_add_u64 v[208:209], s[78:79], 0, v[144:145]
	global_load_lds_dwordx4 v[208:209], off
	s_waitcnt vmcnt(6)
	s_waitcnt lgkmcnt(0)
	s_barrier
	v_mfma_f32_16x16x32_bf16 v[60:63], v[100:103], v[180:183], v[60:63]
	v_mfma_f32_16x16x32_bf16 v[56:59], v[108:111], v[180:183], v[56:59]
	v_mfma_f32_16x16x32_bf16 v[48:51], v[100:103], v[188:191], v[48:51]
	v_mfma_f32_16x16x32_bf16 v[40:43], v[108:111], v[188:191], v[40:43]
	v_mfma_f32_16x16x32_bf16 v[32:35], v[100:103], v[196:199], v[32:35]
	v_mfma_f32_16x16x32_bf16 v[24:27], v[108:111], v[196:199], v[24:27]
	v_mfma_f32_16x16x32_bf16 v[16:19], v[100:103], v[218:221], v[16:19]
	v_mfma_f32_16x16x32_bf16 v[8:11], v[108:111], v[218:221], v[8:11]
	v_mfma_f32_16x16x32_bf16 v[60:63], v[104:107], v[184:187], v[60:63]
	v_mfma_f32_16x16x32_bf16 v[56:59], v[154:157], v[184:187], v[56:59]
	v_mfma_f32_16x16x32_bf16 v[48:51], v[104:107], v[192:195], v[48:51]
	v_mfma_f32_16x16x32_bf16 v[40:43], v[154:157], v[192:195], v[40:43]
	v_mfma_f32_16x16x32_bf16 v[32:35], v[104:107], v[200:203], v[32:35]
	v_mfma_f32_16x16x32_bf16 v[24:27], v[154:157], v[200:203], v[24:27]
	v_mfma_f32_16x16x32_bf16 v[16:19], v[104:107], v[232:235], v[16:19]
	v_mfma_f32_16x16x32_bf16 v[8:11], v[154:157], v[232:235], v[8:11]
	v_mfma_f32_16x16x32_bf16 v[52:55], v[164:167], v[180:183], v[52:55]
	v_mfma_f32_16x16x32_bf16 v[44:47], v[172:175], v[180:183], v[44:47]
	v_mfma_f32_16x16x32_bf16 v[36:39], v[164:167], v[188:191], v[36:39]
	v_mfma_f32_16x16x32_bf16 v[28:31], v[172:175], v[188:191], v[28:31]
	v_mfma_f32_16x16x32_bf16 v[20:23], v[164:167], v[196:199], v[20:23]
	v_mfma_f32_16x16x32_bf16 v[12:15], v[172:175], v[196:199], v[12:15]
	v_mfma_f32_16x16x32_bf16 v[4:7], v[164:167], v[218:221], v[4:7]
	v_mfma_f32_16x16x32_bf16 v[0:3], v[172:175], v[218:221], v[0:3]
	v_mfma_f32_16x16x32_bf16 v[52:55], v[168:171], v[184:187], v[52:55]
	v_mfma_f32_16x16x32_bf16 v[44:47], v[176:179], v[184:187], v[44:47]
	v_mfma_f32_16x16x32_bf16 v[36:39], v[168:171], v[192:195], v[36:39]
	v_mfma_f32_16x16x32_bf16 v[28:31], v[176:179], v[192:195], v[28:31]
	v_mfma_f32_16x16x32_bf16 v[20:23], v[168:171], v[200:203], v[20:23]
	v_mfma_f32_16x16x32_bf16 v[12:15], v[176:179], v[200:203], v[12:15]
	v_mfma_f32_16x16x32_bf16 v[4:7], v[168:171], v[232:235], v[4:7]
	v_mfma_f32_16x16x32_bf16 v[0:3], v[176:179], v[232:235], v[0:3]
	s_barrier
; #define PG8_STAGE(bufoff, gbase, voff) do { _Pragma("unroll") for (int _i = 0; _i < 2; ++_i) \
;         __builtin_amdgcn_global_load_lds((const unsigned*)((const char*)(gbase) + (voff)[_i]), (PG8_LAS unsigned*)(lds + (bufoff) + ldsw + _i * 8192), 16, 0, 0); } while (0)
; #define PG8_LDA(dst, b, h) do { _Pragma("unroll") for (int m = 0; m < 4; ++m) _Pragma("unroll") for (int k = 0; k < 2; ++k) dst[m][k] = *(const PG8_LAS bf16x8*)(lds + PG8_SA(b, h) + aoff + m * 2048 + k * 1024); } while (0)
; #define PG8_LDB(dst, b, h) do { _Pragma("unroll") for (int n = 0; n < 2; ++n) _Pragma("unroll") for (int k = 0; k < 2; ++k) dst[n][k] = *(const PG8_LAS bf16x8*)(lds + PG8_SB(b, h) + boff + n * 2048 + k * 1024); } while (0)
; #define PG8_MMA(ai, bj, At, Bt) do { __builtin_amdgcn_s_setprio(1); _Pragma("unroll") for (int m = 0; m < 4; ++m) _Pragma("unroll") for (int n = 0; n < 2; ++n) _Pragma("unroll") for (int k = 0; k < 2; ++k) \
;         acc[ai][bj][m][n] = __builtin_amdgcn_mfma_f32_16x16x32_bf16(Bt[n][k], At[m][k], acc[ai][bj][m][n], 0, 0, 0); __builtin_amdgcn_s_setprio(0); } while (0)
; #define PG8_WAIT_V(n) asm volatile("s_waitcnt vmcnt(" #n ")" ::: "memory")
; #define PG8_WAIT_L(n) asm volatile("s_waitcnt lgkmcnt(" #n ")" ::: "memory")
; #define PG8_BAR __builtin_amdgcn_s_barrier()
; #define PG8_SCHED __builtin_amdgcn_sched_barrier(0)
; template <class Epi, class Sched, bool ALIGN_EPI = false, bool SP2 = false>
; __device__ __forceinline__ void gemm_phase(PG8_LAS unsigned char* lds, const Gemm g, const Sched& S, const Epi& E) {
;     ...
;             PG8_LDB(B0, 1, 0); PG8_LDB(B1, 1, 1); PG8_SCHED; PG8_LDA(At, 1, 0); PG8_STAGE(PG8_SA(0, 0), a2, voffA); PG8_STAGE(PG8_SA(0, 1), a2 + hstep, voffA);
;             PG8_WAIT_V(8); PG8_WAIT_L(0); PG8_BAR; PG8_MMA(0, 0, At, B0); PG8_MMA(0, 1, At, B1); PG8_BAR; PG8_SCHED;
;             PG8_LDA(At, 1, 1); PG8_STAGE(PG8_SB(1, 0), b3, voffB); PG8_STAGE(PG8_SB(1, 1), b3 + hstep, voffB); (void)a3;
;             PG8_WAIT_V(6); PG8_WAIT_L(0); PG8_BAR; PG8_MMA(1, 0, At, B0); PG8_MMA(1, 1, At, B1); PG8_BAR; PG8_SCHED;
.Lpl_vt:
	s_add_i32 s53, 0, 0x18000
	s_add_i32 s92, 0, 0x1c000
	v_add_u32_e32 v154, s53, v161
	v_add_u32_e32 v176, s92, v161
	ds_read_b128 v[100:103], v154
	ds_read_b128 v[104:107], v154 offset:1024
	ds_read_b128 v[108:111], v154 offset:2048
	ds_read_b128 v[154:157], v154 offset:3072
	ds_read_b128 v[164:167], v176
	ds_read_b128 v[168:171], v176 offset:1024
	ds_read_b128 v[172:175], v176 offset:2048
	ds_read_b128 v[176:179], v176 offset:3072
	s_mov_b32 m0, s57
	v_lshl_add_u64 v[208:209], s[94:95], 0, v[148:149]
	s_add_u32 s78, s94, 0x80000
	ds_read_b128 v[180:183], v163 offset:32768
	ds_read_b128 v[184:187], v163 offset:33792
	ds_read_b128 v[188:191], v163 offset:34816
	ds_read_b128 v[192:195], v163 offset:35840
	ds_read_b128 v[196:199], v163 offset:36864
	ds_read_b128 v[200:203], v163 offset:37888
	ds_read_b128 v[218:221], v163 offset:38912
	ds_read_b128 v[232:235], v163 offset:39936
	global_load_lds_dwordx4 v[208:209], off
	v_lshl_add_u64 v[208:209], s[94:95], 0, v[146:147]
	s_mov_b32 m0, s84
	s_addc_u32 s79, s95, 0
	global_load_lds_dwordx4 v[208:209], off
	s_mov_b32 m0, s97
	v_lshl_add_u64 v[208:209], s[78:79], 0, v[148:149]
	global_load_lds_dwordx4 v[208:209], off
	s_mov_b32 m0, s34
	v_lshl_add_u64 v[208:209], s[78:79], 0, v[146:147]
	global_load_lds_dwordx4 v[208:209], off
	s_waitcnt vmcnt(8)
	s_waitcnt lgkmcnt(0)
	s_barrier
	v_mfma_f32_16x16x32_bf16 v[140:143], v[100:103], v[180:183], v[140:143]
	v_mfma_f32_16x16x32_bf16 v[136:139], v[108:111], v[180:183], v[136:139]
	v_mfma_f32_16x16x32_bf16 v[124:127], v[100:103], v[188:191], v[124:127]
	v_mfma_f32_16x16x32_bf16 v[120:123], v[108:111], v[188:191], v[120:123]
	v_mfma_f32_16x16x32_bf16 v[92:95], v[100:103], v[196:199], v[92:95]
	v_mfma_f32_16x16x32_bf16 v[88:91], v[108:111], v[196:199], v[88:91]
	v_mfma_f32_16x16x32_bf16 v[76:79], v[100:103], v[218:221], v[76:79]
	v_mfma_f32_16x16x32_bf16 v[72:75], v[108:111], v[218:221], v[72:75]
	v_mfma_f32_16x16x32_bf16 v[140:143], v[104:107], v[184:187], v[140:143]
	v_mfma_f32_16x16x32_bf16 v[136:139], v[154:157], v[184:187], v[136:139]
	v_mfma_f32_16x16x32_bf16 v[124:127], v[104:107], v[192:195], v[124:127]
	v_mfma_f32_16x16x32_bf16 v[120:123], v[154:157], v[192:195], v[120:123]
	v_mfma_f32_16x16x32_bf16 v[92:95], v[104:107], v[200:203], v[92:95]
	v_mfma_f32_16x16x32_bf16 v[88:91], v[154:157], v[200:203], v[88:91]
	v_mfma_f32_16x16x32_bf16 v[76:79], v[104:107], v[232:235], v[76:79]
	v_mfma_f32_16x16x32_bf16 v[72:75], v[154:157], v[232:235], v[72:75]
	v_mfma_f32_16x16x32_bf16 v[132:135], v[164:167], v[180:183], v[132:135]
	v_mfma_f32_16x16x32_bf16 v[128:131], v[172:175], v[180:183], v[128:131]
	v_mfma_f32_16x16x32_bf16 v[116:119], v[164:167], v[188:191], v[116:119]
	v_mfma_f32_16x16x32_bf16 v[112:115], v[172:175], v[188:191], v[112:115]
	v_mfma_f32_16x16x32_bf16 v[84:87], v[164:167], v[196:199], v[84:87]
	v_mfma_f32_16x16x32_bf16 v[80:83], v[172:175], v[196:199], v[80:83]
	v_mfma_f32_16x16x32_bf16 v[68:71], v[164:167], v[218:221], v[68:71]
	v_mfma_f32_16x16x32_bf16 v[64:67], v[172:175], v[218:221], v[64:67]
	v_mfma_f32_16x16x32_bf16 v[132:135], v[168:171], v[184:187], v[132:135]
	v_mfma_f32_16x16x32_bf16 v[128:131], v[176:179], v[184:187], v[128:131]
	v_mfma_f32_16x16x32_bf16 v[116:119], v[168:171], v[192:195], v[116:119]
	v_mfma_f32_16x16x32_bf16 v[112:115], v[176:179], v[192:195], v[112:115]
	v_mfma_f32_16x16x32_bf16 v[84:87], v[168:171], v[200:203], v[84:87]
	v_mfma_f32_16x16x32_bf16 v[80:83], v[176:179], v[200:203], v[80:83]
	v_mfma_f32_16x16x32_bf16 v[68:71], v[168:171], v[232:235], v[68:71]
	v_mfma_f32_16x16x32_bf16 v[64:67], v[176:179], v[232:235], v[64:67]
	s_barrier
	s_add_i32 s53, s53, s23
	v_lshl_add_u64 v[158:159], v[158:159], 0, s[26:27]
	s_mov_b32 m0, s53
	ds_read_b128 v[180:183], v163 offset:49152
	ds_read_b128 v[184:187], v163 offset:50176
	ds_read_b128 v[188:191], v163 offset:51200
	ds_read_b128 v[192:195], v163 offset:52224
	ds_read_b128 v[196:199], v163 offset:53248
	ds_read_b128 v[200:203], v163 offset:54272
	ds_read_b128 v[218:221], v163 offset:55296
	ds_read_b128 v[232:235], v163 offset:56320
	global_load_lds_dwordx4 v[158:159], off
	s_add_i32 m0, s53, 0x2000
	s_add_u32 s44, s44, 0x80080
	v_lshl_add_u64 v[158:159], v[206:207], 0, s[26:27]
	s_addc_u32 s45, s45, 0
	s_add_i32 s53, s92, s23
	global_load_lds_dwordx4 v[158:159], off
	s_mov_b32 m0, s53
	v_lshl_add_u64 v[158:159], s[44:45], 0, v[204:205]
	global_load_lds_dwordx4 v[158:159], off
	s_add_i32 m0, s53, 0x2000
	v_lshl_add_u64 v[158:159], s[44:45], 0, v[144:145]
	global_load_lds_dwordx4 v[158:159], off
	s_waitcnt vmcnt(6)
	s_waitcnt lgkmcnt(0)
	s_barrier
	v_mfma_f32_16x16x32_bf16 v[60:63], v[100:103], v[180:183], v[60:63]
	v_mfma_f32_16x16x32_bf16 v[56:59], v[108:111], v[180:183], v[56:59]
	v_mfma_f32_16x16x32_bf16 v[48:51], v[100:103], v[188:191], v[48:51]
	v_mfma_f32_16x16x32_bf16 v[40:43], v[108:111], v[188:191], v[40:43]
	v_mfma_f32_16x16x32_bf16 v[32:35], v[100:103], v[196:199], v[32:35]
	v_mfma_f32_16x16x32_bf16 v[24:27], v[108:111], v[196:199], v[24:27]
	v_mfma_f32_16x16x32_bf16 v[16:19], v[100:103], v[218:221], v[16:19]
	v_mfma_f32_16x16x32_bf16 v[8:11], v[108:111], v[218:221], v[8:11]
	v_mfma_f32_16x16x32_bf16 v[60:63], v[104:107], v[184:187], v[60:63]
	v_mfma_f32_16x16x32_bf16 v[56:59], v[154:157], v[184:187], v[56:59]
	v_mfma_f32_16x16x32_bf16 v[48:51], v[104:107], v[192:195], v[48:51]
	v_mfma_f32_16x16x32_bf16 v[40:43], v[154:157], v[192:195], v[40:43]
	v_mfma_f32_16x16x32_bf16 v[32:35], v[104:107], v[200:203], v[32:35]
	v_mfma_f32_16x16x32_bf16 v[24:27], v[154:157], v[200:203], v[24:27]
	v_mfma_f32_16x16x32_bf16 v[16:19], v[104:107], v[232:235], v[16:19]
	v_mfma_f32_16x16x32_bf16 v[8:11], v[154:157], v[232:235], v[8:11]
	v_mfma_f32_16x16x32_bf16 v[52:55], v[164:167], v[180:183], v[52:55]
	v_mfma_f32_16x16x32_bf16 v[44:47], v[172:175], v[180:183], v[44:47]
	v_mfma_f32_16x16x32_bf16 v[36:39], v[164:167], v[188:191], v[36:39]
	v_mfma_f32_16x16x32_bf16 v[28:31], v[172:175], v[188:191], v[28:31]
	v_mfma_f32_16x16x32_bf16 v[20:23], v[164:167], v[196:199], v[20:23]
	v_mfma_f32_16x16x32_bf16 v[12:15], v[172:175], v[196:199], v[12:15]
	v_mfma_f32_16x16x32_bf16 v[4:7], v[164:167], v[218:221], v[4:7]
	v_mfma_f32_16x16x32_bf16 v[0:3], v[172:175], v[218:221], v[0:3]
	v_mfma_f32_16x16x32_bf16 v[52:55], v[168:171], v[184:187], v[52:55]
	v_mfma_f32_16x16x32_bf16 v[44:47], v[176:179], v[184:187], v[44:47]
	v_mfma_f32_16x16x32_bf16 v[36:39], v[168:171], v[192:195], v[36:39]
	v_mfma_f32_16x16x32_bf16 v[28:31], v[176:179], v[192:195], v[28:31]
	v_mfma_f32_16x16x32_bf16 v[20:23], v[168:171], v[200:203], v[20:23]
	v_mfma_f32_16x16x32_bf16 v[12:15], v[176:179], v[200:203], v[12:15]
	v_mfma_f32_16x16x32_bf16 v[4:7], v[168:171], v[232:235], v[4:7]
	v_mfma_f32_16x16x32_bf16 v[0:3], v[176:179], v[232:235], v[0:3]
	s_barrier
	s_add_i32 s52, s52, 2
	s_add_u32 s88, s88, 0x100
	s_addc_u32 s89, s89, 0
	s_cmp_gt_u32 s52, 29
	s_cbranch_scc0 .LBB0_232
	s_and_b64 vcc, exec, s[8:9]
	s_cbranch_vccz .LBB0_235
	s_barrier

; #define ATT_STAGE(t_, buf_) do { const char* gb_ = gbase + (size_t)(t_) * tstep; _Pragma("unroll") for (int j_ = 0; j_ < NPW * REP_DMA; ++j_) \
;         __builtin_amdgcn_global_load_lds((const unsigned*)(gb_ + ATT_CJ(j_ % NPW) + vbase), (LAS unsigned*)(lds + (buf_) * STAGE + (wid * NPW + j_ % NPW) * 1024), 16, 0, 0); } while (0)
; template <int DV, int NMAP> ...
;     ...
;     for (int t = T0; t <= T1; ++t) {
;         const int cur = (t - T0) & 1;
;         asm volatile("s_waitcnt vmcnt(0)" ::: "memory");
;         asm volatile("s_waitcnt lgkmcnt(0)" ::: "memory"); __builtin_amdgcn_s_barrier(); asm volatile("" ::: "memory");
;         const bool inr = (t >= lo_w && t <= cw);
;         if (t < T1 && (isk || !inr)) ATT_STAGE(t + 1, cur ^ 1);
.LBB0_351:
	s_add_i32 s57, s57, 1
	s_and_b32 s52, s57, 1
	s_cmp_lt_u32 s57, s36
	s_cselect_b64 s[44:45], -1, 0
	s_cmp_gt_i32 s57, s35
	s_cselect_b64 s[68:69], -1, 0
	s_or_b64 s[44:45], s[44:45], s[68:69]
	s_cmp_ge_i32 s57, s34
	s_waitcnt vmcnt(0)
	s_cselect_b64 s[72:73], -1, 0
	s_cmp_lt_i32 s57, s34
	s_waitcnt lgkmcnt(0)
	s_barrier
	s_cselect_b64 s[68:69], -1, 0
	s_or_b64 s[70:71], s[6:7], s[44:45]
	s_and_b64 s[68:69], s[68:69], s[70:71]
	s_andn2_b64 vcc, exec, s[68:69]
	s_cbranch_vccnz .LBB0_353
	s_lshl_b32 s53, s52, 15
	s_xor_b32 s53, s53, 0x8000
	s_add_i32 s53, s23, s53
	s_mov_b32 m0, s53
	v_lshl_add_u64 v[96:97], s[38:39], 0, v[204:205]
	global_load_lds_dwordx4 v[96:97], off
	s_add_i32 m0, s53, 0x400
	v_lshl_add_u64 v[96:97], v[96:97], 0, 64
	global_load_lds_dwordx4 v[96:97], off
	s_add_i32 m0, s53, 0x800
	v_lshl_add_u64 v[96:97], s[16:17], 0, v[204:205]
	global_load_lds_dwordx4 v[96:97], off
	s_add_i32 m0, s53, 0xc00
	v_lshl_add_u64 v[96:97], s[10:11], 0, v[204:205]
	global_load_lds_dwordx4 v[96:97], off

; #define PG8_STAGE(bufoff, gbase, voff) do { _Pragma("unroll") for (int _i = 0; _i < 2; ++_i) \
;         __builtin_amdgcn_global_load_lds((const unsigned*)((const char*)(gbase) + (voff)[_i]), (PG8_LAS unsigned*)(lds + (bufoff) + ldsw + _i * 8192), 16, 0, 0); } while (0)
; #define PG8_LDA(dst, b, h) do { _Pragma("unroll") for (int m = 0; m < 4; ++m) _Pragma("unroll") for (int k = 0; k < 2; ++k) dst[m][k] = *(const PG8_LAS bf16x8*)(lds + PG8_SA(b, h) + aoff + m * 2048 + k * 1024); } while (0)
; #define PG8_LDB(dst, b, h) do { _Pragma("unroll") for (int n = 0; n < 2; ++n) _Pragma("unroll") for (int k = 0; k < 2; ++k) dst[n][k] = *(const PG8_LAS bf16x8*)(lds + PG8_SB(b, h) + boff + n * 2048 + k * 1024); } while (0)
; #define PG8_WAIT_V(n) asm volatile("s_waitcnt vmcnt(" #n ")" ::: "memory")
; #define PG8_WAIT_L(n) asm volatile("s_waitcnt lgkmcnt(" #n ")" ::: "memory")
; #define PG8_BAR __builtin_amdgcn_s_barrier()
; #define PG8_SCHED __builtin_amdgcn_sched_barrier(0)
; template <class Epi, class Sched, bool ALIGN_EPI = false, bool SP2 = false>
; __device__ __forceinline__ void gemm_phase(PG8_LAS unsigned char* lds, const Gemm g, const Sched& S, const Epi& E) {
;     ...
;         const char* nA = has_next ? (const char*)g.A + (size_t)nxt.pm * tstep : cA; const char* nB = has_next ? (const char*)g.Bt + (size_t)nxt.pn * tstep : cB;
;         for (int t = 0; t < nt; t += 2) {
;             const bool last = (t == nt - 2);
;             const char* a1 = cA + (size_t)(t + 1) * kstep;
;             const char* a2 = last ? nA : cA + (size_t)(t + 2) * kstep; const char* b2 = last ? nB : cB + (size_t)(t + 2) * kstep;
;             const char* a3 = a2 + kstep; const char* b3 = b2 + kstep;
;             if (last && has_next) S.a_ready(nxt);
;             if constexpr (SP2) {
;             PG8_LDB(B0, 0, 0); PG8_LDB(B1, 0, 1); PG8_SCHED; PG8_LDA(At, 0, 0); PG8_STAGE(PG8_SA(1, 0), a1, voffA); PG8_STAGE(PG8_SA(1, 1), a1 + hstep, voffA);
;             PG8_WAIT_V(8); PG8_WAIT_L(0); PG8_BAR; PG8_MMA(0, 0, At, B0); PG8_MMA(0, 1, At, B1); PG8_BAR; PG8_SCHED;
;             PG8_LDA(At, 0, 1); PG8_STAGE(PG8_SB(0, 0), b2, voffB); PG8_STAGE(PG8_SB(0, 1), b2 + hstep, voffB);
;             PG8_WAIT_V(6); PG8_WAIT_L(0); PG8_BAR; PG8_MMA(1, 0, At, B0); PG8_MMA(1, 1, At, B1); PG8_BAR; PG8_SCHED;
.LBB0_425:
	s_ashr_i32 s47, s46, 31
	s_lshl_b64 s[52:53], s[46:47], 20
	s_add_u32 s72, s98, s52
	s_addc_u32 s73, s99, s53
	s_and_b64 s[52:53], s[38:39], exec
	s_cselect_b32 s47, s73, s17
	s_cselect_b32 s68, s72, s16
	s_ashr_i32 s43, s42, 31
	s_lshl_b64 s[52:53], s[42:43], 20
	s_add_u32 s76, s20, s52
	s_addc_u32 s77, s21, s53
	s_and_b64 s[52:53], s[38:39], exec
	s_cselect_b32 s43, s77, s45
	s_cselect_b32 s69, s76, s44
	s_add_u32 s70, s44, 0x100
	s_addc_u32 s71, s45, 0
	v_lshl_add_u64 v[138:139], s[16:17], 0, v[134:135]
	v_lshl_add_u64 v[140:141], s[16:17], 0, v[136:137]
	s_mov_b32 s52, -2
	s_mov_b64 s[88:89], 0
	s_add_u32 s44, s16, s88
	s_addc_u32 s45, s17, s89
	s_add_u32 s53, s44, 0x100
	s_addc_u32 s78, s45, 0
	s_add_u32 s44, s70, s88
	s_addc_u32 s45, s71, s89
	s_add_i32 s79, 0, 0x10000
	s_cmpk_eq_i32 s88, 0xf00
	s_cselect_b32 s45, s43, s45
	s_cselect_b32 s44, s69, s44
	s_cselect_b32 s95, s47, s78
	s_cselect_b32 s94, s68, s53
	s_add_i32 s53, 0, 0x14000
	v_add_u32_e32 v158, s79, v143
	ds_read_b128 v[146:149], v158
	ds_read_b128 v[150:153], v158 offset:1024
	ds_read_b128 v[154:157], v158 offset:2048
	ds_read_b128 v[158:161], v158 offset:3072
	v_lshl_add_u64 v[202:203], v[138:139], 0, s[88:89]
	v_lshl_add_u64 v[222:223], v[202:203], 0, s[26:27]
	s_add_i32 m0, s23, 0x8000
	global_load_lds_dwordx4 v[222:223], off
	v_lshl_add_u64 v[222:223], v[140:141], 0, s[88:89]
	v_lshl_add_u64 v[232:233], v[222:223], 0, s[26:27]
	s_add_i32 m0, s23, 0xa000
	v_lshl_add_u64 v[202:203], v[202:203], 0, s[28:29]
	global_load_lds_dwordx4 v[232:233], off
	s_add_i32 m0, s23, 0xc000
	s_nop 0
	global_load_lds_dwordx4 v[202:203], off
	s_add_i32 m0, s23, 0xe000
	v_lshl_add_u64 v[202:203], v[222:223], 0, s[28:29]
	global_load_lds_dwordx4 v[202:203], off
	s_waitcnt vmcnt(8)
	s_waitcnt lgkmcnt(0)
	s_barrier
	v_mfma_f32_16x16x32_bf16 v[124:127], v[146:149], v[178:181], 0
	v_mfma_f32_16x16x32_bf16 v[120:123], v[154:157], v[178:181], 0
	v_mfma_f32_16x16x32_bf16 v[116:119], v[146:149], v[186:189], 0
	v_mfma_f32_16x16x32_bf16 v[108:111], v[154:157], v[186:189], 0
	v_mfma_f32_16x16x32_bf16 v[100:103], v[146:149], v[194:197], 0
	v_mfma_f32_16x16x32_bf16 v[92:95], v[154:157], v[194:197], 0
	v_mfma_f32_16x16x32_bf16 v[84:87], v[146:149], v[206:209], 0
	v_mfma_f32_16x16x32_bf16 v[76:79], v[154:157], v[206:209], 0
	v_mfma_f32_16x16x32_bf16 v[124:127], v[150:153], v[182:185], v[124:127]
	v_mfma_f32_16x16x32_bf16 v[120:123], v[158:161], v[182:185], v[120:123]
	v_mfma_f32_16x16x32_bf16 v[116:119], v[150:153], v[190:193], v[116:119]
	v_mfma_f32_16x16x32_bf16 v[108:111], v[158:161], v[190:193], v[108:111]
	v_mfma_f32_16x16x32_bf16 v[100:103], v[150:153], v[198:201], v[100:103]
	v_mfma_f32_16x16x32_bf16 v[92:95], v[158:161], v[198:201], v[92:95]
	v_mfma_f32_16x16x32_bf16 v[84:87], v[150:153], v[218:221], v[84:87]
	v_mfma_f32_16x16x32_bf16 v[76:79], v[158:161], v[218:221], v[76:79]
	v_mfma_f32_16x16x32_bf16 v[112:115], v[162:165], v[178:181], 0
	v_mfma_f32_16x16x32_bf16 v[104:107], v[170:173], v[178:181], 0
	v_mfma_f32_16x16x32_bf16 v[96:99], v[162:165], v[186:189], 0
	v_mfma_f32_16x16x32_bf16 v[88:91], v[170:173], v[186:189], 0
	v_mfma_f32_16x16x32_bf16 v[80:83], v[162:165], v[194:197], 0
	v_mfma_f32_16x16x32_bf16 v[72:75], v[170:173], v[194:197], 0
	v_mfma_f32_16x16x32_bf16 v[68:71], v[162:165], v[206:209], 0
	v_mfma_f32_16x16x32_bf16 v[64:67], v[170:173], v[206:209], 0
	v_mfma_f32_16x16x32_bf16 v[112:115], v[166:169], v[182:185], v[112:115]
	v_mfma_f32_16x16x32_bf16 v[104:107], v[174:177], v[182:185], v[104:107]
	v_mfma_f32_16x16x32_bf16 v[96:99], v[166:169], v[190:193], v[96:99]
	v_mfma_f32_16x16x32_bf16 v[88:91], v[174:177], v[190:193], v[88:91]
	v_mfma_f32_16x16x32_bf16 v[80:83], v[166:169], v[198:201], v[80:83]
	v_mfma_f32_16x16x32_bf16 v[72:75], v[174:177], v[198:201], v[72:75]
	v_mfma_f32_16x16x32_bf16 v[68:71], v[166:169], v[218:221], v[68:71]
	v_mfma_f32_16x16x32_bf16 v[64:67], v[174:177], v[218:221], v[64:67]
	s_barrier
	s_add_i32 s78, s79, s22
	v_lshl_add_u64 v[202:203], s[44:45], 0, v[204:205]
	s_mov_b32 m0, s78
	ds_read_b128 v[178:181], v145 offset:16384
	ds_read_b128 v[182:185], v145 offset:17408
	ds_read_b128 v[186:189], v145 offset:18432
	ds_read_b128 v[190:193], v145 offset:19456
	ds_read_b128 v[194:197], v145 offset:20480
	ds_read_b128 v[198:201], v145 offset:21504
	ds_read_b128 v[206:209], v145 offset:22528
	ds_read_b128 v[218:221], v145 offset:23552
	global_load_lds_dwordx4 v[202:203], off
	s_add_i32 m0, s78, 0x2000
	s_add_u32 s78, s44, 0x80000
	v_lshl_add_u64 v[222:223], s[44:45], 0, v[128:129]
	s_addc_u32 s79, s45, 0
	s_add_i32 s53, s53, s22
	global_load_lds_dwordx4 v[222:223], off
	s_mov_b32 m0, s53
	v_lshl_add_u64 v[232:233], s[78:79], 0, v[204:205]
	global_load_lds_dwordx4 v[232:233], off
	s_add_i32 m0, s53, 0x2000
	v_lshl_add_u64 v[232:233], s[78:79], 0, v[128:129]
	global_load_lds_dwordx4 v[232:233], off
	s_waitcnt vmcnt(6)
	s_waitcnt lgkmcnt(0)
	s_barrier
	v_mfma_f32_16x16x32_bf16 v[60:63], v[146:149], v[178:181], 0
	v_mfma_f32_16x16x32_bf16 v[56:59], v[154:157], v[178:181], 0
	v_mfma_f32_16x16x32_bf16 v[52:55], v[146:149], v[186:189], 0
	v_mfma_f32_16x16x32_bf16 v[44:47], v[154:157], v[186:189], 0
	v_mfma_f32_16x16x32_bf16 v[36:39], v[146:149], v[194:197], 0
	v_mfma_f32_16x16x32_bf16 v[28:31], v[154:157], v[194:197], 0
	v_mfma_f32_16x16x32_bf16 v[20:23], v[146:149], v[206:209], 0
	v_mfma_f32_16x16x32_bf16 v[12:15], v[154:157], v[206:209], 0
	v_mfma_f32_16x16x32_bf16 v[60:63], v[150:153], v[182:185], v[60:63]
	v_mfma_f32_16x16x32_bf16 v[56:59], v[158:161], v[182:185], v[56:59]
	v_mfma_f32_16x16x32_bf16 v[52:55], v[150:153], v[190:193], v[52:55]
	v_mfma_f32_16x16x32_bf16 v[44:47], v[158:161], v[190:193], v[44:47]
	v_mfma_f32_16x16x32_bf16 v[36:39], v[150:153], v[198:201], v[36:39]
	v_mfma_f32_16x16x32_bf16 v[28:31], v[158:161], v[198:201], v[28:31]
	v_mfma_f32_16x16x32_bf16 v[20:23], v[150:153], v[218:221], v[20:23]
	v_mfma_f32_16x16x32_bf16 v[12:15], v[158:161], v[218:221], v[12:15]
	v_mfma_f32_16x16x32_bf16 v[48:51], v[162:165], v[178:181], 0
	v_mfma_f32_16x16x32_bf16 v[40:43], v[170:173], v[178:181], 0
	v_mfma_f32_16x16x32_bf16 v[32:35], v[162:165], v[186:189], 0
	v_mfma_f32_16x16x32_bf16 v[24:27], v[170:173], v[186:189], 0
	v_mfma_f32_16x16x32_bf16 v[16:19], v[162:165], v[194:197], 0
	v_mfma_f32_16x16x32_bf16 v[8:11], v[170:173], v[194:197], 0
	v_mfma_f32_16x16x32_bf16 v[4:7], v[162:165], v[206:209], 0
	v_mfma_f32_16x16x32_bf16 v[0:3], v[170:173], v[206:209], 0
	v_mfma_f32_16x16x32_bf16 v[48:51], v[166:169], v[182:185], v[48:51]
	v_mfma_f32_16x16x32_bf16 v[40:43], v[174:177], v[182:185], v[40:43]
	v_mfma_f32_16x16x32_bf16 v[32:35], v[166:169], v[190:193], v[32:35]
	v_mfma_f32_16x16x32_bf16 v[24:27], v[174:177], v[190:193], v[24:27]
	v_mfma_f32_16x16x32_bf16 v[16:19], v[166:169], v[198:201], v[16:19]
	v_mfma_f32_16x16x32_bf16 v[8:11], v[174:177], v[198:201], v[8:11]
	v_mfma_f32_16x16x32_bf16 v[4:7], v[166:169], v[218:221], v[4:7]
	v_mfma_f32_16x16x32_bf16 v[0:3], v[174:177], v[218:221], v[0:3]
	s_barrier
	s_branch .Lpl_o
; #define PG8_STAGE(bufoff, gbase, voff) do { _Pragma("unroll") for (int _i = 0; _i < 2; ++_i) \
;         __builtin_amdgcn_global_load_lds((const unsigned*)((const char*)(gbase) + (voff)[_i]), (PG8_LAS unsigned*)(lds + (bufoff) + ldsw + _i * 8192), 16, 0, 0); } while (0)
; #define PG8_LDA(dst, b, h) do { _Pragma("unroll") for (int m = 0; m < 4; ++m) _Pragma("unroll") for (int k = 0; k < 2; ++k) dst[m][k] = *(const PG8_LAS bf16x8*)(lds + PG8_SA(b, h) + aoff + m * 2048 + k * 1024); } while (0)
; #define PG8_LDB(dst, b, h) do { _Pragma("unroll") for (int n = 0; n < 2; ++n) _Pragma("unroll") for (int k = 0; k < 2; ++k) dst[n][k] = *(const PG8_LAS bf16x8*)(lds + PG8_SB(b, h) + boff + n * 2048 + k * 1024); } while (0)
; #define PG8_MMA(ai, bj, At, Bt) do { __builtin_amdgcn_s_setprio(1); _Pragma("unroll") for (int m = 0; m < 4; ++m) _Pragma("unroll") for (int n = 0; n < 2; ++n) _Pragma("unroll") for (int k = 0; k < 2; ++k) \
;         acc[ai][bj][m][n] = __builtin_amdgcn_mfma_f32_16x16x32_bf16(Bt[n][k], At[m][k], acc[ai][bj][m][n], 0, 0, 0); __builtin_amdgcn_s_setprio(0); } while (0)
; #define PG8_WAIT_V(n) asm volatile("s_waitcnt vmcnt(" #n ")" ::: "memory")
; #define PG8_WAIT_L(n) asm volatile("s_waitcnt lgkmcnt(" #n ")" ::: "memory")
; template <class Epi, class Sched, bool ALIGN_EPI = false, bool SP2 = false>
; __device__ __forceinline__ void gemm_phase(PG8_LAS unsigned char* lds, const Gemm g, const Sched& S, const Epi& E) {
;     ...
;             const bool last = (t == nt - 2);
;             const char* a1 = cA + (size_t)(t + 1) * kstep;
;             const char* a2 = last ? nA : cA + (size_t)(t + 2) * kstep; const char* b2 = last ? nB : cB + (size_t)(t + 2) * kstep;
;             const char* a3 = a2 + kstep; const char* b3 = b2 + kstep;
;             if (last && has_next) S.a_ready(nxt);
;             if constexpr (SP2) {
;             PG8_LDB(B0, 0, 0); PG8_LDB(B1, 0, 1); PG8_SCHED; PG8_LDA(At, 0, 0); PG8_STAGE(PG8_SA(1, 0), a1, voffA); PG8_STAGE(PG8_SA(1, 1), a1 + hstep, voffA);
;             PG8_WAIT_V(8); PG8_WAIT_L(0); PG8_BAR; PG8_MMA(0, 0, At, B0); PG8_MMA(0, 1, At, B1); PG8_BAR; PG8_SCHED;
;             PG8_LDA(At, 0, 1); PG8_STAGE(PG8_SB(0, 0), b2, voffB); PG8_STAGE(PG8_SB(0, 1), b2 + hstep, voffB);
;             PG8_WAIT_V(6); PG8_WAIT_L(0); PG8_BAR; PG8_MMA(1, 0, At, B0); PG8_MMA(1, 1, At, B1); PG8_BAR; PG8_SCHED;
.LBB0_426:
	s_add_u32 s44, s16, s88
	s_addc_u32 s45, s17, s89
	s_add_u32 s53, s44, 0x100
	s_addc_u32 s78, s45, 0
	s_add_u32 s44, s70, s88
	s_addc_u32 s45, s71, s89
	s_add_i32 s79, 0, 0x10000
	s_cmpk_eq_i32 s88, 0xf00
	s_cselect_b32 s45, s43, s45
	s_cselect_b32 s44, s69, s44
	s_cselect_b32 s95, s47, s78
	s_cselect_b32 s94, s68, s53
	s_add_i32 s53, 0, 0x14000
	v_add_u32_e32 v158, s79, v143
	v_add_u32_e32 v174, s53, v143
	ds_read_b128 v[146:149], v158
	ds_read_b128 v[150:153], v158 offset:1024
	ds_read_b128 v[154:157], v158 offset:2048
	ds_read_b128 v[158:161], v158 offset:3072
	ds_read_b128 v[162:165], v174
	ds_read_b128 v[166:169], v174 offset:1024
	ds_read_b128 v[170:173], v174 offset:2048
	ds_read_b128 v[174:177], v174 offset:3072
	v_lshl_add_u64 v[202:203], v[138:139], 0, s[88:89]
	v_lshl_add_u64 v[222:223], v[202:203], 0, s[26:27]
	s_add_i32 m0, s23, 0x8000
	ds_read_b128 v[178:181], v145
	ds_read_b128 v[182:185], v145 offset:1024
	ds_read_b128 v[186:189], v145 offset:2048
	ds_read_b128 v[190:193], v145 offset:3072
	ds_read_b128 v[194:197], v145 offset:4096
	ds_read_b128 v[198:201], v145 offset:5120
	ds_read_b128 v[206:209], v145 offset:6144
	ds_read_b128 v[218:221], v145 offset:7168
	global_load_lds_dwordx4 v[222:223], off
	v_lshl_add_u64 v[222:223], v[140:141], 0, s[88:89]
	v_lshl_add_u64 v[232:233], v[222:223], 0, s[26:27]
	s_add_i32 m0, s23, 0xa000
	v_lshl_add_u64 v[202:203], v[202:203], 0, s[28:29]
	global_load_lds_dwordx4 v[232:233], off
	s_add_i32 m0, s23, 0xc000
	s_nop 0
	global_load_lds_dwordx4 v[202:203], off
	s_add_i32 m0, s23, 0xe000
	v_lshl_add_u64 v[202:203], v[222:223], 0, s[28:29]
	global_load_lds_dwordx4 v[202:203], off
	s_waitcnt vmcnt(8)
	s_waitcnt lgkmcnt(0)
	s_barrier
	v_mfma_f32_16x16x32_bf16 v[124:127], v[146:149], v[178:181], v[124:127]
	v_mfma_f32_16x16x32_bf16 v[120:123], v[154:157], v[178:181], v[120:123]
	v_mfma_f32_16x16x32_bf16 v[116:119], v[146:149], v[186:189], v[116:119]
	v_mfma_f32_16x16x32_bf16 v[108:111], v[154:157], v[186:189], v[108:111]
	v_mfma_f32_16x16x32_bf16 v[100:103], v[146:149], v[194:197], v[100:103]
	v_mfma_f32_16x16x32_bf16 v[92:95], v[154:157], v[194:197], v[92:95]
	v_mfma_f32_16x16x32_bf16 v[84:87], v[146:149], v[206:209], v[84:87]
	v_mfma_f32_16x16x32_bf16 v[76:79], v[154:157], v[206:209], v[76:79]
	v_mfma_f32_16x16x32_bf16 v[124:127], v[150:153], v[182:185], v[124:127]
	v_mfma_f32_16x16x32_bf16 v[120:123], v[158:161], v[182:185], v[120:123]
	v_mfma_f32_16x16x32_bf16 v[116:119], v[150:153], v[190:193], v[116:119]
	v_mfma_f32_16x16x32_bf16 v[108:111], v[158:161], v[190:193], v[108:111]
	v_mfma_f32_16x16x32_bf16 v[100:103], v[150:153], v[198:201], v[100:103]
	v_mfma_f32_16x16x32_bf16 v[92:95], v[158:161], v[198:201], v[92:95]
	v_mfma_f32_16x16x32_bf16 v[84:87], v[150:153], v[218:221], v[84:87]
	v_mfma_f32_16x16x32_bf16 v[76:79], v[158:161], v[218:221], v[76:79]
	v_mfma_f32_16x16x32_bf16 v[112:115], v[162:165], v[178:181], v[112:115]
	v_mfma_f32_16x16x32_bf16 v[104:107], v[170:173], v[178:181], v[104:107]
	v_mfma_f32_16x16x32_bf16 v[96:99], v[162:165], v[186:189], v[96:99]
	v_mfma_f32_16x16x32_bf16 v[88:91], v[170:173], v[186:189], v[88:91]
	v_mfma_f32_16x16x32_bf16 v[80:83], v[162:165], v[194:197], v[80:83]
	v_mfma_f32_16x16x32_bf16 v[72:75], v[170:173], v[194:197], v[72:75]
	v_mfma_f32_16x16x32_bf16 v[68:71], v[162:165], v[206:209], v[68:71]
	v_mfma_f32_16x16x32_bf16 v[64:67], v[170:173], v[206:209], v[64:67]
	v_mfma_f32_16x16x32_bf16 v[112:115], v[166:169], v[182:185], v[112:115]
	v_mfma_f32_16x16x32_bf16 v[104:107], v[174:177], v[182:185], v[104:107]
	v_mfma_f32_16x16x32_bf16 v[96:99], v[166:169], v[190:193], v[96:99]
	v_mfma_f32_16x16x32_bf16 v[88:91], v[174:177], v[190:193], v[88:91]
	v_mfma_f32_16x16x32_bf16 v[80:83], v[166:169], v[198:201], v[80:83]
	v_mfma_f32_16x16x32_bf16 v[72:75], v[174:177], v[198:201], v[72:75]
	v_mfma_f32_16x16x32_bf16 v[68:71], v[166:169], v[218:221], v[68:71]
	v_mfma_f32_16x16x32_bf16 v[64:67], v[174:177], v[218:221], v[64:67]
	s_barrier
	s_add_i32 s78, s79, s22
	v_lshl_add_u64 v[202:203], s[44:45], 0, v[204:205]
	s_mov_b32 m0, s78
	ds_read_b128 v[178:181], v145 offset:16384
	ds_read_b128 v[182:185], v145 offset:17408
	ds_read_b128 v[186:189], v145 offset:18432
	ds_read_b128 v[190:193], v145 offset:19456
	ds_read_b128 v[194:197], v145 offset:20480
	ds_read_b128 v[198:201], v145 offset:21504
	ds_read_b128 v[206:209], v145 offset:22528
	ds_read_b128 v[218:221], v145 offset:23552
	global_load_lds_dwordx4 v[202:203], off
	s_add_i32 m0, s78, 0x2000
	s_add_u32 s78, s44, 0x80000
	v_lshl_add_u64 v[222:223], s[44:45], 0, v[128:129]
	s_addc_u32 s79, s45, 0
	s_add_i32 s53, s53, s22
	global_load_lds_dwordx4 v[222:223], off
	s_mov_b32 m0, s53
	v_lshl_add_u64 v[232:233], s[78:79], 0, v[204:205]
	global_load_lds_dwordx4 v[232:233], off
	s_add_i32 m0, s53, 0x2000
	v_lshl_add_u64 v[232:233], s[78:79], 0, v[128:129]
	global_load_lds_dwordx4 v[232:233], off
	s_waitcnt vmcnt(6)
	s_waitcnt lgkmcnt(0)
	s_barrier
; #define PG8_MMA(ai, bj, At, Bt) do { __builtin_amdgcn_s_setprio(1); _Pragma("unroll") for (int m = 0; m < 4; ++m) _Pragma("unroll") for (int n = 0; n < 2; ++n) _Pragma("unroll") for (int k = 0; k < 2; ++k) \
;         acc[ai][bj][m][n] = __builtin_amdgcn_mfma_f32_16x16x32_bf16(Bt[n][k], At[m][k], acc[ai][bj][m][n], 0, 0, 0); __builtin_amdgcn_s_setprio(0); } while (0)
; #define PG8_WAIT_V(n) asm volatile("s_waitcnt vmcnt(" #n ")" ::: "memory")
; #define PG8_WAIT_L(n) asm volatile("s_waitcnt lgkmcnt(" #n ")" ::: "memory")
; #define PG8_BAR __builtin_amdgcn_s_barrier()
; #define PG8_SCHED __builtin_amdgcn_sched_barrier(0)
; template <class Epi, class Sched, bool ALIGN_EPI = false, bool SP2 = false>
; __device__ __forceinline__ void gemm_phase(PG8_LAS unsigned char* lds, const Gemm g, const Sched& S, const Epi& E) {
;     ...
;             PG8_WAIT_V(6); PG8_WAIT_L(0); PG8_BAR; PG8_MMA(1, 0, At, B0); PG8_MMA(1, 1, At, B1); PG8_BAR; PG8_SCHED;
	v_mfma_f32_16x16x32_bf16 v[60:63], v[146:149], v[178:181], v[60:63]
	v_mfma_f32_16x16x32_bf16 v[56:59], v[154:157], v[178:181], v[56:59]
	v_mfma_f32_16x16x32_bf16 v[52:55], v[146:149], v[186:189], v[52:55]
	v_mfma_f32_16x16x32_bf16 v[44:47], v[154:157], v[186:189], v[44:47]
	v_mfma_f32_16x16x32_bf16 v[36:39], v[146:149], v[194:197], v[36:39]
	v_mfma_f32_16x16x32_bf16 v[28:31], v[154:157], v[194:197], v[28:31]
	v_mfma_f32_16x16x32_bf16 v[20:23], v[146:149], v[206:209], v[20:23]
	v_mfma_f32_16x16x32_bf16 v[12:15], v[154:157], v[206:209], v[12:15]
	v_mfma_f32_16x16x32_bf16 v[60:63], v[150:153], v[182:185], v[60:63]
	v_mfma_f32_16x16x32_bf16 v[56:59], v[158:161], v[182:185], v[56:59]
	v_mfma_f32_16x16x32_bf16 v[52:55], v[150:153], v[190:193], v[52:55]
	v_mfma_f32_16x16x32_bf16 v[44:47], v[158:161], v[190:193], v[44:47]
	v_mfma_f32_16x16x32_bf16 v[36:39], v[150:153], v[198:201], v[36:39]
	v_mfma_f32_16x16x32_bf16 v[28:31], v[158:161], v[198:201], v[28:31]
	v_mfma_f32_16x16x32_bf16 v[20:23], v[150:153], v[218:221], v[20:23]
	v_mfma_f32_16x16x32_bf16 v[12:15], v[158:161], v[218:221], v[12:15]
	v_mfma_f32_16x16x32_bf16 v[48:51], v[162:165], v[178:181], v[48:51]
	v_mfma_f32_16x16x32_bf16 v[40:43], v[170:173], v[178:181], v[40:43]
	v_mfma_f32_16x16x32_bf16 v[32:35], v[162:165], v[186:189], v[32:35]
	v_mfma_f32_16x16x32_bf16 v[24:27], v[170:173], v[186:189], v[24:27]
	v_mfma_f32_16x16x32_bf16 v[16:19], v[162:165], v[194:197], v[16:19]
	v_mfma_f32_16x16x32_bf16 v[8:11], v[170:173], v[194:197], v[8:11]
	v_mfma_f32_16x16x32_bf16 v[4:7], v[162:165], v[206:209], v[4:7]
	v_mfma_f32_16x16x32_bf16 v[0:3], v[170:173], v[206:209], v[0:3]
	v_mfma_f32_16x16x32_bf16 v[48:51], v[166:169], v[182:185], v[48:51]
	v_mfma_f32_16x16x32_bf16 v[40:43], v[174:177], v[182:185], v[40:43]
	v_mfma_f32_16x16x32_bf16 v[32:35], v[166:169], v[190:193], v[32:35]
	v_mfma_f32_16x16x32_bf16 v[24:27], v[174:177], v[190:193], v[24:27]
	v_mfma_f32_16x16x32_bf16 v[16:19], v[166:169], v[198:201], v[16:19]
	v_mfma_f32_16x16x32_bf16 v[8:11], v[174:177], v[198:201], v[8:11]
	v_mfma_f32_16x16x32_bf16 v[4:7], v[166:169], v[218:221], v[4:7]
	v_mfma_f32_16x16x32_bf16 v[0:3], v[174:177], v[218:221], v[0:3]
	s_barrier
; #define PG8_STAGE(bufoff, gbase, voff) do { _Pragma("unroll") for (int _i = 0; _i < 2; ++_i) \
;         __builtin_amdgcn_global_load_lds((const unsigned*)((const char*)(gbase) + (voff)[_i]), (PG8_LAS unsigned*)(lds + (bufoff) + ldsw + _i * 8192), 16, 0, 0); } while (0)
; #define PG8_LDA(dst, b, h) do { _Pragma("unroll") for (int m = 0; m < 4; ++m) _Pragma("unroll") for (int k = 0; k < 2; ++k) dst[m][k] = *(const PG8_LAS bf16x8*)(lds + PG8_SA(b, h) + aoff + m * 2048 + k * 1024); } while (0)
; #define PG8_LDB(dst, b, h) do { _Pragma("unroll") for (int n = 0; n < 2; ++n) _Pragma("unroll") for (int k = 0; k < 2; ++k) dst[n][k] = *(const PG8_LAS bf16x8*)(lds + PG8_SB(b, h) + boff + n * 2048 + k * 1024); } while (0)
; #define PG8_MMA(ai, bj, At, Bt) do { __builtin_amdgcn_s_setprio(1); _Pragma("unroll") for (int m = 0; m < 4; ++m) _Pragma("unroll") for (int n = 0; n < 2; ++n) _Pragma("unroll") for (int k = 0; k < 2; ++k) \
;         acc[ai][bj][m][n] = __builtin_amdgcn_mfma_f32_16x16x32_bf16(Bt[n][k], At[m][k], acc[ai][bj][m][n], 0, 0, 0); __builtin_amdgcn_s_setprio(0); } while (0)
; #define PG8_WAIT_V(n) asm volatile("s_waitcnt vmcnt(" #n ")" ::: "memory")
; #define PG8_WAIT_L(n) asm volatile("s_waitcnt lgkmcnt(" #n ")" ::: "memory")
; #define PG8_BAR __builtin_amdgcn_s_barrier()
; #define PG8_SCHED __builtin_amdgcn_sched_barrier(0)
; template <class Epi, class Sched, bool ALIGN_EPI = false, bool SP2 = false>
; __device__ __forceinline__ void gemm_phase(PG8_LAS unsigned char* lds, const Gemm g, const Sched& S, const Epi& E) {
;     ...
;             PG8_LDB(B0, 1, 0); PG8_LDB(B1, 1, 1); PG8_SCHED; PG8_LDA(At, 1, 0); PG8_STAGE(PG8_SA(0, 0), a2, voffA); PG8_STAGE(PG8_SA(0, 1), a2 + hstep, voffA);
;             PG8_WAIT_V(8); PG8_WAIT_L(0); PG8_BAR; PG8_MMA(0, 0, At, B0); PG8_MMA(0, 1, At, B1); PG8_BAR; PG8_SCHED;
;             PG8_LDA(At, 1, 1); PG8_STAGE(PG8_SB(1, 0), b3, voffB); PG8_STAGE(PG8_SB(1, 1), b3 + hstep, voffB); (void)a3;
;             PG8_WAIT_V(6); PG8_WAIT_L(0); PG8_BAR; PG8_MMA(1, 0, At, B0); PG8_MMA(1, 1, At, B1); PG8_BAR; PG8_SCHED;
.Lpl_o:
	s_add_i32 s53, 0, 0x18000
	s_add_i32 s84, 0, 0x1c000
	v_add_u32_e32 v158, s53, v143
	v_add_u32_e32 v174, s84, v143
	ds_read_b128 v[146:149], v158
	ds_read_b128 v[150:153], v158 offset:1024
	ds_read_b128 v[154:157], v158 offset:2048
	ds_read_b128 v[158:161], v158 offset:3072
	ds_read_b128 v[162:165], v174
	ds_read_b128 v[166:169], v174 offset:1024
	ds_read_b128 v[170:173], v174 offset:2048
	ds_read_b128 v[174:177], v174 offset:3072
	s_mov_b32 m0, s23
	v_lshl_add_u64 v[232:233], s[94:95], 0, v[132:133]
	s_add_u32 s78, s94, 0x80000
	ds_read_b128 v[178:181], v145 offset:32768
	ds_read_b128 v[182:185], v145 offset:33792
	ds_read_b128 v[186:189], v145 offset:34816
	ds_read_b128 v[190:193], v145 offset:35840
	ds_read_b128 v[194:197], v145 offset:36864
	ds_read_b128 v[198:201], v145 offset:37888
	ds_read_b128 v[206:209], v145 offset:38912
	ds_read_b128 v[218:221], v145 offset:39936
	global_load_lds_dwordx4 v[232:233], off
	v_lshl_add_u64 v[232:233], s[94:95], 0, v[130:131]
	s_mov_b32 m0, s34
	s_addc_u32 s79, s95, 0
	global_load_lds_dwordx4 v[232:233], off
	s_mov_b32 m0, s35
	v_lshl_add_u64 v[232:233], s[78:79], 0, v[132:133]
	global_load_lds_dwordx4 v[232:233], off
	s_mov_b32 m0, s36
	v_lshl_add_u64 v[232:233], s[78:79], 0, v[130:131]
	global_load_lds_dwordx4 v[232:233], off
	s_waitcnt vmcnt(8)
	s_waitcnt lgkmcnt(0)
	s_barrier
	v_mfma_f32_16x16x32_bf16 v[124:127], v[146:149], v[178:181], v[124:127]
	v_mfma_f32_16x16x32_bf16 v[120:123], v[154:157], v[178:181], v[120:123]
	v_mfma_f32_16x16x32_bf16 v[116:119], v[146:149], v[186:189], v[116:119]
	v_mfma_f32_16x16x32_bf16 v[108:111], v[154:157], v[186:189], v[108:111]
	v_mfma_f32_16x16x32_bf16 v[100:103], v[146:149], v[194:197], v[100:103]
	v_mfma_f32_16x16x32_bf16 v[92:95], v[154:157], v[194:197], v[92:95]
	v_mfma_f32_16x16x32_bf16 v[84:87], v[146:149], v[206:209], v[84:87]
	v_mfma_f32_16x16x32_bf16 v[76:79], v[154:157], v[206:209], v[76:79]
	v_mfma_f32_16x16x32_bf16 v[124:127], v[150:153], v[182:185], v[124:127]
	v_mfma_f32_16x16x32_bf16 v[120:123], v[158:161], v[182:185], v[120:123]
	v_mfma_f32_16x16x32_bf16 v[116:119], v[150:153], v[190:193], v[116:119]
	v_mfma_f32_16x16x32_bf16 v[108:111], v[158:161], v[190:193], v[108:111]
	v_mfma_f32_16x16x32_bf16 v[100:103], v[150:153], v[198:201], v[100:103]
	v_mfma_f32_16x16x32_bf16 v[92:95], v[158:161], v[198:201], v[92:95]
	v_mfma_f32_16x16x32_bf16 v[84:87], v[150:153], v[218:221], v[84:87]
	v_mfma_f32_16x16x32_bf16 v[76:79], v[158:161], v[218:221], v[76:79]
	v_mfma_f32_16x16x32_bf16 v[112:115], v[162:165], v[178:181], v[112:115]
	v_mfma_f32_16x16x32_bf16 v[104:107], v[170:173], v[178:181], v[104:107]
	v_mfma_f32_16x16x32_bf16 v[96:99], v[162:165], v[186:189], v[96:99]
	v_mfma_f32_16x16x32_bf16 v[88:91], v[170:173], v[186:189], v[88:91]
	v_mfma_f32_16x16x32_bf16 v[80:83], v[162:165], v[194:197], v[80:83]
	v_mfma_f32_16x16x32_bf16 v[72:75], v[170:173], v[194:197], v[72:75]
	v_mfma_f32_16x16x32_bf16 v[68:71], v[162:165], v[206:209], v[68:71]
	v_mfma_f32_16x16x32_bf16 v[64:67], v[170:173], v[206:209], v[64:67]
	v_mfma_f32_16x16x32_bf16 v[112:115], v[166:169], v[182:185], v[112:115]
	v_mfma_f32_16x16x32_bf16 v[104:107], v[174:177], v[182:185], v[104:107]
	v_mfma_f32_16x16x32_bf16 v[96:99], v[166:169], v[190:193], v[96:99]
	v_mfma_f32_16x16x32_bf16 v[88:91], v[174:177], v[190:193], v[88:91]
	v_mfma_f32_16x16x32_bf16 v[80:83], v[166:169], v[198:201], v[80:83]
	v_mfma_f32_16x16x32_bf16 v[72:75], v[174:177], v[198:201], v[72:75]
	v_mfma_f32_16x16x32_bf16 v[68:71], v[166:169], v[218:221], v[68:71]
	v_mfma_f32_16x16x32_bf16 v[64:67], v[174:177], v[218:221], v[64:67]
	s_barrier
	s_add_i32 s53, s53, s22
	v_lshl_add_u64 v[202:203], v[202:203], 0, s[26:27]
	s_mov_b32 m0, s53
	ds_read_b128 v[178:181], v145 offset:49152
	ds_read_b128 v[182:185], v145 offset:50176
	ds_read_b128 v[186:189], v145 offset:51200
	ds_read_b128 v[190:193], v145 offset:52224
	ds_read_b128 v[194:197], v145 offset:53248
	ds_read_b128 v[198:201], v145 offset:54272
	ds_read_b128 v[206:209], v145 offset:55296
	ds_read_b128 v[218:221], v145 offset:56320
	global_load_lds_dwordx4 v[202:203], off
	s_add_i32 m0, s53, 0x2000
	s_add_u32 s44, s44, 0x80080
	v_lshl_add_u64 v[202:203], v[222:223], 0, s[26:27]
	s_addc_u32 s45, s45, 0
	s_add_i32 s53, s84, s22
	global_load_lds_dwordx4 v[202:203], off
	s_mov_b32 m0, s53
	v_lshl_add_u64 v[202:203], s[44:45], 0, v[204:205]
	global_load_lds_dwordx4 v[202:203], off
	s_add_i32 m0, s53, 0x2000
	v_lshl_add_u64 v[202:203], s[44:45], 0, v[128:129]
	global_load_lds_dwordx4 v[202:203], off
	s_waitcnt vmcnt(6)
	s_waitcnt lgkmcnt(0)
	s_barrier
	v_mfma_f32_16x16x32_bf16 v[60:63], v[146:149], v[178:181], v[60:63]
	v_mfma_f32_16x16x32_bf16 v[56:59], v[154:157], v[178:181], v[56:59]
	v_mfma_f32_16x16x32_bf16 v[52:55], v[146:149], v[186:189], v[52:55]
	v_mfma_f32_16x16x32_bf16 v[44:47], v[154:157], v[186:189], v[44:47]
	v_mfma_f32_16x16x32_bf16 v[36:39], v[146:149], v[194:197], v[36:39]
	v_mfma_f32_16x16x32_bf16 v[28:31], v[154:157], v[194:197], v[28:31]
	v_mfma_f32_16x16x32_bf16 v[20:23], v[146:149], v[206:209], v[20:23]
	v_mfma_f32_16x16x32_bf16 v[12:15], v[154:157], v[206:209], v[12:15]
	v_mfma_f32_16x16x32_bf16 v[60:63], v[150:153], v[182:185], v[60:63]
	v_mfma_f32_16x16x32_bf16 v[56:59], v[158:161], v[182:185], v[56:59]
	v_mfma_f32_16x16x32_bf16 v[52:55], v[150:153], v[190:193], v[52:55]
	v_mfma_f32_16x16x32_bf16 v[44:47], v[158:161], v[190:193], v[44:47]
	v_mfma_f32_16x16x32_bf16 v[36:39], v[150:153], v[198:201], v[36:39]
	v_mfma_f32_16x16x32_bf16 v[28:31], v[158:161], v[198:201], v[28:31]
	v_mfma_f32_16x16x32_bf16 v[20:23], v[150:153], v[218:221], v[20:23]
	v_mfma_f32_16x16x32_bf16 v[12:15], v[158:161], v[218:221], v[12:15]
	v_mfma_f32_16x16x32_bf16 v[48:51], v[162:165], v[178:181], v[48:51]
	v_mfma_f32_16x16x32_bf16 v[40:43], v[170:173], v[178:181], v[40:43]
	v_mfma_f32_16x16x32_bf16 v[32:35], v[162:165], v[186:189], v[32:35]
	v_mfma_f32_16x16x32_bf16 v[24:27], v[170:173], v[186:189], v[24:27]
	v_mfma_f32_16x16x32_bf16 v[16:19], v[162:165], v[194:197], v[16:19]
	v_mfma_f32_16x16x32_bf16 v[8:11], v[170:173], v[194:197], v[8:11]
	v_mfma_f32_16x16x32_bf16 v[4:7], v[162:165], v[206:209], v[4:7]
	v_mfma_f32_16x16x32_bf16 v[0:3], v[170:173], v[206:209], v[0:3]
	v_mfma_f32_16x16x32_bf16 v[48:51], v[166:169], v[182:185], v[48:51]
	v_mfma_f32_16x16x32_bf16 v[40:43], v[174:177], v[182:185], v[40:43]
	v_mfma_f32_16x16x32_bf16 v[32:35], v[166:169], v[190:193], v[32:35]
	v_mfma_f32_16x16x32_bf16 v[24:27], v[174:177], v[190:193], v[24:27]
	v_mfma_f32_16x16x32_bf16 v[16:19], v[166:169], v[198:201], v[16:19]
	v_mfma_f32_16x16x32_bf16 v[8:11], v[174:177], v[198:201], v[8:11]
	v_mfma_f32_16x16x32_bf16 v[4:7], v[166:169], v[218:221], v[4:7]
	v_mfma_f32_16x16x32_bf16 v[0:3], v[174:177], v[218:221], v[0:3]
	s_barrier
	s_add_i32 s52, s52, 2
	s_add_u32 s88, s88, 0x100
	s_addc_u32 s89, s89, 0
	s_cmp_gt_u32 s52, 29
	s_cbranch_scc0 .LBB0_426
	s_and_b64 vcc, exec, s[10:11]
	s_cbranch_vccz .LBB0_429
	s_barrier

; #define PG8_STAGE(bufoff, gbase, voff) do { _Pragma("unroll") for (int _i = 0; _i < 2; ++_i) \
;         __builtin_amdgcn_global_load_lds((const unsigned*)((const char*)(gbase) + (voff)[_i]), (PG8_LAS unsigned*)(lds + (bufoff) + ldsw + _i * 8192), 16, 0, 0); } while (0)
; #define PG8_LDA(dst, b, h) do { _Pragma("unroll") for (int m = 0; m < 4; ++m) _Pragma("unroll") for (int k = 0; k < 2; ++k) dst[m][k] = *(const PG8_LAS bf16x8*)(lds + PG8_SA(b, h) + aoff + m * 2048 + k * 1024); } while (0)
; #define PG8_WAIT_V(n) asm volatile("s_waitcnt vmcnt(" #n ")" ::: "memory")
; #define PG8_WAIT_L(n) asm volatile("s_waitcnt lgkmcnt(" #n ")" ::: "memory")
;     __device__ __forceinline__ void operator()(const f32x4 (&acc)[2][2][4][2], const Unit& u, int wr, int wc, int fr, int fq) const {
;     ...
;             for (int m = 0; m < 4; ++m) { bf16_t* rowp = O + (size_t)(row0 + ai * HALF + m * 16) * ldc + col0;
;                 float rsc = sc; if (rsmode == 1) { const float r_ = rs[row0 + ai * HALF + m * 16]; rsc = sc * (ACT == 2 ? r_ * r_ : r_); }
; template <class Epi, class Sched, bool ALIGN_EPI = false, bool SP2 = false>
; __device__ __forceinline__ void gemm_phase(PG8_LAS unsigned char* lds, const Gemm g, const Sched& S, const Epi& E) {
;     ...
;         const char* nA = has_next ? (const char*)g.A + (size_t)nxt.pm * tstep : cA; const char* nB = has_next ? (const char*)g.Bt + (size_t)nxt.pn * tstep : cB;
;         for (int t = 0; t < nt; t += 2) {
;             const bool last = (t == nt - 2);
;             const char* a1 = cA + (size_t)(t + 1) * kstep;
;             const char* a2 = last ? nA : cA + (size_t)(t + 2) * kstep; const char* b2 = last ? nB : cB + (size_t)(t + 2) * kstep;
;             const char* a3 = a2 + kstep; const char* b3 = b2 + kstep;
;             if (last && has_next) S.a_ready(nxt);
;             if constexpr (SP2) {
;             PG8_LDB(B0, 0, 0); PG8_LDB(B1, 0, 1); PG8_SCHED; PG8_LDA(At, 0, 0); PG8_STAGE(PG8_SA(1, 0), a1, voffA); PG8_STAGE(PG8_SA(1, 1), a1 + hstep, voffA);
;             PG8_WAIT_V(8); PG8_WAIT_L(0); PG8_BAR; PG8_MMA(0, 0, At, B0); PG8_MMA(0, 1, At, B1); PG8_BAR; PG8_SCHED;
;             PG8_LDA(At, 0, 1); PG8_STAGE(PG8_SB(0, 0), b2, voffB); PG8_STAGE(PG8_SB(0, 1), b2 + hstep, voffB);
;             PG8_WAIT_V(6); PG8_WAIT_L(0); PG8_BAR; PG8_MMA(1, 0, At, B0); PG8_MMA(1, 1, At, B1); PG8_BAR; PG8_SCHED;
.LBB0_604:
	s_ashr_i32 s95, s94, 31
	s_lshl_b64 s[16:17], s[94:95], 20
	s_add_u32 s16, s20, s16
	s_addc_u32 s17, s21, s17
	s_and_b64 s[44:45], s[42:43], exec
	s_cselect_b32 s95, s17, s9
	s_cselect_b32 s70, s16, s8
	s_ashr_i32 s7, s6, 31
	s_lshl_b64 s[44:45], s[6:7], 20
	s_add_u32 s44, s22, s44
	s_addc_u32 s45, s23, s45
	s_and_b64 s[52:53], s[42:43], exec
	s_cselect_b32 s7, s45, s11
	s_cselect_b32 s71, s44, s10
	s_add_u32 s79, s10, 0x100
	v_lshl_add_u64 v[138:139], s[8:9], 0, v[134:135]
	v_lshl_add_u64 v[140:141], s[8:9], 0, v[136:137]
	s_addc_u32 s52, s11, 0
	s_mov_b32 s53, -2
	s_mov_b64 vcc, 0
	v_lshl_add_u32 v240, s35, 8, v142
	v_ashrrev_i32_e32 v241, 31, v240
	v_lshl_add_u64 v[240:241], v[240:241], 2, s[88:89]
	global_load_dword v242, v[240:241], off
	global_load_dword v243, v[240:241], off offset:64
	global_load_dword v244, v[240:241], off offset:128
	global_load_dword v245, v[240:241], off offset:192
	global_load_dword v246, v[240:241], off offset:512
	global_load_dword v247, v[240:241], off offset:576
	global_load_dword v248, v[240:241], off offset:640
	global_load_dword v249, v[240:241], off offset:704
	s_add_u32 s10, s8, vcc_lo
	s_addc_u32 s11, s9, vcc_hi
	s_add_u32 s38, s10, 0x100
	s_addc_u32 s39, s11, 0
	s_add_u32 s10, s79, vcc_lo
	s_addc_u32 s11, s52, vcc_hi
	s_add_i32 s78, 0, 0x10000
	s_cmpk_eq_i32 vcc_lo, 0xf00
	s_cselect_b32 s11, s7, s11
	s_cselect_b32 s10, s71, s10
	s_cselect_b32 s69, s95, s39
	s_cselect_b32 s68, s70, s38
	s_add_i32 s92, 0, 0x14000
	v_add_u32_e32 v158, s78, v143
	ds_read_b128 v[146:149], v158
	ds_read_b128 v[150:153], v158 offset:1024
	ds_read_b128 v[154:157], v158 offset:2048
	ds_read_b128 v[158:161], v158 offset:3072
	v_lshl_add_u64 v[202:203], v[140:141], 0, vcc
	v_lshl_add_u64 v[222:223], v[202:203], 0, s[26:27]
	s_add_i32 m0, s37, 0x8000
	global_load_lds_dwordx4 v[222:223], off
	v_lshl_add_u64 v[222:223], v[138:139], 0, vcc
	v_lshl_add_u64 v[232:233], v[222:223], 0, s[26:27]
	s_add_i32 m0, s37, 0xa000
	v_lshl_add_u64 v[202:203], v[202:203], 0, s[28:29]
	global_load_lds_dwordx4 v[232:233], off
	s_add_i32 m0, s37, 0xc000
	s_nop 0
	global_load_lds_dwordx4 v[202:203], off
	s_add_i32 m0, s37, 0xe000
	v_lshl_add_u64 v[202:203], v[222:223], 0, s[28:29]
	global_load_lds_dwordx4 v[202:203], off
	s_waitcnt vmcnt(8)
	s_waitcnt lgkmcnt(0)
	s_barrier
	v_mfma_f32_16x16x32_bf16 v[124:127], v[146:149], v[178:181], 0
	v_mfma_f32_16x16x32_bf16 v[120:123], v[154:157], v[178:181], 0
	v_mfma_f32_16x16x32_bf16 v[108:111], v[146:149], v[186:189], 0
	v_mfma_f32_16x16x32_bf16 v[104:107], v[154:157], v[186:189], 0
	v_mfma_f32_16x16x32_bf16 v[92:95], v[146:149], v[194:197], 0
	v_mfma_f32_16x16x32_bf16 v[88:91], v[154:157], v[194:197], 0
	v_mfma_f32_16x16x32_bf16 v[76:79], v[146:149], v[206:209], 0
	v_mfma_f32_16x16x32_bf16 v[72:75], v[154:157], v[206:209], 0
	v_mfma_f32_16x16x32_bf16 v[124:127], v[150:153], v[182:185], v[124:127]
	v_mfma_f32_16x16x32_bf16 v[120:123], v[158:161], v[182:185], v[120:123]
	v_mfma_f32_16x16x32_bf16 v[108:111], v[150:153], v[190:193], v[108:111]
	v_mfma_f32_16x16x32_bf16 v[104:107], v[158:161], v[190:193], v[104:107]
	v_mfma_f32_16x16x32_bf16 v[92:95], v[150:153], v[198:201], v[92:95]
	v_mfma_f32_16x16x32_bf16 v[88:91], v[158:161], v[198:201], v[88:91]
	v_mfma_f32_16x16x32_bf16 v[76:79], v[150:153], v[218:221], v[76:79]
	v_mfma_f32_16x16x32_bf16 v[72:75], v[158:161], v[218:221], v[72:75]
	v_mfma_f32_16x16x32_bf16 v[116:119], v[162:165], v[178:181], 0
	v_mfma_f32_16x16x32_bf16 v[112:115], v[170:173], v[178:181], 0
	v_mfma_f32_16x16x32_bf16 v[100:103], v[162:165], v[186:189], 0
	v_mfma_f32_16x16x32_bf16 v[96:99], v[170:173], v[186:189], 0
	v_mfma_f32_16x16x32_bf16 v[84:87], v[162:165], v[194:197], 0
	v_mfma_f32_16x16x32_bf16 v[80:83], v[170:173], v[194:197], 0
	v_mfma_f32_16x16x32_bf16 v[68:71], v[162:165], v[206:209], 0
	v_mfma_f32_16x16x32_bf16 v[64:67], v[170:173], v[206:209], 0
	v_mfma_f32_16x16x32_bf16 v[116:119], v[166:169], v[182:185], v[116:119]
	v_mfma_f32_16x16x32_bf16 v[112:115], v[174:177], v[182:185], v[112:115]
	v_mfma_f32_16x16x32_bf16 v[100:103], v[166:169], v[190:193], v[100:103]
	v_mfma_f32_16x16x32_bf16 v[96:99], v[174:177], v[190:193], v[96:99]
	v_mfma_f32_16x16x32_bf16 v[84:87], v[166:169], v[198:201], v[84:87]
	v_mfma_f32_16x16x32_bf16 v[80:83], v[174:177], v[198:201], v[80:83]
	v_mfma_f32_16x16x32_bf16 v[68:71], v[166:169], v[218:221], v[68:71]
	v_mfma_f32_16x16x32_bf16 v[64:67], v[174:177], v[218:221], v[64:67]
	s_barrier
	s_add_i32 s38, s78, s36
	v_lshl_add_u64 v[202:203], s[10:11], 0, v[204:205]
	s_mov_b32 m0, s38
	ds_read_b128 v[178:181], v145 offset:16384
	ds_read_b128 v[182:185], v145 offset:17408
	ds_read_b128 v[186:189], v145 offset:18432
	ds_read_b128 v[190:193], v145 offset:19456
	ds_read_b128 v[194:197], v145 offset:20480
	ds_read_b128 v[198:201], v145 offset:21504
	ds_read_b128 v[206:209], v145 offset:22528
	ds_read_b128 v[218:221], v145 offset:23552
	global_load_lds_dwordx4 v[202:203], off
	s_add_i32 m0, s38, 0x2000
	s_add_u32 s38, s10, 0x80000
	v_lshl_add_u64 v[222:223], s[10:11], 0, v[128:129]
	s_addc_u32 s39, s11, 0
	s_add_i32 s78, s92, s36
	global_load_lds_dwordx4 v[222:223], off
	s_mov_b32 m0, s78
	v_lshl_add_u64 v[232:233], s[38:39], 0, v[204:205]
	global_load_lds_dwordx4 v[232:233], off
	s_add_i32 m0, s78, 0x2000
	v_lshl_add_u64 v[232:233], s[38:39], 0, v[128:129]
	global_load_lds_dwordx4 v[232:233], off
	s_waitcnt vmcnt(6)
	s_waitcnt lgkmcnt(0)
	s_barrier
; #define PG8_STAGE(bufoff, gbase, voff) do { _Pragma("unroll") for (int _i = 0; _i < 2; ++_i) \
;         __builtin_amdgcn_global_load_lds((const unsigned*)((const char*)(gbase) + (voff)[_i]), (PG8_LAS unsigned*)(lds + (bufoff) + ldsw + _i * 8192), 16, 0, 0); } while (0)
; #define PG8_LDA(dst, b, h) do { _Pragma("unroll") for (int m = 0; m < 4; ++m) _Pragma("unroll") for (int k = 0; k < 2; ++k) dst[m][k] = *(const PG8_LAS bf16x8*)(lds + PG8_SA(b, h) + aoff + m * 2048 + k * 1024); } while (0)
; #define PG8_LDB(dst, b, h) do { _Pragma("unroll") for (int n = 0; n < 2; ++n) _Pragma("unroll") for (int k = 0; k < 2; ++k) dst[n][k] = *(const PG8_LAS bf16x8*)(lds + PG8_SB(b, h) + boff + n * 2048 + k * 1024); } while (0)
; #define PG8_MMA(ai, bj, At, Bt) do { __builtin_amdgcn_s_setprio(1); _Pragma("unroll") for (int m = 0; m < 4; ++m) _Pragma("unroll") for (int n = 0; n < 2; ++n) _Pragma("unroll") for (int k = 0; k < 2; ++k) \
;         acc[ai][bj][m][n] = __builtin_amdgcn_mfma_f32_16x16x32_bf16(Bt[n][k], At[m][k], acc[ai][bj][m][n], 0, 0, 0); __builtin_amdgcn_s_setprio(0); } while (0)
; #define PG8_WAIT_V(n) asm volatile("s_waitcnt vmcnt(" #n ")" ::: "memory")
; #define PG8_WAIT_L(n) asm volatile("s_waitcnt lgkmcnt(" #n ")" ::: "memory")
; #define PG8_BAR __builtin_amdgcn_s_barrier()
; #define PG8_SCHED __builtin_amdgcn_sched_barrier(0)
; template <class Epi, class Sched, bool ALIGN_EPI = false, bool SP2 = false>
; __device__ __forceinline__ void gemm_phase(PG8_LAS unsigned char* lds, const Gemm g, const Sched& S, const Epi& E) {
;     ...
;             const char* a2 = last ? nA : cA + (size_t)(t + 2) * kstep; const char* b2 = last ? nB : cB + (size_t)(t + 2) * kstep;
;             const char* a3 = a2 + kstep; const char* b3 = b2 + kstep;
;             if (last && has_next) S.a_ready(nxt);
;             if constexpr (SP2) {
;             PG8_LDB(B0, 0, 0); PG8_LDB(B1, 0, 1); PG8_SCHED; PG8_LDA(At, 0, 0); PG8_STAGE(PG8_SA(1, 0), a1, voffA); PG8_STAGE(PG8_SA(1, 1), a1 + hstep, voffA);
;             PG8_WAIT_V(8); PG8_WAIT_L(0); PG8_BAR; PG8_MMA(0, 0, At, B0); PG8_MMA(0, 1, At, B1); PG8_BAR; PG8_SCHED;
;             PG8_LDA(At, 0, 1); PG8_STAGE(PG8_SB(0, 0), b2, voffB); PG8_STAGE(PG8_SB(0, 1), b2 + hstep, voffB);
;             PG8_WAIT_V(6); PG8_WAIT_L(0); PG8_BAR; PG8_MMA(1, 0, At, B0); PG8_MMA(1, 1, At, B1); PG8_BAR; PG8_SCHED;
	v_mfma_f32_16x16x32_bf16 v[60:63], v[146:149], v[178:181], 0
	v_mfma_f32_16x16x32_bf16 v[56:59], v[154:157], v[178:181], 0
	v_mfma_f32_16x16x32_bf16 v[44:47], v[146:149], v[186:189], 0
	v_mfma_f32_16x16x32_bf16 v[40:43], v[154:157], v[186:189], 0
	v_mfma_f32_16x16x32_bf16 v[28:31], v[146:149], v[194:197], 0
	v_mfma_f32_16x16x32_bf16 v[24:27], v[154:157], v[194:197], 0
	v_mfma_f32_16x16x32_bf16 v[12:15], v[146:149], v[206:209], 0
	v_mfma_f32_16x16x32_bf16 v[8:11], v[154:157], v[206:209], 0
	v_mfma_f32_16x16x32_bf16 v[60:63], v[150:153], v[182:185], v[60:63]
	v_mfma_f32_16x16x32_bf16 v[56:59], v[158:161], v[182:185], v[56:59]
	v_mfma_f32_16x16x32_bf16 v[44:47], v[150:153], v[190:193], v[44:47]
	v_mfma_f32_16x16x32_bf16 v[40:43], v[158:161], v[190:193], v[40:43]
	v_mfma_f32_16x16x32_bf16 v[28:31], v[150:153], v[198:201], v[28:31]
	v_mfma_f32_16x16x32_bf16 v[24:27], v[158:161], v[198:201], v[24:27]
	v_mfma_f32_16x16x32_bf16 v[12:15], v[150:153], v[218:221], v[12:15]
	v_mfma_f32_16x16x32_bf16 v[8:11], v[158:161], v[218:221], v[8:11]
	v_mfma_f32_16x16x32_bf16 v[52:55], v[162:165], v[178:181], 0
	v_mfma_f32_16x16x32_bf16 v[48:51], v[170:173], v[178:181], 0
	v_mfma_f32_16x16x32_bf16 v[36:39], v[162:165], v[186:189], 0
	v_mfma_f32_16x16x32_bf16 v[32:35], v[170:173], v[186:189], 0
	v_mfma_f32_16x16x32_bf16 v[20:23], v[162:165], v[194:197], 0
	v_mfma_f32_16x16x32_bf16 v[16:19], v[170:173], v[194:197], 0
	v_mfma_f32_16x16x32_bf16 v[4:7], v[162:165], v[206:209], 0
	v_mfma_f32_16x16x32_bf16 v[0:3], v[170:173], v[206:209], 0
	v_mfma_f32_16x16x32_bf16 v[52:55], v[166:169], v[182:185], v[52:55]
	v_mfma_f32_16x16x32_bf16 v[48:51], v[174:177], v[182:185], v[48:51]
	v_mfma_f32_16x16x32_bf16 v[36:39], v[166:169], v[190:193], v[36:39]
	v_mfma_f32_16x16x32_bf16 v[32:35], v[174:177], v[190:193], v[32:35]
	v_mfma_f32_16x16x32_bf16 v[20:23], v[166:169], v[198:201], v[20:23]
	v_mfma_f32_16x16x32_bf16 v[16:19], v[174:177], v[198:201], v[16:19]
	v_mfma_f32_16x16x32_bf16 v[4:7], v[166:169], v[218:221], v[4:7]
	v_mfma_f32_16x16x32_bf16 v[0:3], v[174:177], v[218:221], v[0:3]
	s_barrier
	s_branch .Lpl_up
.LBB0_605:
	s_add_u32 s10, s8, vcc_lo
	s_addc_u32 s11, s9, vcc_hi
	s_add_u32 s38, s10, 0x100
	s_addc_u32 s39, s11, 0
	s_add_u32 s10, s79, vcc_lo
	s_addc_u32 s11, s52, vcc_hi
	s_add_i32 s78, 0, 0x10000
	s_cmpk_eq_i32 vcc_lo, 0xf00
	s_cselect_b32 s11, s7, s11
	s_cselect_b32 s10, s71, s10
	s_cselect_b32 s69, s95, s39
	s_cselect_b32 s68, s70, s38
	s_add_i32 s92, 0, 0x14000
	v_add_u32_e32 v158, s78, v143
	v_add_u32_e32 v174, s92, v143
	ds_read_b128 v[146:149], v158
	ds_read_b128 v[150:153], v158 offset:1024
	ds_read_b128 v[154:157], v158 offset:2048
	ds_read_b128 v[158:161], v158 offset:3072
	ds_read_b128 v[162:165], v174
	ds_read_b128 v[166:169], v174 offset:1024
	ds_read_b128 v[170:173], v174 offset:2048
	ds_read_b128 v[174:177], v174 offset:3072
	v_lshl_add_u64 v[202:203], v[140:141], 0, vcc
	v_lshl_add_u64 v[222:223], v[202:203], 0, s[26:27]
	s_add_i32 m0, s37, 0x8000
	ds_read_b128 v[178:181], v145
	ds_read_b128 v[182:185], v145 offset:1024
	ds_read_b128 v[186:189], v145 offset:2048
	ds_read_b128 v[190:193], v145 offset:3072
	ds_read_b128 v[194:197], v145 offset:4096
	ds_read_b128 v[198:201], v145 offset:5120
	ds_read_b128 v[206:209], v145 offset:6144
	ds_read_b128 v[218:221], v145 offset:7168
	global_load_lds_dwordx4 v[222:223], off
	v_lshl_add_u64 v[222:223], v[138:139], 0, vcc
	v_lshl_add_u64 v[232:233], v[222:223], 0, s[26:27]
	s_add_i32 m0, s37, 0xa000
	v_lshl_add_u64 v[202:203], v[202:203], 0, s[28:29]
	global_load_lds_dwordx4 v[232:233], off
	s_add_i32 m0, s37, 0xc000
	s_nop 0
	global_load_lds_dwordx4 v[202:203], off
	s_add_i32 m0, s37, 0xe000
	v_lshl_add_u64 v[202:203], v[222:223], 0, s[28:29]
	global_load_lds_dwordx4 v[202:203], off
	s_waitcnt vmcnt(8)
	s_waitcnt lgkmcnt(0)
	s_barrier
	v_mfma_f32_16x16x32_bf16 v[124:127], v[146:149], v[178:181], v[124:127]
	v_mfma_f32_16x16x32_bf16 v[120:123], v[154:157], v[178:181], v[120:123]
	v_mfma_f32_16x16x32_bf16 v[108:111], v[146:149], v[186:189], v[108:111]
	v_mfma_f32_16x16x32_bf16 v[104:107], v[154:157], v[186:189], v[104:107]
	v_mfma_f32_16x16x32_bf16 v[92:95], v[146:149], v[194:197], v[92:95]
	v_mfma_f32_16x16x32_bf16 v[88:91], v[154:157], v[194:197], v[88:91]
	v_mfma_f32_16x16x32_bf16 v[76:79], v[146:149], v[206:209], v[76:79]
	v_mfma_f32_16x16x32_bf16 v[72:75], v[154:157], v[206:209], v[72:75]
	v_mfma_f32_16x16x32_bf16 v[124:127], v[150:153], v[182:185], v[124:127]
	v_mfma_f32_16x16x32_bf16 v[120:123], v[158:161], v[182:185], v[120:123]
	v_mfma_f32_16x16x32_bf16 v[108:111], v[150:153], v[190:193], v[108:111]
	v_mfma_f32_16x16x32_bf16 v[104:107], v[158:161], v[190:193], v[104:107]
	v_mfma_f32_16x16x32_bf16 v[92:95], v[150:153], v[198:201], v[92:95]
	v_mfma_f32_16x16x32_bf16 v[88:91], v[158:161], v[198:201], v[88:91]
	v_mfma_f32_16x16x32_bf16 v[76:79], v[150:153], v[218:221], v[76:79]
	v_mfma_f32_16x16x32_bf16 v[72:75], v[158:161], v[218:221], v[72:75]
	v_mfma_f32_16x16x32_bf16 v[116:119], v[162:165], v[178:181], v[116:119]
	v_mfma_f32_16x16x32_bf16 v[112:115], v[170:173], v[178:181], v[112:115]
	v_mfma_f32_16x16x32_bf16 v[100:103], v[162:165], v[186:189], v[100:103]
	v_mfma_f32_16x16x32_bf16 v[96:99], v[170:173], v[186:189], v[96:99]
	v_mfma_f32_16x16x32_bf16 v[84:87], v[162:165], v[194:197], v[84:87]
	v_mfma_f32_16x16x32_bf16 v[80:83], v[170:173], v[194:197], v[80:83]
	v_mfma_f32_16x16x32_bf16 v[68:71], v[162:165], v[206:209], v[68:71]
	v_mfma_f32_16x16x32_bf16 v[64:67], v[170:173], v[206:209], v[64:67]
	v_mfma_f32_16x16x32_bf16 v[116:119], v[166:169], v[182:185], v[116:119]
	v_mfma_f32_16x16x32_bf16 v[112:115], v[174:177], v[182:185], v[112:115]
	v_mfma_f32_16x16x32_bf16 v[100:103], v[166:169], v[190:193], v[100:103]
	v_mfma_f32_16x16x32_bf16 v[96:99], v[174:177], v[190:193], v[96:99]
	v_mfma_f32_16x16x32_bf16 v[84:87], v[166:169], v[198:201], v[84:87]
	v_mfma_f32_16x16x32_bf16 v[80:83], v[174:177], v[198:201], v[80:83]
	v_mfma_f32_16x16x32_bf16 v[68:71], v[166:169], v[218:221], v[68:71]
	v_mfma_f32_16x16x32_bf16 v[64:67], v[174:177], v[218:221], v[64:67]
	s_barrier
; #define PG8_STAGE(bufoff, gbase, voff) do { _Pragma("unroll") for (int _i = 0; _i < 2; ++_i) \
;         __builtin_amdgcn_global_load_lds((const unsigned*)((const char*)(gbase) + (voff)[_i]), (PG8_LAS unsigned*)(lds + (bufoff) + ldsw + _i * 8192), 16, 0, 0); } while (0)
; #define PG8_LDA(dst, b, h) do { _Pragma("unroll") for (int m = 0; m < 4; ++m) _Pragma("unroll") for (int k = 0; k < 2; ++k) dst[m][k] = *(const PG8_LAS bf16x8*)(lds + PG8_SA(b, h) + aoff + m * 2048 + k * 1024); } while (0)
; #define PG8_MMA(ai, bj, At, Bt) do { __builtin_amdgcn_s_setprio(1); _Pragma("unroll") for (int m = 0; m < 4; ++m) _Pragma("unroll") for (int n = 0; n < 2; ++n) _Pragma("unroll") for (int k = 0; k < 2; ++k) \
;         acc[ai][bj][m][n] = __builtin_amdgcn_mfma_f32_16x16x32_bf16(Bt[n][k], At[m][k], acc[ai][bj][m][n], 0, 0, 0); __builtin_amdgcn_s_setprio(0); } while (0)
; #define PG8_WAIT_V(n) asm volatile("s_waitcnt vmcnt(" #n ")" ::: "memory")
; #define PG8_WAIT_L(n) asm volatile("s_waitcnt lgkmcnt(" #n ")" ::: "memory")
; #define PG8_BAR __builtin_amdgcn_s_barrier()
; #define PG8_SCHED __builtin_amdgcn_sched_barrier(0)
; template <class Epi, class Sched, bool ALIGN_EPI = false, bool SP2 = false>
; __device__ __forceinline__ void gemm_phase(PG8_LAS unsigned char* lds, const Gemm g, const Sched& S, const Epi& E) {
;     ...
;             PG8_LDA(At, 0, 1); PG8_STAGE(PG8_SB(0, 0), b2, voffB); PG8_STAGE(PG8_SB(0, 1), b2 + hstep, voffB);
;             PG8_WAIT_V(6); PG8_WAIT_L(0); PG8_BAR; PG8_MMA(1, 0, At, B0); PG8_MMA(1, 1, At, B1); PG8_BAR; PG8_SCHED;
	s_add_i32 s38, s78, s36
	v_lshl_add_u64 v[202:203], s[10:11], 0, v[204:205]
	s_mov_b32 m0, s38
	ds_read_b128 v[178:181], v145 offset:16384
	ds_read_b128 v[182:185], v145 offset:17408
	ds_read_b128 v[186:189], v145 offset:18432
	ds_read_b128 v[190:193], v145 offset:19456
	ds_read_b128 v[194:197], v145 offset:20480
	ds_read_b128 v[198:201], v145 offset:21504
	ds_read_b128 v[206:209], v145 offset:22528
	ds_read_b128 v[218:221], v145 offset:23552
	global_load_lds_dwordx4 v[202:203], off
	s_add_i32 m0, s38, 0x2000
	s_add_u32 s38, s10, 0x80000
	v_lshl_add_u64 v[222:223], s[10:11], 0, v[128:129]
	s_addc_u32 s39, s11, 0
	s_add_i32 s78, s92, s36
	global_load_lds_dwordx4 v[222:223], off
	s_mov_b32 m0, s78
	v_lshl_add_u64 v[232:233], s[38:39], 0, v[204:205]
	global_load_lds_dwordx4 v[232:233], off
	s_add_i32 m0, s78, 0x2000
	v_lshl_add_u64 v[232:233], s[38:39], 0, v[128:129]
	global_load_lds_dwordx4 v[232:233], off
	s_waitcnt vmcnt(6)
	s_waitcnt lgkmcnt(0)
	s_barrier
	v_mfma_f32_16x16x32_bf16 v[60:63], v[146:149], v[178:181], v[60:63]
	v_mfma_f32_16x16x32_bf16 v[56:59], v[154:157], v[178:181], v[56:59]
	v_mfma_f32_16x16x32_bf16 v[44:47], v[146:149], v[186:189], v[44:47]
	v_mfma_f32_16x16x32_bf16 v[40:43], v[154:157], v[186:189], v[40:43]
	v_mfma_f32_16x16x32_bf16 v[28:31], v[146:149], v[194:197], v[28:31]
	v_mfma_f32_16x16x32_bf16 v[24:27], v[154:157], v[194:197], v[24:27]
	v_mfma_f32_16x16x32_bf16 v[12:15], v[146:149], v[206:209], v[12:15]
	v_mfma_f32_16x16x32_bf16 v[8:11], v[154:157], v[206:209], v[8:11]
	v_mfma_f32_16x16x32_bf16 v[60:63], v[150:153], v[182:185], v[60:63]
	v_mfma_f32_16x16x32_bf16 v[56:59], v[158:161], v[182:185], v[56:59]
	v_mfma_f32_16x16x32_bf16 v[44:47], v[150:153], v[190:193], v[44:47]
	v_mfma_f32_16x16x32_bf16 v[40:43], v[158:161], v[190:193], v[40:43]
	v_mfma_f32_16x16x32_bf16 v[28:31], v[150:153], v[198:201], v[28:31]
	v_mfma_f32_16x16x32_bf16 v[24:27], v[158:161], v[198:201], v[24:27]
	v_mfma_f32_16x16x32_bf16 v[12:15], v[150:153], v[218:221], v[12:15]
	v_mfma_f32_16x16x32_bf16 v[8:11], v[158:161], v[218:221], v[8:11]
	v_mfma_f32_16x16x32_bf16 v[52:55], v[162:165], v[178:181], v[52:55]
	v_mfma_f32_16x16x32_bf16 v[48:51], v[170:173], v[178:181], v[48:51]
	v_mfma_f32_16x16x32_bf16 v[36:39], v[162:165], v[186:189], v[36:39]
	v_mfma_f32_16x16x32_bf16 v[32:35], v[170:173], v[186:189], v[32:35]
	v_mfma_f32_16x16x32_bf16 v[20:23], v[162:165], v[194:197], v[20:23]
	v_mfma_f32_16x16x32_bf16 v[16:19], v[170:173], v[194:197], v[16:19]
	v_mfma_f32_16x16x32_bf16 v[4:7], v[162:165], v[206:209], v[4:7]
	v_mfma_f32_16x16x32_bf16 v[0:3], v[170:173], v[206:209], v[0:3]
	v_mfma_f32_16x16x32_bf16 v[52:55], v[166:169], v[182:185], v[52:55]
	v_mfma_f32_16x16x32_bf16 v[48:51], v[174:177], v[182:185], v[48:51]
	v_mfma_f32_16x16x32_bf16 v[36:39], v[166:169], v[190:193], v[36:39]
	v_mfma_f32_16x16x32_bf16 v[32:35], v[174:177], v[190:193], v[32:35]
	v_mfma_f32_16x16x32_bf16 v[20:23], v[166:169], v[198:201], v[20:23]
	v_mfma_f32_16x16x32_bf16 v[16:19], v[174:177], v[198:201], v[16:19]
	v_mfma_f32_16x16x32_bf16 v[4:7], v[166:169], v[218:221], v[4:7]
	v_mfma_f32_16x16x32_bf16 v[0:3], v[174:177], v[218:221], v[0:3]
	s_barrier
; #define PG8_STAGE(bufoff, gbase, voff) do { _Pragma("unroll") for (int _i = 0; _i < 2; ++_i) \
;         __builtin_amdgcn_global_load_lds((const unsigned*)((const char*)(gbase) + (voff)[_i]), (PG8_LAS unsigned*)(lds + (bufoff) + ldsw + _i * 8192), 16, 0, 0); } while (0)
; #define PG8_LDA(dst, b, h) do { _Pragma("unroll") for (int m = 0; m < 4; ++m) _Pragma("unroll") for (int k = 0; k < 2; ++k) dst[m][k] = *(const PG8_LAS bf16x8*)(lds + PG8_SA(b, h) + aoff + m * 2048 + k * 1024); } while (0)
; #define PG8_LDB(dst, b, h) do { _Pragma("unroll") for (int n = 0; n < 2; ++n) _Pragma("unroll") for (int k = 0; k < 2; ++k) dst[n][k] = *(const PG8_LAS bf16x8*)(lds + PG8_SB(b, h) + boff + n * 2048 + k * 1024); } while (0)
; #define PG8_MMA(ai, bj, At, Bt) do { __builtin_amdgcn_s_setprio(1); _Pragma("unroll") for (int m = 0; m < 4; ++m) _Pragma("unroll") for (int n = 0; n < 2; ++n) _Pragma("unroll") for (int k = 0; k < 2; ++k) \
;         acc[ai][bj][m][n] = __builtin_amdgcn_mfma_f32_16x16x32_bf16(Bt[n][k], At[m][k], acc[ai][bj][m][n], 0, 0, 0); __builtin_amdgcn_s_setprio(0); } while (0)
; #define PG8_WAIT_V(n) asm volatile("s_waitcnt vmcnt(" #n ")" ::: "memory")
; #define PG8_WAIT_L(n) asm volatile("s_waitcnt lgkmcnt(" #n ")" ::: "memory")
; #define PG8_BAR __builtin_amdgcn_s_barrier()
; #define PG8_SCHED __builtin_amdgcn_sched_barrier(0)
; template <class Epi, class Sched, bool ALIGN_EPI = false, bool SP2 = false>
; __device__ __forceinline__ void gemm_phase(PG8_LAS unsigned char* lds, const Gemm g, const Sched& S, const Epi& E) {
;     ...
;             PG8_LDB(B0, 1, 0); PG8_LDB(B1, 1, 1); PG8_SCHED; PG8_LDA(At, 1, 0); PG8_STAGE(PG8_SA(0, 0), a2, voffA); PG8_STAGE(PG8_SA(0, 1), a2 + hstep, voffA);
;             PG8_WAIT_V(8); PG8_WAIT_L(0); PG8_BAR; PG8_MMA(0, 0, At, B0); PG8_MMA(0, 1, At, B1); PG8_BAR; PG8_SCHED;
;             PG8_LDA(At, 1, 1); PG8_STAGE(PG8_SB(1, 0), b3, voffB); PG8_STAGE(PG8_SB(1, 1), b3 + hstep, voffB); (void)a3;
;             PG8_WAIT_V(6); PG8_WAIT_L(0); PG8_BAR; PG8_MMA(1, 0, At, B0); PG8_MMA(1, 1, At, B1); PG8_BAR; PG8_SCHED;
.Lpl_up:
	s_add_i32 s78, 0, 0x18000
	s_add_i32 s92, 0, 0x1c000
	v_add_u32_e32 v158, s78, v143
	v_add_u32_e32 v174, s92, v143
	ds_read_b128 v[146:149], v158
	ds_read_b128 v[150:153], v158 offset:1024
	ds_read_b128 v[154:157], v158 offset:2048
	ds_read_b128 v[158:161], v158 offset:3072
	ds_read_b128 v[162:165], v174
	ds_read_b128 v[166:169], v174 offset:1024
	ds_read_b128 v[170:173], v174 offset:2048
	ds_read_b128 v[174:177], v174 offset:3072
	s_mov_b32 m0, s37
	v_lshl_add_u64 v[232:233], s[68:69], 0, v[132:133]
	s_add_u32 s38, s68, 0x80000
	ds_read_b128 v[178:181], v145 offset:32768
	ds_read_b128 v[182:185], v145 offset:33792
	ds_read_b128 v[186:189], v145 offset:34816
	ds_read_b128 v[190:193], v145 offset:35840
	ds_read_b128 v[194:197], v145 offset:36864
	ds_read_b128 v[198:201], v145 offset:37888
	ds_read_b128 v[206:209], v145 offset:38912
	ds_read_b128 v[218:221], v145 offset:39936
	global_load_lds_dwordx4 v[232:233], off
	v_lshl_add_u64 v[232:233], s[68:69], 0, v[130:131]
	s_mov_b32 m0, s57
	s_addc_u32 s39, s69, 0
	global_load_lds_dwordx4 v[232:233], off
	s_mov_b32 m0, s75
	v_lshl_add_u64 v[232:233], s[38:39], 0, v[132:133]
	global_load_lds_dwordx4 v[232:233], off
	s_mov_b32 m0, s84
	v_lshl_add_u64 v[232:233], s[38:39], 0, v[130:131]
	global_load_lds_dwordx4 v[232:233], off
	s_waitcnt vmcnt(8)
	s_waitcnt lgkmcnt(0)
	s_barrier
	v_mfma_f32_16x16x32_bf16 v[124:127], v[146:149], v[178:181], v[124:127]
	v_mfma_f32_16x16x32_bf16 v[120:123], v[154:157], v[178:181], v[120:123]
	v_mfma_f32_16x16x32_bf16 v[108:111], v[146:149], v[186:189], v[108:111]
	v_mfma_f32_16x16x32_bf16 v[104:107], v[154:157], v[186:189], v[104:107]
	v_mfma_f32_16x16x32_bf16 v[92:95], v[146:149], v[194:197], v[92:95]
	v_mfma_f32_16x16x32_bf16 v[88:91], v[154:157], v[194:197], v[88:91]
	v_mfma_f32_16x16x32_bf16 v[76:79], v[146:149], v[206:209], v[76:79]
	v_mfma_f32_16x16x32_bf16 v[72:75], v[154:157], v[206:209], v[72:75]
	v_mfma_f32_16x16x32_bf16 v[124:127], v[150:153], v[182:185], v[124:127]
	v_mfma_f32_16x16x32_bf16 v[120:123], v[158:161], v[182:185], v[120:123]
	v_mfma_f32_16x16x32_bf16 v[108:111], v[150:153], v[190:193], v[108:111]
	v_mfma_f32_16x16x32_bf16 v[104:107], v[158:161], v[190:193], v[104:107]
	v_mfma_f32_16x16x32_bf16 v[92:95], v[150:153], v[198:201], v[92:95]
	v_mfma_f32_16x16x32_bf16 v[88:91], v[158:161], v[198:201], v[88:91]
	v_mfma_f32_16x16x32_bf16 v[76:79], v[150:153], v[218:221], v[76:79]
	v_mfma_f32_16x16x32_bf16 v[72:75], v[158:161], v[218:221], v[72:75]
	v_mfma_f32_16x16x32_bf16 v[116:119], v[162:165], v[178:181], v[116:119]
	v_mfma_f32_16x16x32_bf16 v[112:115], v[170:173], v[178:181], v[112:115]
	v_mfma_f32_16x16x32_bf16 v[100:103], v[162:165], v[186:189], v[100:103]
	v_mfma_f32_16x16x32_bf16 v[96:99], v[170:173], v[186:189], v[96:99]
	v_mfma_f32_16x16x32_bf16 v[84:87], v[162:165], v[194:197], v[84:87]
	v_mfma_f32_16x16x32_bf16 v[80:83], v[170:173], v[194:197], v[80:83]
	v_mfma_f32_16x16x32_bf16 v[68:71], v[162:165], v[206:209], v[68:71]
	v_mfma_f32_16x16x32_bf16 v[64:67], v[170:173], v[206:209], v[64:67]
	v_mfma_f32_16x16x32_bf16 v[116:119], v[166:169], v[182:185], v[116:119]
	v_mfma_f32_16x16x32_bf16 v[112:115], v[174:177], v[182:185], v[112:115]
	v_mfma_f32_16x16x32_bf16 v[100:103], v[166:169], v[190:193], v[100:103]
	v_mfma_f32_16x16x32_bf16 v[96:99], v[174:177], v[190:193], v[96:99]
	v_mfma_f32_16x16x32_bf16 v[84:87], v[166:169], v[198:201], v[84:87]
	v_mfma_f32_16x16x32_bf16 v[80:83], v[174:177], v[198:201], v[80:83]
	v_mfma_f32_16x16x32_bf16 v[68:71], v[166:169], v[218:221], v[68:71]
	v_mfma_f32_16x16x32_bf16 v[64:67], v[174:177], v[218:221], v[64:67]
	s_barrier
	s_add_i32 s38, s78, s36
	v_lshl_add_u64 v[202:203], v[202:203], 0, s[26:27]
	s_mov_b32 m0, s38
	ds_read_b128 v[178:181], v145 offset:49152
	ds_read_b128 v[182:185], v145 offset:50176
	ds_read_b128 v[186:189], v145 offset:51200
	ds_read_b128 v[190:193], v145 offset:52224
	ds_read_b128 v[194:197], v145 offset:53248
	ds_read_b128 v[198:201], v145 offset:54272
	ds_read_b128 v[206:209], v145 offset:55296
	ds_read_b128 v[218:221], v145 offset:56320
	global_load_lds_dwordx4 v[202:203], off
	s_add_i32 m0, s38, 0x2000
	s_add_u32 s10, s10, 0x80080
	v_lshl_add_u64 v[202:203], v[222:223], 0, s[26:27]
	s_addc_u32 s11, s11, 0
	s_add_i32 s38, s92, s36
	global_load_lds_dwordx4 v[202:203], off
	s_mov_b32 m0, s38
	v_lshl_add_u64 v[202:203], s[10:11], 0, v[204:205]
	global_load_lds_dwordx4 v[202:203], off
	s_add_i32 m0, s38, 0x2000
	v_lshl_add_u64 v[202:203], s[10:11], 0, v[128:129]
	global_load_lds_dwordx4 v[202:203], off
	s_waitcnt vmcnt(6)
	s_waitcnt lgkmcnt(0)
	s_barrier
	v_mfma_f32_16x16x32_bf16 v[60:63], v[146:149], v[178:181], v[60:63]
	v_mfma_f32_16x16x32_bf16 v[56:59], v[154:157], v[178:181], v[56:59]
	v_mfma_f32_16x16x32_bf16 v[44:47], v[146:149], v[186:189], v[44:47]
	v_mfma_f32_16x16x32_bf16 v[40:43], v[154:157], v[186:189], v[40:43]
	v_mfma_f32_16x16x32_bf16 v[28:31], v[146:149], v[194:197], v[28:31]
	v_mfma_f32_16x16x32_bf16 v[24:27], v[154:157], v[194:197], v[24:27]
	v_mfma_f32_16x16x32_bf16 v[12:15], v[146:149], v[206:209], v[12:15]
	v_mfma_f32_16x16x32_bf16 v[8:11], v[154:157], v[206:209], v[8:11]
	v_mfma_f32_16x16x32_bf16 v[60:63], v[150:153], v[182:185], v[60:63]
	v_mfma_f32_16x16x32_bf16 v[56:59], v[158:161], v[182:185], v[56:59]
	v_mfma_f32_16x16x32_bf16 v[44:47], v[150:153], v[190:193], v[44:47]
	v_mfma_f32_16x16x32_bf16 v[40:43], v[158:161], v[190:193], v[40:43]
	v_mfma_f32_16x16x32_bf16 v[28:31], v[150:153], v[198:201], v[28:31]
	v_mfma_f32_16x16x32_bf16 v[24:27], v[158:161], v[198:201], v[24:27]
	v_mfma_f32_16x16x32_bf16 v[12:15], v[150:153], v[218:221], v[12:15]
	v_mfma_f32_16x16x32_bf16 v[8:11], v[158:161], v[218:221], v[8:11]
	v_mfma_f32_16x16x32_bf16 v[52:55], v[162:165], v[178:181], v[52:55]
	v_mfma_f32_16x16x32_bf16 v[48:51], v[170:173], v[178:181], v[48:51]
	v_mfma_f32_16x16x32_bf16 v[36:39], v[162:165], v[186:189], v[36:39]
	v_mfma_f32_16x16x32_bf16 v[32:35], v[170:173], v[186:189], v[32:35]
	v_mfma_f32_16x16x32_bf16 v[20:23], v[162:165], v[194:197], v[20:23]
	v_mfma_f32_16x16x32_bf16 v[16:19], v[170:173], v[194:197], v[16:19]
	v_mfma_f32_16x16x32_bf16 v[4:7], v[162:165], v[206:209], v[4:7]
	v_mfma_f32_16x16x32_bf16 v[0:3], v[170:173], v[206:209], v[0:3]
	v_mfma_f32_16x16x32_bf16 v[52:55], v[166:169], v[182:185], v[52:55]
	v_mfma_f32_16x16x32_bf16 v[48:51], v[174:177], v[182:185], v[48:51]
	v_mfma_f32_16x16x32_bf16 v[36:39], v[166:169], v[190:193], v[36:39]
	v_mfma_f32_16x16x32_bf16 v[32:35], v[174:177], v[190:193], v[32:35]
	v_mfma_f32_16x16x32_bf16 v[20:23], v[166:169], v[198:201], v[20:23]
	v_mfma_f32_16x16x32_bf16 v[16:19], v[174:177], v[198:201], v[16:19]
	v_mfma_f32_16x16x32_bf16 v[4:7], v[166:169], v[218:221], v[4:7]
	v_mfma_f32_16x16x32_bf16 v[0:3], v[174:177], v[218:221], v[0:3]
	s_barrier
	s_add_i32 s53, s53, 2
	s_add_u32 vcc_lo, vcc_lo, 0x100
	s_addc_u32 vcc_hi, vcc_hi, 0
	s_cmp_gt_u32 s53, 29
	s_cbranch_scc0 .LBB0_605
	s_and_b64 vcc, exec, s[4:5]
	s_cbranch_vccz .LBB0_608
	s_barrier

; #define PG8_STAGE(bufoff, gbase, voff) do { _Pragma("unroll") for (int _i = 0; _i < 2; ++_i) \
;         __builtin_amdgcn_global_load_lds((const unsigned*)((const char*)(gbase) + (voff)[_i]), (PG8_LAS unsigned*)(lds + (bufoff) + ldsw + _i * 8192), 16, 0, 0); } while (0)
; #define PG8_LDA(dst, b, h) do { _Pragma("unroll") for (int m = 0; m < 4; ++m) _Pragma("unroll") for (int k = 0; k < 2; ++k) dst[m][k] = *(const PG8_LAS bf16x8*)(lds + PG8_SA(b, h) + aoff + m * 2048 + k * 1024); } while (0)
; #define PG8_LDB(dst, b, h) do { _Pragma("unroll") for (int n = 0; n < 2; ++n) _Pragma("unroll") for (int k = 0; k < 2; ++k) dst[n][k] = *(const PG8_LAS bf16x8*)(lds + PG8_SB(b, h) + boff + n * 2048 + k * 1024); } while (0)
; #define PG8_WAIT_V(n) asm volatile("s_waitcnt vmcnt(" #n ")" ::: "memory")
; #define PG8_WAIT_L(n) asm volatile("s_waitcnt lgkmcnt(" #n ")" ::: "memory")
; #define PG8_BAR __builtin_amdgcn_s_barrier()
; #define PG8_SCHED __builtin_amdgcn_sched_barrier(0)
; template <class Epi, class Sched, bool ALIGN_EPI = false, bool SP2 = false>
; __device__ __forceinline__ void gemm_phase(PG8_LAS unsigned char* lds, const Gemm g, const Sched& S, const Epi& E) {
;     ...
;         const char* nA = has_next ? (const char*)g.A + (size_t)nxt.pm * tstep : cA; const char* nB = has_next ? (const char*)g.Bt + (size_t)nxt.pn * tstep : cB;
;         for (int t = 0; t < nt; t += 2) {
;             const bool last = (t == nt - 2);
;             const char* a1 = cA + (size_t)(t + 1) * kstep;
;             const char* a2 = last ? nA : cA + (size_t)(t + 2) * kstep; const char* b2 = last ? nB : cB + (size_t)(t + 2) * kstep;
;             const char* a3 = a2 + kstep; const char* b3 = b2 + kstep;
;             if (last && has_next) S.a_ready(nxt);
;             if constexpr (SP2) {
;             PG8_LDB(B0, 0, 0); PG8_LDB(B1, 0, 1); PG8_SCHED; PG8_LDA(At, 0, 0); PG8_STAGE(PG8_SA(1, 0), a1, voffA); PG8_STAGE(PG8_SA(1, 1), a1 + hstep, voffA);
;             PG8_WAIT_V(8); PG8_WAIT_L(0); PG8_BAR; PG8_MMA(0, 0, At, B0); PG8_MMA(0, 1, At, B1); PG8_BAR; PG8_SCHED;
;             PG8_LDA(At, 0, 1); PG8_STAGE(PG8_SB(0, 0), b2, voffB); PG8_STAGE(PG8_SB(0, 1), b2 + hstep, voffB);
;             PG8_WAIT_V(6); PG8_WAIT_L(0); PG8_BAR; PG8_MMA(1, 0, At, B0); PG8_MMA(1, 1, At, B1); PG8_BAR; PG8_SCHED;
.LBB0_701:
	s_ashr_i32 s47, s46, 31
	s_lshl_b64 s[38:39], s[46:47], 22
	s_add_u32 s72, s20, s38
	s_addc_u32 s73, s21, s39
	s_and_b64 s[38:39], s[40:41], exec
	s_cselect_b32 s47, s73, s17
	s_cselect_b32 s70, s72, s16
	s_ashr_i32 s43, s42, 31
	s_lshl_b64 s[38:39], s[42:43], 22
	s_add_u32 s76, s23, s38
	s_addc_u32 s77, s34, s39
	s_and_b64 s[38:39], s[40:41], exec
	s_cselect_b32 s43, s77, s45
	s_cselect_b32 s71, s76, s44
	s_add_u32 s97, s44, 0x100
	s_addc_u32 vcc_lo, s45, 0
	v_lshl_add_u64 v[138:139], s[16:17], 0, v[134:135]
	v_lshl_add_u64 v[140:141], s[16:17], 0, v[136:137]
	s_mov_b32 s52, -2
	s_mov_b64 s[88:89], 0
	s_add_u32 s38, s16, s88
	s_addc_u32 s39, s17, s89
	s_add_u32 s38, s38, 0x100
	s_addc_u32 s39, s39, 0
	s_add_u32 s44, s97, s88
	s_addc_u32 s45, vcc_lo, s89
	s_add_i32 s53, 0, 0x10000
	s_cmpk_eq_i32 s88, 0x3f00
	s_cselect_b32 s45, s43, s45
	s_cselect_b32 s44, s71, s44
	s_cselect_b32 s69, s47, s39
	s_cselect_b32 s68, s70, s38
	s_add_i32 s78, 0, 0x14000
	v_add_u32_e32 v158, s53, v143
	ds_read_b128 v[146:149], v158
	ds_read_b128 v[150:153], v158 offset:1024
	ds_read_b128 v[154:157], v158 offset:2048
	ds_read_b128 v[158:161], v158 offset:3072
	v_lshl_add_u64 v[202:203], v[138:139], 0, s[88:89]
	v_lshl_add_u64 v[222:223], v[202:203], 0, s[26:27]
	s_add_i32 m0, s36, 0x8000
	global_load_lds_dwordx4 v[222:223], off
	v_lshl_add_u64 v[222:223], v[140:141], 0, s[88:89]
	v_lshl_add_u64 v[232:233], v[222:223], 0, s[26:27]
	s_add_i32 m0, s36, 0xa000
	v_lshl_add_u64 v[202:203], v[202:203], 0, s[90:91]
	global_load_lds_dwordx4 v[232:233], off
	s_add_i32 m0, s36, 0xc000
	s_nop 0
	global_load_lds_dwordx4 v[202:203], off
	s_add_i32 m0, s36, 0xe000
	v_lshl_add_u64 v[202:203], v[222:223], 0, s[90:91]
	global_load_lds_dwordx4 v[202:203], off
	s_waitcnt vmcnt(8)
	s_waitcnt lgkmcnt(0)
	s_barrier
	v_mfma_f32_16x16x32_bf16 v[124:127], v[146:149], v[178:181], 0
	v_mfma_f32_16x16x32_bf16 v[120:123], v[154:157], v[178:181], 0
	v_mfma_f32_16x16x32_bf16 v[116:119], v[146:149], v[186:189], 0
	v_mfma_f32_16x16x32_bf16 v[108:111], v[154:157], v[186:189], 0
	v_mfma_f32_16x16x32_bf16 v[100:103], v[146:149], v[194:197], 0
	v_mfma_f32_16x16x32_bf16 v[92:95], v[154:157], v[194:197], 0
	v_mfma_f32_16x16x32_bf16 v[84:87], v[146:149], v[206:209], 0
	v_mfma_f32_16x16x32_bf16 v[76:79], v[154:157], v[206:209], 0
	v_mfma_f32_16x16x32_bf16 v[124:127], v[150:153], v[182:185], v[124:127]
	v_mfma_f32_16x16x32_bf16 v[120:123], v[158:161], v[182:185], v[120:123]
	v_mfma_f32_16x16x32_bf16 v[116:119], v[150:153], v[190:193], v[116:119]
	v_mfma_f32_16x16x32_bf16 v[108:111], v[158:161], v[190:193], v[108:111]
	v_mfma_f32_16x16x32_bf16 v[100:103], v[150:153], v[198:201], v[100:103]
	v_mfma_f32_16x16x32_bf16 v[92:95], v[158:161], v[198:201], v[92:95]
	v_mfma_f32_16x16x32_bf16 v[84:87], v[150:153], v[218:221], v[84:87]
	v_mfma_f32_16x16x32_bf16 v[76:79], v[158:161], v[218:221], v[76:79]
	v_mfma_f32_16x16x32_bf16 v[112:115], v[162:165], v[178:181], 0
	v_mfma_f32_16x16x32_bf16 v[104:107], v[170:173], v[178:181], 0
	v_mfma_f32_16x16x32_bf16 v[96:99], v[162:165], v[186:189], 0
	v_mfma_f32_16x16x32_bf16 v[88:91], v[170:173], v[186:189], 0
	v_mfma_f32_16x16x32_bf16 v[80:83], v[162:165], v[194:197], 0
	v_mfma_f32_16x16x32_bf16 v[72:75], v[170:173], v[194:197], 0
	v_mfma_f32_16x16x32_bf16 v[68:71], v[162:165], v[206:209], 0
	v_mfma_f32_16x16x32_bf16 v[64:67], v[170:173], v[206:209], 0
	v_mfma_f32_16x16x32_bf16 v[112:115], v[166:169], v[182:185], v[112:115]
	v_mfma_f32_16x16x32_bf16 v[104:107], v[174:177], v[182:185], v[104:107]
	v_mfma_f32_16x16x32_bf16 v[96:99], v[166:169], v[190:193], v[96:99]
	v_mfma_f32_16x16x32_bf16 v[88:91], v[174:177], v[190:193], v[88:91]
	v_mfma_f32_16x16x32_bf16 v[80:83], v[166:169], v[198:201], v[80:83]
	v_mfma_f32_16x16x32_bf16 v[72:75], v[174:177], v[198:201], v[72:75]
	v_mfma_f32_16x16x32_bf16 v[68:71], v[166:169], v[218:221], v[68:71]
	v_mfma_f32_16x16x32_bf16 v[64:67], v[174:177], v[218:221], v[64:67]
	s_barrier
	s_add_i32 s38, s53, s35
	v_lshl_add_u64 v[202:203], s[44:45], 0, v[204:205]
	s_mov_b32 m0, s38
	ds_read_b128 v[178:181], v145 offset:16384
	ds_read_b128 v[182:185], v145 offset:17408
	ds_read_b128 v[186:189], v145 offset:18432
	ds_read_b128 v[190:193], v145 offset:19456
	ds_read_b128 v[194:197], v145 offset:20480
	ds_read_b128 v[198:201], v145 offset:21504
	ds_read_b128 v[206:209], v145 offset:22528
	ds_read_b128 v[218:221], v145 offset:23552
	global_load_lds_dwordx4 v[202:203], off
	s_add_i32 m0, s38, 0x2000
	s_add_u32 s38, s44, 0x200000
	v_lshl_add_u64 v[222:223], s[44:45], 0, v[128:129]
	s_addc_u32 s39, s45, 0
	s_add_i32 s53, s78, s35
	global_load_lds_dwordx4 v[222:223], off
	s_mov_b32 m0, s53
	v_lshl_add_u64 v[232:233], s[38:39], 0, v[204:205]
	global_load_lds_dwordx4 v[232:233], off
	s_add_i32 m0, s53, 0x2000
	v_lshl_add_u64 v[232:233], s[38:39], 0, v[128:129]
	global_load_lds_dwordx4 v[232:233], off
	s_waitcnt vmcnt(6)
	s_waitcnt lgkmcnt(0)
	s_barrier
	v_mfma_f32_16x16x32_bf16 v[60:63], v[146:149], v[178:181], 0
	v_mfma_f32_16x16x32_bf16 v[56:59], v[154:157], v[178:181], 0
	v_mfma_f32_16x16x32_bf16 v[52:55], v[146:149], v[186:189], 0
	v_mfma_f32_16x16x32_bf16 v[44:47], v[154:157], v[186:189], 0
	v_mfma_f32_16x16x32_bf16 v[36:39], v[146:149], v[194:197], 0
	v_mfma_f32_16x16x32_bf16 v[28:31], v[154:157], v[194:197], 0
	v_mfma_f32_16x16x32_bf16 v[20:23], v[146:149], v[206:209], 0
	v_mfma_f32_16x16x32_bf16 v[12:15], v[154:157], v[206:209], 0
	v_mfma_f32_16x16x32_bf16 v[60:63], v[150:153], v[182:185], v[60:63]
	v_mfma_f32_16x16x32_bf16 v[56:59], v[158:161], v[182:185], v[56:59]
	v_mfma_f32_16x16x32_bf16 v[52:55], v[150:153], v[190:193], v[52:55]
	v_mfma_f32_16x16x32_bf16 v[44:47], v[158:161], v[190:193], v[44:47]
	v_mfma_f32_16x16x32_bf16 v[36:39], v[150:153], v[198:201], v[36:39]
	v_mfma_f32_16x16x32_bf16 v[28:31], v[158:161], v[198:201], v[28:31]
	v_mfma_f32_16x16x32_bf16 v[20:23], v[150:153], v[218:221], v[20:23]
	v_mfma_f32_16x16x32_bf16 v[12:15], v[158:161], v[218:221], v[12:15]
	v_mfma_f32_16x16x32_bf16 v[48:51], v[162:165], v[178:181], 0
	v_mfma_f32_16x16x32_bf16 v[40:43], v[170:173], v[178:181], 0
	v_mfma_f32_16x16x32_bf16 v[32:35], v[162:165], v[186:189], 0
	v_mfma_f32_16x16x32_bf16 v[24:27], v[170:173], v[186:189], 0
	v_mfma_f32_16x16x32_bf16 v[16:19], v[162:165], v[194:197], 0
	v_mfma_f32_16x16x32_bf16 v[8:11], v[170:173], v[194:197], 0
	v_mfma_f32_16x16x32_bf16 v[4:7], v[162:165], v[206:209], 0
	v_mfma_f32_16x16x32_bf16 v[0:3], v[170:173], v[206:209], 0
	v_mfma_f32_16x16x32_bf16 v[48:51], v[166:169], v[182:185], v[48:51]
	v_mfma_f32_16x16x32_bf16 v[40:43], v[174:177], v[182:185], v[40:43]
	v_mfma_f32_16x16x32_bf16 v[32:35], v[166:169], v[190:193], v[32:35]
	v_mfma_f32_16x16x32_bf16 v[24:27], v[174:177], v[190:193], v[24:27]
	v_mfma_f32_16x16x32_bf16 v[16:19], v[166:169], v[198:201], v[16:19]
	v_mfma_f32_16x16x32_bf16 v[8:11], v[174:177], v[198:201], v[8:11]
	v_mfma_f32_16x16x32_bf16 v[4:7], v[166:169], v[218:221], v[4:7]
	v_mfma_f32_16x16x32_bf16 v[0:3], v[174:177], v[218:221], v[0:3]
	s_barrier
	s_branch .Lpl_down
; #define PG8_STAGE(bufoff, gbase, voff) do { _Pragma("unroll") for (int _i = 0; _i < 2; ++_i) \
;         __builtin_amdgcn_global_load_lds((const unsigned*)((const char*)(gbase) + (voff)[_i]), (PG8_LAS unsigned*)(lds + (bufoff) + ldsw + _i * 8192), 16, 0, 0); } while (0)
; #define PG8_LDA(dst, b, h) do { _Pragma("unroll") for (int m = 0; m < 4; ++m) _Pragma("unroll") for (int k = 0; k < 2; ++k) dst[m][k] = *(const PG8_LAS bf16x8*)(lds + PG8_SA(b, h) + aoff + m * 2048 + k * 1024); } while (0)
; #define PG8_LDB(dst, b, h) do { _Pragma("unroll") for (int n = 0; n < 2; ++n) _Pragma("unroll") for (int k = 0; k < 2; ++k) dst[n][k] = *(const PG8_LAS bf16x8*)(lds + PG8_SB(b, h) + boff + n * 2048 + k * 1024); } while (0)
; #define PG8_MMA(ai, bj, At, Bt) do { __builtin_amdgcn_s_setprio(1); _Pragma("unroll") for (int m = 0; m < 4; ++m) _Pragma("unroll") for (int n = 0; n < 2; ++n) _Pragma("unroll") for (int k = 0; k < 2; ++k) \
;         acc[ai][bj][m][n] = __builtin_amdgcn_mfma_f32_16x16x32_bf16(Bt[n][k], At[m][k], acc[ai][bj][m][n], 0, 0, 0); __builtin_amdgcn_s_setprio(0); } while (0)
; #define PG8_WAIT_V(n) asm volatile("s_waitcnt vmcnt(" #n ")" ::: "memory")
; #define PG8_WAIT_L(n) asm volatile("s_waitcnt lgkmcnt(" #n ")" ::: "memory")
; template <class Epi, class Sched, bool ALIGN_EPI = false, bool SP2 = false>
; __device__ __forceinline__ void gemm_phase(PG8_LAS unsigned char* lds, const Gemm g, const Sched& S, const Epi& E) {
;     ...
;             const bool last = (t == nt - 2);
;             const char* a1 = cA + (size_t)(t + 1) * kstep;
;             const char* a2 = last ? nA : cA + (size_t)(t + 2) * kstep; const char* b2 = last ? nB : cB + (size_t)(t + 2) * kstep;
;             const char* a3 = a2 + kstep; const char* b3 = b2 + kstep;
;             if (last && has_next) S.a_ready(nxt);
;             if constexpr (SP2) {
;             PG8_LDB(B0, 0, 0); PG8_LDB(B1, 0, 1); PG8_SCHED; PG8_LDA(At, 0, 0); PG8_STAGE(PG8_SA(1, 0), a1, voffA); PG8_STAGE(PG8_SA(1, 1), a1 + hstep, voffA);
;             PG8_WAIT_V(8); PG8_WAIT_L(0); PG8_BAR; PG8_MMA(0, 0, At, B0); PG8_MMA(0, 1, At, B1); PG8_BAR; PG8_SCHED;
;             PG8_LDA(At, 0, 1); PG8_STAGE(PG8_SB(0, 0), b2, voffB); PG8_STAGE(PG8_SB(0, 1), b2 + hstep, voffB);
;             PG8_WAIT_V(6); PG8_WAIT_L(0); PG8_BAR; PG8_MMA(1, 0, At, B0); PG8_MMA(1, 1, At, B1); PG8_BAR; PG8_SCHED;
.LBB0_702:
	s_add_u32 s38, s16, s88
	s_addc_u32 s39, s17, s89
	s_add_u32 s38, s38, 0x100
	s_addc_u32 s39, s39, 0
	s_add_u32 s44, s97, s88
	s_addc_u32 s45, vcc_lo, s89
	s_add_i32 s53, 0, 0x10000
	s_cmpk_eq_i32 s88, 0x3f00
	s_cselect_b32 s45, s43, s45
	s_cselect_b32 s44, s71, s44
	s_cselect_b32 s69, s47, s39
	s_cselect_b32 s68, s70, s38
	s_add_i32 s78, 0, 0x14000
	v_add_u32_e32 v158, s53, v143
	v_add_u32_e32 v174, s78, v143
	ds_read_b128 v[146:149], v158
	ds_read_b128 v[150:153], v158 offset:1024
	ds_read_b128 v[154:157], v158 offset:2048
	ds_read_b128 v[158:161], v158 offset:3072
	ds_read_b128 v[162:165], v174
	ds_read_b128 v[166:169], v174 offset:1024
	ds_read_b128 v[170:173], v174 offset:2048
	ds_read_b128 v[174:177], v174 offset:3072
	v_lshl_add_u64 v[202:203], v[138:139], 0, s[88:89]
	v_lshl_add_u64 v[222:223], v[202:203], 0, s[26:27]
	s_add_i32 m0, s36, 0x8000
	ds_read_b128 v[178:181], v145
	ds_read_b128 v[182:185], v145 offset:1024
	ds_read_b128 v[186:189], v145 offset:2048
	ds_read_b128 v[190:193], v145 offset:3072
	ds_read_b128 v[194:197], v145 offset:4096
	ds_read_b128 v[198:201], v145 offset:5120
	ds_read_b128 v[206:209], v145 offset:6144
	ds_read_b128 v[218:221], v145 offset:7168
	global_load_lds_dwordx4 v[222:223], off
	v_lshl_add_u64 v[222:223], v[140:141], 0, s[88:89]
	v_lshl_add_u64 v[232:233], v[222:223], 0, s[26:27]
	s_add_i32 m0, s36, 0xa000
	v_lshl_add_u64 v[202:203], v[202:203], 0, s[90:91]
	global_load_lds_dwordx4 v[232:233], off
	s_add_i32 m0, s36, 0xc000
	s_nop 0
	global_load_lds_dwordx4 v[202:203], off
	s_add_i32 m0, s36, 0xe000
	v_lshl_add_u64 v[202:203], v[222:223], 0, s[90:91]
	global_load_lds_dwordx4 v[202:203], off
	s_waitcnt vmcnt(8)
	s_waitcnt lgkmcnt(0)
	s_barrier
	v_mfma_f32_16x16x32_bf16 v[124:127], v[146:149], v[178:181], v[124:127]
	v_mfma_f32_16x16x32_bf16 v[120:123], v[154:157], v[178:181], v[120:123]
	v_mfma_f32_16x16x32_bf16 v[116:119], v[146:149], v[186:189], v[116:119]
	v_mfma_f32_16x16x32_bf16 v[108:111], v[154:157], v[186:189], v[108:111]
	v_mfma_f32_16x16x32_bf16 v[100:103], v[146:149], v[194:197], v[100:103]
	v_mfma_f32_16x16x32_bf16 v[92:95], v[154:157], v[194:197], v[92:95]
	v_mfma_f32_16x16x32_bf16 v[84:87], v[146:149], v[206:209], v[84:87]
	v_mfma_f32_16x16x32_bf16 v[76:79], v[154:157], v[206:209], v[76:79]
	v_mfma_f32_16x16x32_bf16 v[124:127], v[150:153], v[182:185], v[124:127]
	v_mfma_f32_16x16x32_bf16 v[120:123], v[158:161], v[182:185], v[120:123]
	v_mfma_f32_16x16x32_bf16 v[116:119], v[150:153], v[190:193], v[116:119]
	v_mfma_f32_16x16x32_bf16 v[108:111], v[158:161], v[190:193], v[108:111]
	v_mfma_f32_16x16x32_bf16 v[100:103], v[150:153], v[198:201], v[100:103]
	v_mfma_f32_16x16x32_bf16 v[92:95], v[158:161], v[198:201], v[92:95]
	v_mfma_f32_16x16x32_bf16 v[84:87], v[150:153], v[218:221], v[84:87]
	v_mfma_f32_16x16x32_bf16 v[76:79], v[158:161], v[218:221], v[76:79]
	v_mfma_f32_16x16x32_bf16 v[112:115], v[162:165], v[178:181], v[112:115]
	v_mfma_f32_16x16x32_bf16 v[104:107], v[170:173], v[178:181], v[104:107]
	v_mfma_f32_16x16x32_bf16 v[96:99], v[162:165], v[186:189], v[96:99]
	v_mfma_f32_16x16x32_bf16 v[88:91], v[170:173], v[186:189], v[88:91]
	v_mfma_f32_16x16x32_bf16 v[80:83], v[162:165], v[194:197], v[80:83]
	v_mfma_f32_16x16x32_bf16 v[72:75], v[170:173], v[194:197], v[72:75]
	v_mfma_f32_16x16x32_bf16 v[68:71], v[162:165], v[206:209], v[68:71]
	v_mfma_f32_16x16x32_bf16 v[64:67], v[170:173], v[206:209], v[64:67]
	v_mfma_f32_16x16x32_bf16 v[112:115], v[166:169], v[182:185], v[112:115]
	v_mfma_f32_16x16x32_bf16 v[104:107], v[174:177], v[182:185], v[104:107]
	v_mfma_f32_16x16x32_bf16 v[96:99], v[166:169], v[190:193], v[96:99]
	v_mfma_f32_16x16x32_bf16 v[88:91], v[174:177], v[190:193], v[88:91]
	v_mfma_f32_16x16x32_bf16 v[80:83], v[166:169], v[198:201], v[80:83]
	v_mfma_f32_16x16x32_bf16 v[72:75], v[174:177], v[198:201], v[72:75]
	v_mfma_f32_16x16x32_bf16 v[68:71], v[166:169], v[218:221], v[68:71]
	v_mfma_f32_16x16x32_bf16 v[64:67], v[174:177], v[218:221], v[64:67]
	s_barrier
	s_add_i32 s38, s53, s35
	v_lshl_add_u64 v[202:203], s[44:45], 0, v[204:205]
	s_mov_b32 m0, s38
	ds_read_b128 v[178:181], v145 offset:16384
	ds_read_b128 v[182:185], v145 offset:17408
	ds_read_b128 v[186:189], v145 offset:18432
	ds_read_b128 v[190:193], v145 offset:19456
	ds_read_b128 v[194:197], v145 offset:20480
	ds_read_b128 v[198:201], v145 offset:21504
	ds_read_b128 v[206:209], v145 offset:22528
	ds_read_b128 v[218:221], v145 offset:23552
	global_load_lds_dwordx4 v[202:203], off
	s_add_i32 m0, s38, 0x2000
	s_add_u32 s38, s44, 0x200000
	v_lshl_add_u64 v[222:223], s[44:45], 0, v[128:129]
	s_addc_u32 s39, s45, 0
	s_add_i32 s53, s78, s35
	global_load_lds_dwordx4 v[222:223], off
	s_mov_b32 m0, s53
	v_lshl_add_u64 v[232:233], s[38:39], 0, v[204:205]
	global_load_lds_dwordx4 v[232:233], off
	s_add_i32 m0, s53, 0x2000
	v_lshl_add_u64 v[232:233], s[38:39], 0, v[128:129]
	global_load_lds_dwordx4 v[232:233], off
	s_waitcnt vmcnt(6)
	s_waitcnt lgkmcnt(0)
	s_barrier
; #define PG8_MMA(ai, bj, At, Bt) do { __builtin_amdgcn_s_setprio(1); _Pragma("unroll") for (int m = 0; m < 4; ++m) _Pragma("unroll") for (int n = 0; n < 2; ++n) _Pragma("unroll") for (int k = 0; k < 2; ++k) \
;         acc[ai][bj][m][n] = __builtin_amdgcn_mfma_f32_16x16x32_bf16(Bt[n][k], At[m][k], acc[ai][bj][m][n], 0, 0, 0); __builtin_amdgcn_s_setprio(0); } while (0)
; #define PG8_WAIT_V(n) asm volatile("s_waitcnt vmcnt(" #n ")" ::: "memory")
; #define PG8_WAIT_L(n) asm volatile("s_waitcnt lgkmcnt(" #n ")" ::: "memory")
; #define PG8_BAR __builtin_amdgcn_s_barrier()
; #define PG8_SCHED __builtin_amdgcn_sched_barrier(0)
; template <class Epi, class Sched, bool ALIGN_EPI = false, bool SP2 = false>
; __device__ __forceinline__ void gemm_phase(PG8_LAS unsigned char* lds, const Gemm g, const Sched& S, const Epi& E) {
;     ...
;             PG8_WAIT_V(6); PG8_WAIT_L(0); PG8_BAR; PG8_MMA(1, 0, At, B0); PG8_MMA(1, 1, At, B1); PG8_BAR; PG8_SCHED;
	v_mfma_f32_16x16x32_bf16 v[60:63], v[146:149], v[178:181], v[60:63]
	v_mfma_f32_16x16x32_bf16 v[56:59], v[154:157], v[178:181], v[56:59]
	v_mfma_f32_16x16x32_bf16 v[52:55], v[146:149], v[186:189], v[52:55]
	v_mfma_f32_16x16x32_bf16 v[44:47], v[154:157], v[186:189], v[44:47]
	v_mfma_f32_16x16x32_bf16 v[36:39], v[146:149], v[194:197], v[36:39]
	v_mfma_f32_16x16x32_bf16 v[28:31], v[154:157], v[194:197], v[28:31]
	v_mfma_f32_16x16x32_bf16 v[20:23], v[146:149], v[206:209], v[20:23]
	v_mfma_f32_16x16x32_bf16 v[12:15], v[154:157], v[206:209], v[12:15]
	v_mfma_f32_16x16x32_bf16 v[60:63], v[150:153], v[182:185], v[60:63]
	v_mfma_f32_16x16x32_bf16 v[56:59], v[158:161], v[182:185], v[56:59]
	v_mfma_f32_16x16x32_bf16 v[52:55], v[150:153], v[190:193], v[52:55]
	v_mfma_f32_16x16x32_bf16 v[44:47], v[158:161], v[190:193], v[44:47]
	v_mfma_f32_16x16x32_bf16 v[36:39], v[150:153], v[198:201], v[36:39]
	v_mfma_f32_16x16x32_bf16 v[28:31], v[158:161], v[198:201], v[28:31]
	v_mfma_f32_16x16x32_bf16 v[20:23], v[150:153], v[218:221], v[20:23]
	v_mfma_f32_16x16x32_bf16 v[12:15], v[158:161], v[218:221], v[12:15]
	v_mfma_f32_16x16x32_bf16 v[48:51], v[162:165], v[178:181], v[48:51]
	v_mfma_f32_16x16x32_bf16 v[40:43], v[170:173], v[178:181], v[40:43]
	v_mfma_f32_16x16x32_bf16 v[32:35], v[162:165], v[186:189], v[32:35]
	v_mfma_f32_16x16x32_bf16 v[24:27], v[170:173], v[186:189], v[24:27]
	v_mfma_f32_16x16x32_bf16 v[16:19], v[162:165], v[194:197], v[16:19]
	v_mfma_f32_16x16x32_bf16 v[8:11], v[170:173], v[194:197], v[8:11]
	v_mfma_f32_16x16x32_bf16 v[4:7], v[162:165], v[206:209], v[4:7]
	v_mfma_f32_16x16x32_bf16 v[0:3], v[170:173], v[206:209], v[0:3]
	v_mfma_f32_16x16x32_bf16 v[48:51], v[166:169], v[182:185], v[48:51]
	v_mfma_f32_16x16x32_bf16 v[40:43], v[174:177], v[182:185], v[40:43]
	v_mfma_f32_16x16x32_bf16 v[32:35], v[166:169], v[190:193], v[32:35]
	v_mfma_f32_16x16x32_bf16 v[24:27], v[174:177], v[190:193], v[24:27]
	v_mfma_f32_16x16x32_bf16 v[16:19], v[166:169], v[198:201], v[16:19]
	v_mfma_f32_16x16x32_bf16 v[8:11], v[174:177], v[198:201], v[8:11]
	v_mfma_f32_16x16x32_bf16 v[4:7], v[166:169], v[218:221], v[4:7]
	v_mfma_f32_16x16x32_bf16 v[0:3], v[174:177], v[218:221], v[0:3]
	s_barrier
; #define PG8_STAGE(bufoff, gbase, voff) do { _Pragma("unroll") for (int _i = 0; _i < 2; ++_i) \
;         __builtin_amdgcn_global_load_lds((const unsigned*)((const char*)(gbase) + (voff)[_i]), (PG8_LAS unsigned*)(lds + (bufoff) + ldsw + _i * 8192), 16, 0, 0); } while (0)
; #define PG8_LDA(dst, b, h) do { _Pragma("unroll") for (int m = 0; m < 4; ++m) _Pragma("unroll") for (int k = 0; k < 2; ++k) dst[m][k] = *(const PG8_LAS bf16x8*)(lds + PG8_SA(b, h) + aoff + m * 2048 + k * 1024); } while (0)
; #define PG8_LDB(dst, b, h) do { _Pragma("unroll") for (int n = 0; n < 2; ++n) _Pragma("unroll") for (int k = 0; k < 2; ++k) dst[n][k] = *(const PG8_LAS bf16x8*)(lds + PG8_SB(b, h) + boff + n * 2048 + k * 1024); } while (0)
; #define PG8_MMA(ai, bj, At, Bt) do { __builtin_amdgcn_s_setprio(1); _Pragma("unroll") for (int m = 0; m < 4; ++m) _Pragma("unroll") for (int n = 0; n < 2; ++n) _Pragma("unroll") for (int k = 0; k < 2; ++k) \
;         acc[ai][bj][m][n] = __builtin_amdgcn_mfma_f32_16x16x32_bf16(Bt[n][k], At[m][k], acc[ai][bj][m][n], 0, 0, 0); __builtin_amdgcn_s_setprio(0); } while (0)
; #define PG8_WAIT_V(n) asm volatile("s_waitcnt vmcnt(" #n ")" ::: "memory")
; #define PG8_WAIT_L(n) asm volatile("s_waitcnt lgkmcnt(" #n ")" ::: "memory")
; #define PG8_BAR __builtin_amdgcn_s_barrier()
; #define PG8_SCHED __builtin_amdgcn_sched_barrier(0)
; template <class Epi, class Sched, bool ALIGN_EPI = false, bool SP2 = false>
; __device__ __forceinline__ void gemm_phase(PG8_LAS unsigned char* lds, const Gemm g, const Sched& S, const Epi& E) {
;     ...
;             PG8_LDB(B0, 1, 0); PG8_LDB(B1, 1, 1); PG8_SCHED; PG8_LDA(At, 1, 0); PG8_STAGE(PG8_SA(0, 0), a2, voffA); PG8_STAGE(PG8_SA(0, 1), a2 + hstep, voffA);
;             PG8_WAIT_V(8); PG8_WAIT_L(0); PG8_BAR; PG8_MMA(0, 0, At, B0); PG8_MMA(0, 1, At, B1); PG8_BAR; PG8_SCHED;
;             PG8_LDA(At, 1, 1); PG8_STAGE(PG8_SB(1, 0), b3, voffB); PG8_STAGE(PG8_SB(1, 1), b3 + hstep, voffB); (void)a3;
;             PG8_WAIT_V(6); PG8_WAIT_L(0); PG8_BAR; PG8_MMA(1, 0, At, B0); PG8_MMA(1, 1, At, B1); PG8_BAR; PG8_SCHED;
.Lpl_down:
	s_add_i32 s53, 0, 0x18000
	s_add_i32 s78, 0, 0x1c000
	v_add_u32_e32 v158, s53, v143
	v_add_u32_e32 v174, s78, v143
	ds_read_b128 v[146:149], v158
	ds_read_b128 v[150:153], v158 offset:1024
	ds_read_b128 v[154:157], v158 offset:2048
	ds_read_b128 v[158:161], v158 offset:3072
	ds_read_b128 v[162:165], v174
	ds_read_b128 v[166:169], v174 offset:1024
	ds_read_b128 v[170:173], v174 offset:2048
	ds_read_b128 v[174:177], v174 offset:3072
	s_mov_b32 m0, s36
	v_lshl_add_u64 v[232:233], s[68:69], 0, v[132:133]
	s_add_u32 s38, s68, 0x200000
	ds_read_b128 v[178:181], v145 offset:32768
	ds_read_b128 v[182:185], v145 offset:33792
	ds_read_b128 v[186:189], v145 offset:34816
	ds_read_b128 v[190:193], v145 offset:35840
	ds_read_b128 v[194:197], v145 offset:36864
	ds_read_b128 v[198:201], v145 offset:37888
	ds_read_b128 v[206:209], v145 offset:38912
	ds_read_b128 v[218:221], v145 offset:39936
	global_load_lds_dwordx4 v[232:233], off
	v_lshl_add_u64 v[232:233], s[68:69], 0, v[130:131]
	s_mov_b32 m0, s37
	s_addc_u32 s39, s69, 0
	global_load_lds_dwordx4 v[232:233], off
	s_mov_b32 m0, s57
	v_lshl_add_u64 v[232:233], s[38:39], 0, v[132:133]
	global_load_lds_dwordx4 v[232:233], off
	s_mov_b32 m0, s75
	v_lshl_add_u64 v[232:233], s[38:39], 0, v[130:131]
	global_load_lds_dwordx4 v[232:233], off
	s_waitcnt vmcnt(8)
	s_waitcnt lgkmcnt(0)
	s_barrier
	v_mfma_f32_16x16x32_bf16 v[124:127], v[146:149], v[178:181], v[124:127]
	v_mfma_f32_16x16x32_bf16 v[120:123], v[154:157], v[178:181], v[120:123]
	v_mfma_f32_16x16x32_bf16 v[116:119], v[146:149], v[186:189], v[116:119]
	v_mfma_f32_16x16x32_bf16 v[108:111], v[154:157], v[186:189], v[108:111]
	v_mfma_f32_16x16x32_bf16 v[100:103], v[146:149], v[194:197], v[100:103]
	v_mfma_f32_16x16x32_bf16 v[92:95], v[154:157], v[194:197], v[92:95]
	v_mfma_f32_16x16x32_bf16 v[84:87], v[146:149], v[206:209], v[84:87]
	v_mfma_f32_16x16x32_bf16 v[76:79], v[154:157], v[206:209], v[76:79]
	v_mfma_f32_16x16x32_bf16 v[124:127], v[150:153], v[182:185], v[124:127]
	v_mfma_f32_16x16x32_bf16 v[120:123], v[158:161], v[182:185], v[120:123]
	v_mfma_f32_16x16x32_bf16 v[116:119], v[150:153], v[190:193], v[116:119]
	v_mfma_f32_16x16x32_bf16 v[108:111], v[158:161], v[190:193], v[108:111]
	v_mfma_f32_16x16x32_bf16 v[100:103], v[150:153], v[198:201], v[100:103]
	v_mfma_f32_16x16x32_bf16 v[92:95], v[158:161], v[198:201], v[92:95]
	v_mfma_f32_16x16x32_bf16 v[84:87], v[150:153], v[218:221], v[84:87]
	v_mfma_f32_16x16x32_bf16 v[76:79], v[158:161], v[218:221], v[76:79]
	v_mfma_f32_16x16x32_bf16 v[112:115], v[162:165], v[178:181], v[112:115]
	v_mfma_f32_16x16x32_bf16 v[104:107], v[170:173], v[178:181], v[104:107]
	v_mfma_f32_16x16x32_bf16 v[96:99], v[162:165], v[186:189], v[96:99]
	v_mfma_f32_16x16x32_bf16 v[88:91], v[170:173], v[186:189], v[88:91]
	v_mfma_f32_16x16x32_bf16 v[80:83], v[162:165], v[194:197], v[80:83]
	v_mfma_f32_16x16x32_bf16 v[72:75], v[170:173], v[194:197], v[72:75]
	v_mfma_f32_16x16x32_bf16 v[68:71], v[162:165], v[206:209], v[68:71]
	v_mfma_f32_16x16x32_bf16 v[64:67], v[170:173], v[206:209], v[64:67]
	v_mfma_f32_16x16x32_bf16 v[112:115], v[166:169], v[182:185], v[112:115]
	v_mfma_f32_16x16x32_bf16 v[104:107], v[174:177], v[182:185], v[104:107]
	v_mfma_f32_16x16x32_bf16 v[96:99], v[166:169], v[190:193], v[96:99]
	v_mfma_f32_16x16x32_bf16 v[88:91], v[174:177], v[190:193], v[88:91]
	v_mfma_f32_16x16x32_bf16 v[80:83], v[166:169], v[198:201], v[80:83]
	v_mfma_f32_16x16x32_bf16 v[72:75], v[174:177], v[198:201], v[72:75]
	v_mfma_f32_16x16x32_bf16 v[68:71], v[166:169], v[218:221], v[68:71]
	v_mfma_f32_16x16x32_bf16 v[64:67], v[174:177], v[218:221], v[64:67]
	s_barrier
	s_add_i32 s38, s53, s35
	v_lshl_add_u64 v[202:203], v[202:203], 0, s[26:27]
	s_mov_b32 m0, s38
	ds_read_b128 v[178:181], v145 offset:49152
	ds_read_b128 v[182:185], v145 offset:50176
	ds_read_b128 v[186:189], v145 offset:51200
	ds_read_b128 v[190:193], v145 offset:52224
	ds_read_b128 v[194:197], v145 offset:53248
	ds_read_b128 v[198:201], v145 offset:54272
	ds_read_b128 v[206:209], v145 offset:55296
	ds_read_b128 v[218:221], v145 offset:56320
	global_load_lds_dwordx4 v[202:203], off
	s_add_i32 m0, s38, 0x2000
	s_add_u32 s38, s44, 0x200080
	v_lshl_add_u64 v[202:203], v[222:223], 0, s[26:27]
	s_addc_u32 s39, s45, 0
	s_add_i32 s44, s78, s35
	global_load_lds_dwordx4 v[202:203], off
	s_mov_b32 m0, s44
	v_lshl_add_u64 v[202:203], s[38:39], 0, v[204:205]
	global_load_lds_dwordx4 v[202:203], off
	s_add_i32 m0, s44, 0x2000
	v_lshl_add_u64 v[202:203], s[38:39], 0, v[128:129]
	global_load_lds_dwordx4 v[202:203], off
	s_waitcnt vmcnt(6)
	s_waitcnt lgkmcnt(0)
	s_barrier
	v_mfma_f32_16x16x32_bf16 v[60:63], v[146:149], v[178:181], v[60:63]
	v_mfma_f32_16x16x32_bf16 v[56:59], v[154:157], v[178:181], v[56:59]
	v_mfma_f32_16x16x32_bf16 v[52:55], v[146:149], v[186:189], v[52:55]
	v_mfma_f32_16x16x32_bf16 v[44:47], v[154:157], v[186:189], v[44:47]
	v_mfma_f32_16x16x32_bf16 v[36:39], v[146:149], v[194:197], v[36:39]
	v_mfma_f32_16x16x32_bf16 v[28:31], v[154:157], v[194:197], v[28:31]
	v_mfma_f32_16x16x32_bf16 v[20:23], v[146:149], v[206:209], v[20:23]
	v_mfma_f32_16x16x32_bf16 v[12:15], v[154:157], v[206:209], v[12:15]
	v_mfma_f32_16x16x32_bf16 v[60:63], v[150:153], v[182:185], v[60:63]
	v_mfma_f32_16x16x32_bf16 v[56:59], v[158:161], v[182:185], v[56:59]
	v_mfma_f32_16x16x32_bf16 v[52:55], v[150:153], v[190:193], v[52:55]
	v_mfma_f32_16x16x32_bf16 v[44:47], v[158:161], v[190:193], v[44:47]
	v_mfma_f32_16x16x32_bf16 v[36:39], v[150:153], v[198:201], v[36:39]
	v_mfma_f32_16x16x32_bf16 v[28:31], v[158:161], v[198:201], v[28:31]
	v_mfma_f32_16x16x32_bf16 v[20:23], v[150:153], v[218:221], v[20:23]
	v_mfma_f32_16x16x32_bf16 v[12:15], v[158:161], v[218:221], v[12:15]
	v_mfma_f32_16x16x32_bf16 v[48:51], v[162:165], v[178:181], v[48:51]
	v_mfma_f32_16x16x32_bf16 v[40:43], v[170:173], v[178:181], v[40:43]
	v_mfma_f32_16x16x32_bf16 v[32:35], v[162:165], v[186:189], v[32:35]
	v_mfma_f32_16x16x32_bf16 v[24:27], v[170:173], v[186:189], v[24:27]
	v_mfma_f32_16x16x32_bf16 v[16:19], v[162:165], v[194:197], v[16:19]
	v_mfma_f32_16x16x32_bf16 v[8:11], v[170:173], v[194:197], v[8:11]
	v_mfma_f32_16x16x32_bf16 v[4:7], v[162:165], v[206:209], v[4:7]
	v_mfma_f32_16x16x32_bf16 v[0:3], v[170:173], v[206:209], v[0:3]
	v_mfma_f32_16x16x32_bf16 v[48:51], v[166:169], v[182:185], v[48:51]
	v_mfma_f32_16x16x32_bf16 v[40:43], v[174:177], v[182:185], v[40:43]
	v_mfma_f32_16x16x32_bf16 v[32:35], v[166:169], v[190:193], v[32:35]
	v_mfma_f32_16x16x32_bf16 v[24:27], v[174:177], v[190:193], v[24:27]
	v_mfma_f32_16x16x32_bf16 v[16:19], v[166:169], v[198:201], v[16:19]
	v_mfma_f32_16x16x32_bf16 v[8:11], v[174:177], v[198:201], v[8:11]
	v_mfma_f32_16x16x32_bf16 v[4:7], v[166:169], v[218:221], v[4:7]
	v_mfma_f32_16x16x32_bf16 v[0:3], v[174:177], v[218:221], v[0:3]
	s_barrier
	s_add_i32 s52, s52, 2
	s_add_u32 s88, s88, 0x100
	s_addc_u32 s89, s89, 0
	s_cmpk_gt_u32 s52, 0x7d
	s_cbranch_scc0 .LBB0_702
	s_and_b64 vcc, exec, s[10:11]
	s_cbranch_vccz .LBB0_705
	s_barrier
